# stack of latency rewrites: barrier conversion absmax via DPP/readlane, scan chain block re-scheduled (LDS operands requested up front), v-pass 64-lane reductions via DPP; on top of nt hints + interlea
# baseline (speedup 1.0000x reference)
; #define GAS __attribute__((address_space(1)))
; #define Q4(x) fminf(fmaxf((x) * sc, -6.f), 6.f)
; #define Q4(x) fminf(fmaxf((x) * sc, -6.f), 6.f)
; __device__ __forceinline__ void table_row_to_fp4(const f32x4 (&v)[4], int lane, bool isv, int r, unsigned char* ws) {
;     float m = 0.f;
; #pragma unroll
;     for (int j = 0; j < 4; ++j) m = fmaxf(fmaxf(m, fmaxf(fabsf(v[j].x), fabsf(v[j].y))), fmaxf(fabsf(v[j].z), fabsf(v[j].w)));
; #pragma unroll
;     for (int o = 1; o < 64; o <<= 1) m = fmaxf(m, __shfl_xor(m, o));
;     m = fmaxf(m, 1e-30f);
;     const float sc = 7.f / m;
;     unsigned w0 = 0u, w1 = 0u;
;     ...
;     w0 = __builtin_amdgcn_cvt_scalef32_pk_fp4_f32(w0, Q4(v[0].x), Q4(v[0].y), 1.0f, 0); w0 = __builtin_amdgcn_cvt_scalef32_pk_fp4_f32(w0, Q4(v[0].z), Q4(v[0].w), 1.0f, 1);
;     w0 = __builtin_amdgcn_cvt_scalef32_pk_fp4_f32(w0, Q4(v[1].x), Q4(v[1].y), 1.0f, 2); w0 = __builtin_amdgcn_cvt_scalef32_pk_fp4_f32(w0, Q4(v[1].z), Q4(v[1].w), 1.0f, 3);
;     w1 = __builtin_amdgcn_cvt_scalef32_pk_fp4_f32(w1, Q4(v[2].x), Q4(v[2].y), 1.0f, 0); w1 = __builtin_amdgcn_cvt_scalef32_pk_fp4_f32(w1, Q4(v[2].z), Q4(v[2].w), 1.0f, 1);
;     w1 = __builtin_amdgcn_cvt_scalef32_pk_fp4_f32(w1, Q4(v[3].x), Q4(v[3].y), 1.0f, 2); w1 = __builtin_amdgcn_cvt_scalef32_pk_fp4_f32(w1, Q4(v[3].z), Q4(v[3].w), 1.0f, 3);
;     ...
;     *((GAS v2u*)(ws + (isv ? WS_V8 : WS_U8) + (size_t)r * 512) + lane) = (v2u){w0, w1};
;     if (lane == 0) ((float*)(ws + (isv ? WS_DQV : WS_DQU)))[r] = m * (1.f / 7.f);
.LBB0_150:
	s_andn2_b64 vcc, exec, s[4:5]
	v_cmp_eq_u32_e64 s[4:5], 0, v1
	s_cbranch_vccnz .LBB0_155
	s_add_i32 s2, s2, s14
	s_cmpk_gt_i32 s2, 0x7fff
	s_cbranch_scc1 .LBB0_155
	s_waitcnt vmcnt(0)
	v_max_f32_e64 v50, |v47|, |v47|
	v_max_f32_e64 v51, |v46|, |v46|
	v_max_f32_e32 v50, v51, v50
	v_max_f32_e64 v51, |v49|, |v49|
	v_max_f32_e64 v52, |v48|, |v48|
	v_max_f32_e32 v51, v52, v51
	v_max3_f32 v50, v50, 0, v51
	v_max_f32_e64 v51, |v43|, |v43|
	v_max_f32_e64 v52, |v42|, |v42|
	v_max_f32_e32 v51, v52, v51
	v_max_f32_e64 v52, |v45|, |v45|
	v_max_f32_e64 v53, |v44|, |v44|
	v_max_f32_e32 v52, v53, v52
	v_max3_f32 v50, v50, v51, v52
	v_max_f32_e64 v51, |v39|, |v39|
	v_max_f32_e64 v52, |v38|, |v38|
	v_max_f32_e32 v51, v52, v51
	v_max_f32_e64 v52, |v41|, |v41|
	v_max_f32_e64 v53, |v40|, |v40|
	v_max_f32_e32 v52, v53, v52
	v_max3_f32 v50, v50, v51, v52
	v_max_f32_e64 v51, |v35|, |v35|
	v_max_f32_e64 v52, |v34|, |v34|
	v_max_f32_e32 v51, v52, v51
	v_max_f32_e64 v52, |v37|, |v37|
	v_max_f32_e64 v53, |v36|, |v36|
	v_max_f32_e32 v52, v53, v52
	v_max3_f32 v50, v50, v51, v52
	s_mov_b32 s10, 0xda24260
	s_mov_b32 s17, 0x40e00000
	s_ashr_i32 s3, s2, 1
	s_and_b32 s3, s3, 0xffffc000
	s_and_b32 s12, s2, 0x3fff
	s_nop 1
	v_max_f32_dpp v50, v50, v50 quad_perm:[1,0,3,2] row_mask:0xf bank_mask:0xf
	s_nop 1
	v_max_f32_dpp v50, v50, v50 quad_perm:[2,3,0,1] row_mask:0xf bank_mask:0xf
	s_nop 1
	v_max_f32_dpp v50, v50, v50 row_half_mirror row_mask:0xf bank_mask:0xf
	s_nop 1
	v_max_f32_dpp v50, v50, v50 row_mirror row_mask:0xf bank_mask:0xf
	s_nop 1
	v_readlane_b32 vcc_lo, v50, 0
	v_readlane_b32 vcc_hi, v50, 16
	s_max_u32 vcc_lo, vcc_lo, vcc_hi
	v_readlane_b32 vcc_hi, v50, 32
	s_nop 0
	s_max_u32 vcc_lo, vcc_lo, vcc_hi
	v_readlane_b32 vcc_hi, v50, 48
	s_nop 0
	s_max_u32 vcc_lo, vcc_lo, vcc_hi
	v_mov_b32_e32 v50, vcc_lo
	v_max_f32_e32 v50, s10, v50
	v_div_scale_f32 v51, s[10:11], v50, v50, s17
	v_rcp_f32_e32 v52, v51
	s_or_b32 s10, s3, s12
	s_bitcmp0_b32 s2, 14
	s_mov_b32 s2, 0xc0c00000
	v_fma_f32 v53, -v51, v52, 1.0
	v_fmac_f32_e32 v52, v53, v52
	v_div_scale_f32 v53, vcc, s17, v50, s17
	v_mul_f32_e32 v54, v53, v52
	v_fma_f32 v55, -v51, v54, v53
	v_fmac_f32_e32 v54, v55, v52
	v_fma_f32 v51, -v51, v54, v53
	v_div_fmas_f32 v51, v51, v52, v54
	v_div_fixup_f32 v51, v51, v50, s17
	v_mul_f32_e32 v46, v46, v51
	v_mov_b32_e32 v54, 0x40c00000
	v_med3_f32 v53, v46, s2, v54
	v_mul_f32_e32 v46, v47, v51
	v_med3_f32 v47, v46, s2, v54
	v_mov_b32_e32 v52, 0
	v_mul_f32_e32 v38, v38, v51
	v_mul_f32_e32 v39, v39, v51
	v_cvt_scalef32_pk_fp4_f32 v52, v53, v47, 1.0
	v_med3_f32 v38, v38, s2, v54
	v_med3_f32 v39, v39, s2, v54
	v_mov_b32_e32 v53, 0
	v_mul_f32_e32 v47, v48, v51
	v_mul_f32_e32 v48, v49, v51
	v_cvt_scalef32_pk_fp4_f32 v53, v38, v39, 1.0
	v_mul_f32_e32 v38, v40, v51
	v_mul_f32_e32 v39, v41, v51
	v_med3_f32 v47, v47, s2, v54
	v_med3_f32 v48, v48, s2, v54
	v_mul_f32_e32 v42, v42, v51
	v_mul_f32_e32 v43, v43, v51
	v_med3_f32 v38, v38, s2, v54
	v_med3_f32 v39, v39, s2, v54
	v_mul_f32_e32 v34, v34, v51
	v_mul_f32_e32 v35, v35, v51
	v_cvt_scalef32_pk_fp4_f32 v52, v47, v48, 1.0 op_sel:[0,0,1,0]
	v_med3_f32 v42, v42, s2, v54
	v_med3_f32 v43, v43, s2, v54
	v_cvt_scalef32_pk_fp4_f32 v53, v38, v39, 1.0 op_sel:[0,0,1,0]
	v_med3_f32 v34, v34, s2, v54
	v_med3_f32 v35, v35, s2, v54
	s_cselect_b64 s[12:13], -1, 0
	v_cvt_scalef32_pk_fp4_f32 v52, v42, v43, 1.0 op_sel:[0,0,0,1]
	v_mul_f32_e32 v42, v44, v51
	v_mul_f32_e32 v43, v45, v51
	v_cvt_scalef32_pk_fp4_f32 v53, v34, v35, 1.0 op_sel:[0,0,0,1]
	v_mul_f32_e32 v34, v36, v51
	v_mul_f32_e32 v35, v37, v51
	v_med3_f32 v42, v42, s2, v54
	v_med3_f32 v43, v43, s2, v54
	v_med3_f32 v34, v34, s2, v54
	v_med3_f32 v35, v35, s2, v54
	s_brev_b32 s11, 64
	s_and_b64 s[2:3], s[12:13], exec
	s_cselect_b32 s2, s11, 0x4000000
	s_add_u32 s17, s82, s2
	s_addc_u32 s18, s83, 0
	s_ashr_i32 s11, s10, 31
	s_lshl_b64 s[2:3], s[10:11], 9
	s_add_u32 s2, s17, s2
	v_mov_b32_e32 v46, 0
	v_cvt_scalef32_pk_fp4_f32 v52, v42, v43, 1.0 op_sel:[0,0,1,1]
	v_cvt_scalef32_pk_fp4_f32 v53, v34, v35, 1.0 op_sel:[0,0,1,1]
	s_addc_u32 s3, s18, s3
	v_lshlrev_b32_e32 v34, 3, v1
	global_store_dwordx2 v34, v[52:53], s[2:3]
	s_and_saveexec_b64 s[2:3], s[4:5]
	s_cbranch_execz .LBB0_154
	s_mov_b32 s17, 0x1d00000
	s_and_b64 s[12:13], s[12:13], exec
	s_cselect_b32 s12, s17, 0x1d00004
	s_add_u32 s12, s82, s12
	s_addc_u32 s13, s83, 0
	s_lshl_b64 s[10:11], s[10:11], 3
	s_add_u32 s10, s12, s10
	v_mul_f32_e32 v34, 0x3e124925, v50
	s_addc_u32 s11, s13, s11
	global_store_dword v46, v34, s[10:11]

; #define GAS __attribute__((address_space(1)))
; #define Q4(x) fminf(fmaxf((x) * sc, -6.f), 6.f)
; #define Q4(x) fminf(fmaxf((x) * sc, -6.f), 6.f)
; __device__ __forceinline__ void table_row_to_fp4(const f32x4 (&v)[4], int lane, bool isv, int r, unsigned char* ws) {
;     float m = 0.f;
; #pragma unroll
;     for (int j = 0; j < 4; ++j) m = fmaxf(fmaxf(m, fmaxf(fabsf(v[j].x), fabsf(v[j].y))), fmaxf(fabsf(v[j].z), fabsf(v[j].w)));
; #pragma unroll
;     for (int o = 1; o < 64; o <<= 1) m = fmaxf(m, __shfl_xor(m, o));
;     m = fmaxf(m, 1e-30f);
;     const float sc = 7.f / m;
;     unsigned w0 = 0u, w1 = 0u;
;     ...
;     w0 = __builtin_amdgcn_cvt_scalef32_pk_fp4_f32(w0, Q4(v[0].x), Q4(v[0].y), 1.0f, 0); w0 = __builtin_amdgcn_cvt_scalef32_pk_fp4_f32(w0, Q4(v[0].z), Q4(v[0].w), 1.0f, 1);
;     w0 = __builtin_amdgcn_cvt_scalef32_pk_fp4_f32(w0, Q4(v[1].x), Q4(v[1].y), 1.0f, 2); w0 = __builtin_amdgcn_cvt_scalef32_pk_fp4_f32(w0, Q4(v[1].z), Q4(v[1].w), 1.0f, 3);
;     w1 = __builtin_amdgcn_cvt_scalef32_pk_fp4_f32(w1, Q4(v[2].x), Q4(v[2].y), 1.0f, 0); w1 = __builtin_amdgcn_cvt_scalef32_pk_fp4_f32(w1, Q4(v[2].z), Q4(v[2].w), 1.0f, 1);
;     w1 = __builtin_amdgcn_cvt_scalef32_pk_fp4_f32(w1, Q4(v[3].x), Q4(v[3].y), 1.0f, 2); w1 = __builtin_amdgcn_cvt_scalef32_pk_fp4_f32(w1, Q4(v[3].z), Q4(v[3].w), 1.0f, 3);
;     ...
;     *((GAS v2u*)(ws + (isv ? WS_V8 : WS_U8) + (size_t)r * 512) + lane) = (v2u){w0, w1};
;     if (lane == 0) ((float*)(ws + (isv ? WS_DQV : WS_DQU)))[r] = m * (1.f / 7.f);
.LBB0_155:
	s_andn2_b64 vcc, exec, s[8:9]
	s_cbranch_vccnz .LBB0_160
	s_add_i32 s16, s16, s14
	s_cmpk_gt_i32 s16, 0x7fff
	s_cbranch_scc1 .LBB0_160
	s_waitcnt vmcnt(0)
	v_max_f32_e64 v34, |v31|, |v31|
	v_max_f32_e64 v35, |v30|, |v30|
	v_max_f32_e32 v34, v35, v34
	v_max_f32_e64 v35, |v33|, |v33|
	v_max_f32_e64 v36, |v32|, |v32|
	v_max_f32_e32 v35, v36, v35
	v_max3_f32 v34, v34, 0, v35
	v_max_f32_e64 v35, |v27|, |v27|
	v_max_f32_e64 v36, |v26|, |v26|
	v_max_f32_e32 v35, v36, v35
	v_max_f32_e64 v36, |v29|, |v29|
	v_max_f32_e64 v37, |v28|, |v28|
	v_max_f32_e32 v36, v37, v36
	v_max3_f32 v34, v34, v35, v36
	v_max_f32_e64 v35, |v23|, |v23|
	v_max_f32_e64 v36, |v22|, |v22|
	v_max_f32_e32 v35, v36, v35
	v_max_f32_e64 v36, |v25|, |v25|
	v_max_f32_e64 v37, |v24|, |v24|
	v_max_f32_e32 v36, v37, v36
	v_max3_f32 v34, v34, v35, v36
	v_max_f32_e64 v35, |v19|, |v19|
	v_max_f32_e64 v36, |v18|, |v18|
	v_max_f32_e32 v35, v36, v35
	v_max_f32_e64 v36, |v21|, |v21|
	v_max_f32_e64 v37, |v20|, |v20|
	v_max_f32_e32 v36, v37, v36
	v_max3_f32 v34, v34, v35, v36
	s_ashr_i32 s2, s16, 1
	s_and_b32 s8, s2, 0xffffc000
	s_mov_b32 s2, 0xda24260
	s_mov_b32 s12, 0x40e00000
	s_and_b32 s9, s16, 0x3fff
	s_or_b32 s8, s8, s9
	s_bitcmp0_b32 s16, 14
	s_cselect_b64 s[10:11], -1, 0
	s_brev_b32 s9, 64
	s_nop 1
	v_max_f32_dpp v34, v34, v34 quad_perm:[1,0,3,2] row_mask:0xf bank_mask:0xf
	s_nop 1
	v_max_f32_dpp v34, v34, v34 quad_perm:[2,3,0,1] row_mask:0xf bank_mask:0xf
	s_nop 1
	v_max_f32_dpp v34, v34, v34 row_half_mirror row_mask:0xf bank_mask:0xf
	s_nop 1
	v_max_f32_dpp v34, v34, v34 row_mirror row_mask:0xf bank_mask:0xf
	s_nop 1
	v_readlane_b32 vcc_lo, v34, 0
	v_readlane_b32 vcc_hi, v34, 16
	s_max_u32 vcc_lo, vcc_lo, vcc_hi
	v_readlane_b32 vcc_hi, v34, 32
	s_nop 0
	s_max_u32 vcc_lo, vcc_lo, vcc_hi
	v_readlane_b32 vcc_hi, v34, 48
	s_nop 0
	s_max_u32 vcc_lo, vcc_lo, vcc_hi
	v_mov_b32_e32 v34, vcc_lo
	v_max_f32_e32 v34, s2, v34
	v_div_scale_f32 v35, s[2:3], v34, v34, s12
	v_rcp_f32_e32 v36, v35
	s_mov_b32 s2, 0xc0c00000
	v_fma_f32 v37, -v35, v36, 1.0
	v_fmac_f32_e32 v36, v37, v36
	v_div_scale_f32 v37, vcc, s12, v34, s12
	v_mul_f32_e32 v38, v37, v36
	v_fma_f32 v39, -v35, v38, v37
	v_fmac_f32_e32 v38, v39, v36
	v_fma_f32 v35, -v35, v38, v37
	v_div_fmas_f32 v35, v35, v36, v38
	v_div_fixup_f32 v35, v35, v34, s12
	v_mul_f32_e32 v30, v30, v35
	v_mov_b32_e32 v38, 0x40c00000
	v_med3_f32 v37, v30, s2, v38
	v_mul_f32_e32 v30, v31, v35
	v_med3_f32 v31, v30, s2, v38
	v_mov_b32_e32 v36, 0
	v_mul_f32_e32 v22, v22, v35
	v_mul_f32_e32 v23, v23, v35
	v_cvt_scalef32_pk_fp4_f32 v36, v37, v31, 1.0
	v_med3_f32 v22, v22, s2, v38
	v_med3_f32 v23, v23, s2, v38
	v_mov_b32_e32 v37, 0
	v_mul_f32_e32 v31, v32, v35
	v_mul_f32_e32 v32, v33, v35
	v_cvt_scalef32_pk_fp4_f32 v37, v22, v23, 1.0
	v_mul_f32_e32 v22, v24, v35
	v_mul_f32_e32 v23, v25, v35
	v_med3_f32 v31, v31, s2, v38
	v_med3_f32 v32, v32, s2, v38
	v_mul_f32_e32 v26, v26, v35
	v_mul_f32_e32 v27, v27, v35
	v_med3_f32 v22, v22, s2, v38
	v_med3_f32 v23, v23, s2, v38
	v_mul_f32_e32 v18, v18, v35
	v_mul_f32_e32 v19, v19, v35
	v_cvt_scalef32_pk_fp4_f32 v36, v31, v32, 1.0 op_sel:[0,0,1,0]
	v_med3_f32 v26, v26, s2, v38
	v_med3_f32 v27, v27, s2, v38
	v_cvt_scalef32_pk_fp4_f32 v37, v22, v23, 1.0 op_sel:[0,0,1,0]
	v_med3_f32 v18, v18, s2, v38
	v_med3_f32 v19, v19, s2, v38
	v_cvt_scalef32_pk_fp4_f32 v36, v26, v27, 1.0 op_sel:[0,0,0,1]
	v_mul_f32_e32 v26, v28, v35
	v_mul_f32_e32 v27, v29, v35
	v_cvt_scalef32_pk_fp4_f32 v37, v18, v19, 1.0 op_sel:[0,0,0,1]
	v_mul_f32_e32 v18, v20, v35
	v_mul_f32_e32 v19, v21, v35
	v_med3_f32 v26, v26, s2, v38
	v_med3_f32 v27, v27, s2, v38
	v_med3_f32 v18, v18, s2, v38
	v_med3_f32 v19, v19, s2, v38
	s_and_b64 s[2:3], s[10:11], exec
	s_cselect_b32 s2, s9, 0x4000000
	s_add_u32 s12, s82, s2
	s_addc_u32 s13, s83, 0
	s_ashr_i32 s9, s8, 31
	s_lshl_b64 s[2:3], s[8:9], 9
	s_add_u32 s2, s12, s2
	v_mov_b32_e32 v30, 0
	v_cvt_scalef32_pk_fp4_f32 v36, v26, v27, 1.0 op_sel:[0,0,1,1]
	v_cvt_scalef32_pk_fp4_f32 v37, v18, v19, 1.0 op_sel:[0,0,1,1]
	s_addc_u32 s3, s13, s3
	v_lshlrev_b32_e32 v18, 3, v1
	global_store_dwordx2 v18, v[36:37], s[2:3]
	s_and_saveexec_b64 s[2:3], s[4:5]
	s_cbranch_execz .LBB0_159
	s_mov_b32 s12, 0x1d00000
	s_and_b64 s[10:11], s[10:11], exec
	s_cselect_b32 s10, s12, 0x1d00004
	s_add_u32 s10, s82, s10
	s_addc_u32 s11, s83, 0
	s_lshl_b64 s[8:9], s[8:9], 3
	s_add_u32 s8, s10, s8
	v_mul_f32_e32 v18, 0x3e124925, v34
	s_addc_u32 s9, s11, s9
	global_store_dword v30, v18, s[8:9]

; #define GAS __attribute__((address_space(1)))
; #define Q4(x) fminf(fmaxf((x) * sc, -6.f), 6.f)
; #define Q4(x) fminf(fmaxf((x) * sc, -6.f), 6.f)
; __device__ __forceinline__ void table_row_to_fp4(const f32x4 (&v)[4], int lane, bool isv, int r, unsigned char* ws) {
;     float m = 0.f;
; #pragma unroll
;     for (int j = 0; j < 4; ++j) m = fmaxf(fmaxf(m, fmaxf(fabsf(v[j].x), fabsf(v[j].y))), fmaxf(fabsf(v[j].z), fabsf(v[j].w)));
; #pragma unroll
;     for (int o = 1; o < 64; o <<= 1) m = fmaxf(m, __shfl_xor(m, o));
;     m = fmaxf(m, 1e-30f);
;     const float sc = 7.f / m;
;     unsigned w0 = 0u, w1 = 0u;
;     ...
;     w0 = __builtin_amdgcn_cvt_scalef32_pk_fp4_f32(w0, Q4(v[0].x), Q4(v[0].y), 1.0f, 0); w0 = __builtin_amdgcn_cvt_scalef32_pk_fp4_f32(w0, Q4(v[0].z), Q4(v[0].w), 1.0f, 1);
;     w0 = __builtin_amdgcn_cvt_scalef32_pk_fp4_f32(w0, Q4(v[1].x), Q4(v[1].y), 1.0f, 2); w0 = __builtin_amdgcn_cvt_scalef32_pk_fp4_f32(w0, Q4(v[1].z), Q4(v[1].w), 1.0f, 3);
;     w1 = __builtin_amdgcn_cvt_scalef32_pk_fp4_f32(w1, Q4(v[2].x), Q4(v[2].y), 1.0f, 0); w1 = __builtin_amdgcn_cvt_scalef32_pk_fp4_f32(w1, Q4(v[2].z), Q4(v[2].w), 1.0f, 1);
;     w1 = __builtin_amdgcn_cvt_scalef32_pk_fp4_f32(w1, Q4(v[3].x), Q4(v[3].y), 1.0f, 2); w1 = __builtin_amdgcn_cvt_scalef32_pk_fp4_f32(w1, Q4(v[3].z), Q4(v[3].w), 1.0f, 3);
;     ...
;     *((GAS v2u*)(ws + (isv ? WS_V8 : WS_U8) + (size_t)r * 512) + lane) = (v2u){w0, w1};
;     if (lane == 0) ((float*)(ws + (isv ? WS_DQV : WS_DQU)))[r] = m * (1.f / 7.f);
.LBB0_160:
	s_andn2_b64 vcc, exec, s[6:7]
	s_cbranch_vccnz .LBB0_165
	s_add_i32 s15, s15, s14
	s_cmpk_gt_i32 s15, 0x7fff
	s_cbranch_scc1 .LBB0_165
	s_waitcnt vmcnt(0)
	v_max_f32_e64 v18, |v15|, |v15|
	v_max_f32_e64 v19, |v14|, |v14|
	v_max_f32_e32 v18, v19, v18
	v_max_f32_e64 v19, |v17|, |v17|
	v_max_f32_e64 v20, |v16|, |v16|
	v_max_f32_e32 v19, v20, v19
	v_max3_f32 v18, v18, 0, v19
	v_max_f32_e64 v19, |v11|, |v11|
	v_max_f32_e64 v20, |v10|, |v10|
	v_max_f32_e32 v19, v20, v19
	v_max_f32_e64 v20, |v13|, |v13|
	v_max_f32_e64 v21, |v12|, |v12|
	v_max_f32_e32 v20, v21, v20
	v_max3_f32 v18, v18, v19, v20
	v_max_f32_e64 v19, |v7|, |v7|
	v_max_f32_e64 v20, |v6|, |v6|
	v_max_f32_e32 v19, v20, v19
	v_max_f32_e64 v20, |v9|, |v9|
	v_max_f32_e64 v21, |v8|, |v8|
	v_max_f32_e32 v20, v21, v20
	v_max3_f32 v18, v18, v19, v20
	v_max_f32_e64 v19, |v3|, |v3|
	v_max_f32_e64 v20, |v2|, |v2|
	v_max_f32_e32 v19, v20, v19
	v_max_f32_e64 v20, |v5|, |v5|
	v_max_f32_e64 v21, |v4|, |v4|
	v_max_f32_e32 v20, v21, v20
	v_max3_f32 v18, v18, v19, v20
	s_ashr_i32 s2, s15, 1
	s_and_b32 s6, s2, 0xffffc000
	s_mov_b32 s2, 0xda24260
	s_mov_b32 s10, 0x40e00000
	s_and_b32 s7, s15, 0x3fff
	s_or_b32 s6, s6, s7
	s_bitcmp0_b32 s15, 14
	s_cselect_b64 s[8:9], -1, 0
	s_brev_b32 s7, 64
	v_lshlrev_b32_e32 v1, 3, v1
	s_nop 1
	v_max_f32_dpp v18, v18, v18 quad_perm:[1,0,3,2] row_mask:0xf bank_mask:0xf
	s_nop 1
	v_max_f32_dpp v18, v18, v18 quad_perm:[2,3,0,1] row_mask:0xf bank_mask:0xf
	s_nop 1
	v_max_f32_dpp v18, v18, v18 row_half_mirror row_mask:0xf bank_mask:0xf
	s_nop 1
	v_max_f32_dpp v18, v18, v18 row_mirror row_mask:0xf bank_mask:0xf
	s_nop 1
	v_readlane_b32 vcc_lo, v18, 0
	v_readlane_b32 vcc_hi, v18, 16
	s_max_u32 vcc_lo, vcc_lo, vcc_hi
	v_readlane_b32 vcc_hi, v18, 32
	s_nop 0
	s_max_u32 vcc_lo, vcc_lo, vcc_hi
	v_readlane_b32 vcc_hi, v18, 48
	s_nop 0
	s_max_u32 vcc_lo, vcc_lo, vcc_hi
	v_mov_b32_e32 v18, vcc_lo
	v_max_f32_e32 v18, s2, v18
	v_div_scale_f32 v19, s[2:3], v18, v18, s10
	v_rcp_f32_e32 v20, v19
	s_mov_b32 s2, 0xc0c00000
	v_fma_f32 v21, -v19, v20, 1.0
	v_fmac_f32_e32 v20, v21, v20
	v_div_scale_f32 v21, vcc, s10, v18, s10
	v_mul_f32_e32 v22, v21, v20
	v_fma_f32 v23, -v19, v22, v21
	v_fmac_f32_e32 v22, v23, v20
	v_fma_f32 v19, -v19, v22, v21
	v_div_fmas_f32 v19, v19, v20, v22
	v_div_fixup_f32 v19, v19, v18, s10
	v_mul_f32_e32 v14, v14, v19
	v_mov_b32_e32 v22, 0x40c00000
	v_med3_f32 v21, v14, s2, v22
	v_mul_f32_e32 v14, v15, v19
	v_med3_f32 v15, v14, s2, v22
	v_mov_b32_e32 v20, 0
	v_mul_f32_e32 v6, v6, v19
	v_mul_f32_e32 v7, v7, v19
	v_cvt_scalef32_pk_fp4_f32 v20, v21, v15, 1.0
	v_med3_f32 v6, v6, s2, v22
	v_med3_f32 v7, v7, s2, v22
	v_mov_b32_e32 v21, 0
	v_mul_f32_e32 v15, v16, v19
	v_mul_f32_e32 v16, v17, v19
	v_cvt_scalef32_pk_fp4_f32 v21, v6, v7, 1.0
	v_mul_f32_e32 v6, v8, v19
	v_mul_f32_e32 v7, v9, v19
	v_med3_f32 v15, v15, s2, v22
	v_med3_f32 v16, v16, s2, v22
	v_mul_f32_e32 v10, v10, v19
	v_mul_f32_e32 v11, v11, v19
	v_med3_f32 v6, v6, s2, v22
	v_med3_f32 v7, v7, s2, v22
	v_mul_f32_e32 v2, v2, v19
	v_mul_f32_e32 v3, v3, v19
	v_cvt_scalef32_pk_fp4_f32 v20, v15, v16, 1.0 op_sel:[0,0,1,0]
	v_med3_f32 v10, v10, s2, v22
	v_med3_f32 v11, v11, s2, v22
	v_cvt_scalef32_pk_fp4_f32 v21, v6, v7, 1.0 op_sel:[0,0,1,0]
	v_med3_f32 v2, v2, s2, v22
	v_med3_f32 v3, v3, s2, v22
	v_cvt_scalef32_pk_fp4_f32 v20, v10, v11, 1.0 op_sel:[0,0,0,1]
	v_mul_f32_e32 v10, v12, v19
	v_mul_f32_e32 v11, v13, v19
	v_cvt_scalef32_pk_fp4_f32 v21, v2, v3, 1.0 op_sel:[0,0,0,1]
	v_mul_f32_e32 v2, v4, v19
	v_mul_f32_e32 v3, v5, v19
	v_med3_f32 v10, v10, s2, v22
	v_med3_f32 v11, v11, s2, v22
	v_med3_f32 v2, v2, s2, v22
	v_med3_f32 v3, v3, s2, v22
	s_and_b64 s[2:3], s[8:9], exec
	s_cselect_b32 s2, s7, 0x4000000
	s_add_u32 s10, s82, s2
	s_addc_u32 s11, s83, 0
	s_ashr_i32 s7, s6, 31
	s_lshl_b64 s[2:3], s[6:7], 9
	s_add_u32 s2, s10, s2
	v_mov_b32_e32 v14, 0
	v_cvt_scalef32_pk_fp4_f32 v20, v10, v11, 1.0 op_sel:[0,0,1,1]
	v_cvt_scalef32_pk_fp4_f32 v21, v2, v3, 1.0 op_sel:[0,0,1,1]
	s_addc_u32 s3, s11, s3
	global_store_dwordx2 v1, v[20:21], s[2:3]
	s_and_saveexec_b64 s[2:3], s[4:5]
	s_cbranch_execz .LBB0_164
	s_mov_b32 s10, 0x1d00000
	s_and_b64 s[4:5], s[8:9], exec
	s_cselect_b32 s4, s10, 0x1d00004
	s_add_u32 s8, s82, s4
	s_addc_u32 s9, s83, 0
	s_lshl_b64 s[4:5], s[6:7], 3
	s_add_u32 s4, s8, s4
	v_mul_f32_e32 v1, 0x3e124925, v18
	s_addc_u32 s5, s9, s5
	global_store_dword v14, v1, s[4:5]

; #define GAS __attribute__((address_space(1)))
; #define Q4(x) fminf(fmaxf((x) * sc, -6.f), 6.f)
; #define Q4(x) fminf(fmaxf((x) * sc, -6.f), 6.f)
; __device__ __forceinline__ void table_row_to_fp4(const f32x4 (&v)[4], int lane, bool isv, int r, unsigned char* ws) {
;     float m = 0.f;
; #pragma unroll
;     for (int j = 0; j < 4; ++j) m = fmaxf(fmaxf(m, fmaxf(fabsf(v[j].x), fabsf(v[j].y))), fmaxf(fabsf(v[j].z), fabsf(v[j].w)));
; #pragma unroll
;     for (int o = 1; o < 64; o <<= 1) m = fmaxf(m, __shfl_xor(m, o));
;     m = fmaxf(m, 1e-30f);
;     const float sc = 7.f / m;
;     unsigned w0 = 0u, w1 = 0u;
;     ...
;     w0 = __builtin_amdgcn_cvt_scalef32_pk_fp4_f32(w0, Q4(v[0].x), Q4(v[0].y), 1.0f, 0); w0 = __builtin_amdgcn_cvt_scalef32_pk_fp4_f32(w0, Q4(v[0].z), Q4(v[0].w), 1.0f, 1);
;     w0 = __builtin_amdgcn_cvt_scalef32_pk_fp4_f32(w0, Q4(v[1].x), Q4(v[1].y), 1.0f, 2); w0 = __builtin_amdgcn_cvt_scalef32_pk_fp4_f32(w0, Q4(v[1].z), Q4(v[1].w), 1.0f, 3);
;     w1 = __builtin_amdgcn_cvt_scalef32_pk_fp4_f32(w1, Q4(v[2].x), Q4(v[2].y), 1.0f, 0); w1 = __builtin_amdgcn_cvt_scalef32_pk_fp4_f32(w1, Q4(v[2].z), Q4(v[2].w), 1.0f, 1);
;     w1 = __builtin_amdgcn_cvt_scalef32_pk_fp4_f32(w1, Q4(v[3].x), Q4(v[3].y), 1.0f, 2); w1 = __builtin_amdgcn_cvt_scalef32_pk_fp4_f32(w1, Q4(v[3].z), Q4(v[3].w), 1.0f, 3);
;     ...
;     *((GAS v2u*)(ws + (isv ? WS_V8 : WS_U8) + (size_t)r * 512) + lane) = (v2u){w0, w1};
;     if (lane == 0) ((float*)(ws + (isv ? WS_DQV : WS_DQU)))[r] = m * (1.f / 7.f);
.LBB0_724:
	s_andn2_b64 vcc, exec, s[0:1]
	s_cbranch_vccnz .LBB0_729
	s_add_i32 s15, s15, s14
	s_cmpk_gt_i32 s15, 0x7fff
	s_cbranch_scc1 .LBB0_729
	s_waitcnt vmcnt(0)
	v_max_f32_e64 v18, |v15|, |v15|
	v_max_f32_e64 v19, |v14|, |v14|
	v_max_f32_e32 v18, v19, v18
	v_max_f32_e64 v19, |v17|, |v17|
	v_max_f32_e64 v20, |v16|, |v16|
	v_max_f32_e32 v19, v20, v19
	v_max3_f32 v18, v18, 0, v19
	v_max_f32_e64 v19, |v11|, |v11|
	v_max_f32_e64 v20, |v10|, |v10|
	v_max_f32_e32 v19, v20, v19
	v_max_f32_e64 v20, |v13|, |v13|
	v_max_f32_e64 v21, |v12|, |v12|
	v_max_f32_e32 v20, v21, v20
	v_max3_f32 v18, v18, v19, v20
	v_max_f32_e64 v19, |v7|, |v7|
	v_max_f32_e64 v20, |v6|, |v6|
	v_max_f32_e32 v19, v20, v19
	v_max_f32_e64 v20, |v9|, |v9|
	v_max_f32_e64 v21, |v8|, |v8|
	v_max_f32_e32 v20, v21, v20
	v_max3_f32 v18, v18, v19, v20
	v_max_f32_e64 v19, |v3|, |v3|
	v_max_f32_e64 v20, |v2|, |v2|
	v_max_f32_e32 v19, v20, v19
	v_max_f32_e64 v20, |v5|, |v5|
	v_max_f32_e64 v21, |v4|, |v4|
	v_max_f32_e32 v20, v21, v20
	v_max3_f32 v18, v18, v19, v20
	s_ashr_i32 s0, s15, 1
	s_and_b32 s2, s0, 0xffffc000
	s_mov_b32 s0, 0xda24260
	s_mov_b32 s10, 0x40e00000
	s_and_b32 s3, s15, 0x3fff
	v_lshlrev_b32_e32 v1, 3, v1
	s_nop 1
	v_max_f32_dpp v18, v18, v18 quad_perm:[1,0,3,2] row_mask:0xf bank_mask:0xf
	s_nop 1
	v_max_f32_dpp v18, v18, v18 quad_perm:[2,3,0,1] row_mask:0xf bank_mask:0xf
	s_nop 1
	v_max_f32_dpp v18, v18, v18 row_half_mirror row_mask:0xf bank_mask:0xf
	s_nop 1
	v_max_f32_dpp v18, v18, v18 row_mirror row_mask:0xf bank_mask:0xf
	s_nop 1
	v_readlane_b32 vcc_lo, v18, 0
	v_readlane_b32 vcc_hi, v18, 16
	s_max_u32 vcc_lo, vcc_lo, vcc_hi
	v_readlane_b32 vcc_hi, v18, 32
	s_nop 0
	s_max_u32 vcc_lo, vcc_lo, vcc_hi
	v_readlane_b32 vcc_hi, v18, 48
	s_nop 0
	s_max_u32 vcc_lo, vcc_lo, vcc_hi
	v_mov_b32_e32 v18, vcc_lo
	v_max_f32_e32 v18, s0, v18
	v_div_scale_f32 v19, s[0:1], v18, v18, s10
	v_rcp_f32_e32 v20, v19
	s_mov_b32 s1, 0xc0c00000
	s_or_b32 s0, s2, s3
	s_bitcmp0_b32 s15, 14
	v_fma_f32 v21, -v19, v20, 1.0
	v_fmac_f32_e32 v20, v21, v20
	v_div_scale_f32 v21, vcc, s10, v18, s10
	v_mul_f32_e32 v22, v21, v20
	v_fma_f32 v23, -v19, v22, v21
	v_fmac_f32_e32 v22, v23, v20
	v_fma_f32 v19, -v19, v22, v21
	v_div_fmas_f32 v19, v19, v20, v22
	v_div_fixup_f32 v19, v19, v18, s10
	v_mul_f32_e32 v14, v14, v19
	v_mov_b32_e32 v22, 0x40c00000
	v_med3_f32 v21, v14, s1, v22
	v_mul_f32_e32 v14, v15, v19
	v_med3_f32 v15, v14, s1, v22
	v_mov_b32_e32 v20, 0
	v_mul_f32_e32 v6, v6, v19
	v_mul_f32_e32 v7, v7, v19
	v_cvt_scalef32_pk_fp4_f32 v20, v21, v15, 1.0
	v_med3_f32 v6, v6, s1, v22
	v_med3_f32 v7, v7, s1, v22
	v_mov_b32_e32 v21, 0
	v_mul_f32_e32 v15, v16, v19
	v_mul_f32_e32 v16, v17, v19
	v_cvt_scalef32_pk_fp4_f32 v21, v6, v7, 1.0
	v_mul_f32_e32 v6, v8, v19
	v_mul_f32_e32 v7, v9, v19
	v_med3_f32 v15, v15, s1, v22
	v_med3_f32 v16, v16, s1, v22
	v_mul_f32_e32 v10, v10, v19
	v_mul_f32_e32 v11, v11, v19
	v_med3_f32 v6, v6, s1, v22
	v_med3_f32 v7, v7, s1, v22
	v_mul_f32_e32 v2, v2, v19
	v_mul_f32_e32 v3, v3, v19
	v_cvt_scalef32_pk_fp4_f32 v20, v15, v16, 1.0 op_sel:[0,0,1,0]
	v_med3_f32 v10, v10, s1, v22
	v_med3_f32 v11, v11, s1, v22
	v_cvt_scalef32_pk_fp4_f32 v21, v6, v7, 1.0 op_sel:[0,0,1,0]
	v_med3_f32 v2, v2, s1, v22
	v_med3_f32 v3, v3, s1, v22
	s_cselect_b64 s[8:9], -1, 0
	v_cvt_scalef32_pk_fp4_f32 v20, v10, v11, 1.0 op_sel:[0,0,0,1]
	v_mul_f32_e32 v10, v12, v19
	v_mul_f32_e32 v11, v13, v19
	v_cvt_scalef32_pk_fp4_f32 v21, v2, v3, 1.0 op_sel:[0,0,0,1]
	v_mul_f32_e32 v2, v4, v19
	v_mul_f32_e32 v3, v5, v19
	v_med3_f32 v10, v10, s1, v22
	v_med3_f32 v11, v11, s1, v22
	v_med3_f32 v2, v2, s1, v22
	v_med3_f32 v3, v3, s1, v22
	s_brev_b32 s1, 64
	s_and_b64 s[2:3], s[8:9], exec
	s_cselect_b32 s1, s1, 0x4000000
	s_add_u32 s10, s82, s1
	s_addc_u32 s11, s83, 0
	s_ashr_i32 s1, s0, 31
	s_lshl_b64 s[2:3], s[0:1], 9
	s_add_u32 s2, s10, s2
	v_mov_b32_e32 v14, 0
	v_cvt_scalef32_pk_fp4_f32 v20, v10, v11, 1.0 op_sel:[0,0,1,1]
	v_cvt_scalef32_pk_fp4_f32 v21, v2, v3, 1.0 op_sel:[0,0,1,1]
	s_addc_u32 s3, s11, s3
	global_store_dwordx2 v1, v[20:21], s[2:3]
	s_and_saveexec_b64 s[2:3], s[4:5]
	s_cbranch_execz .LBB0_728
	s_mov_b32 s10, 0x1d00000
	s_and_b64 s[4:5], s[8:9], exec
	s_cselect_b32 s4, s10, 0x1d00004
	s_add_u32 s4, s82, s4
	s_addc_u32 s5, s83, 0
	s_lshl_b64 s[0:1], s[0:1], 3
	s_add_u32 s0, s4, s0
	v_mul_f32_e32 v1, 0x3e124925, v18
	s_addc_u32 s1, s5, s1
	global_store_dword v14, v1, s[0:1]

; #define GAS __attribute__((address_space(1)))
; #define Q4(x) fminf(fmaxf((x) * sc, -6.f), 6.f)
; #define Q4(x) fminf(fmaxf((x) * sc, -6.f), 6.f)
; __device__ __forceinline__ void table_row_to_fp4(const f32x4 (&v)[4], int lane, bool isv, int r, unsigned char* ws) {
;     float m = 0.f;
; #pragma unroll
;     for (int j = 0; j < 4; ++j) m = fmaxf(fmaxf(m, fmaxf(fabsf(v[j].x), fabsf(v[j].y))), fmaxf(fabsf(v[j].z), fabsf(v[j].w)));
; #pragma unroll
;     for (int o = 1; o < 64; o <<= 1) m = fmaxf(m, __shfl_xor(m, o));
;     m = fmaxf(m, 1e-30f);
;     const float sc = 7.f / m;
;     unsigned w0 = 0u, w1 = 0u;
;     ...
;     w0 = __builtin_amdgcn_cvt_scalef32_pk_fp4_f32(w0, Q4(v[0].x), Q4(v[0].y), 1.0f, 0); w0 = __builtin_amdgcn_cvt_scalef32_pk_fp4_f32(w0, Q4(v[0].z), Q4(v[0].w), 1.0f, 1);
;     w0 = __builtin_amdgcn_cvt_scalef32_pk_fp4_f32(w0, Q4(v[1].x), Q4(v[1].y), 1.0f, 2); w0 = __builtin_amdgcn_cvt_scalef32_pk_fp4_f32(w0, Q4(v[1].z), Q4(v[1].w), 1.0f, 3);
;     w1 = __builtin_amdgcn_cvt_scalef32_pk_fp4_f32(w1, Q4(v[2].x), Q4(v[2].y), 1.0f, 0); w1 = __builtin_amdgcn_cvt_scalef32_pk_fp4_f32(w1, Q4(v[2].z), Q4(v[2].w), 1.0f, 1);
;     w1 = __builtin_amdgcn_cvt_scalef32_pk_fp4_f32(w1, Q4(v[3].x), Q4(v[3].y), 1.0f, 2); w1 = __builtin_amdgcn_cvt_scalef32_pk_fp4_f32(w1, Q4(v[3].z), Q4(v[3].w), 1.0f, 3);
;     ...
;     *((GAS v2u*)(ws + (isv ? WS_V8 : WS_U8) + (size_t)r * 512) + lane) = (v2u){w0, w1};
;     if (lane == 0) ((float*)(ws + (isv ? WS_DQV : WS_DQU)))[r] = m * (1.f / 7.f);
.LBB0_911:
	s_andn2_b64 vcc, exec, s[4:5]
	v_cmp_eq_u32_e64 s[4:5], 0, v1
	s_cbranch_vccnz .LBB0_916
	s_add_i32 s2, s2, s14
	s_cmp_gt_i32 s2, 0xffff
	s_cbranch_scc1 .LBB0_916
	s_waitcnt vmcnt(0)
	v_max_f32_e64 v50, |v47|, |v47|
	v_max_f32_e64 v51, |v46|, |v46|
	v_max_f32_e32 v50, v51, v50
	v_max_f32_e64 v51, |v49|, |v49|
	v_max_f32_e64 v52, |v48|, |v48|
	v_max_f32_e32 v51, v52, v51
	v_max3_f32 v50, v50, 0, v51
	v_max_f32_e64 v51, |v43|, |v43|
	v_max_f32_e64 v52, |v42|, |v42|
	v_max_f32_e32 v51, v52, v51
	v_max_f32_e64 v52, |v45|, |v45|
	v_max_f32_e64 v53, |v44|, |v44|
	v_max_f32_e32 v52, v53, v52
	v_max3_f32 v50, v50, v51, v52
	v_max_f32_e64 v51, |v39|, |v39|
	v_max_f32_e64 v52, |v38|, |v38|
	v_max_f32_e32 v51, v52, v51
	v_max_f32_e64 v52, |v41|, |v41|
	v_max_f32_e64 v53, |v40|, |v40|
	v_max_f32_e32 v52, v53, v52
	v_max3_f32 v50, v50, v51, v52
	v_max_f32_e64 v51, |v35|, |v35|
	v_max_f32_e64 v52, |v34|, |v34|
	v_max_f32_e32 v51, v52, v51
	v_max_f32_e64 v52, |v37|, |v37|
	v_max_f32_e64 v53, |v36|, |v36|
	v_max_f32_e32 v52, v53, v52
	v_max3_f32 v50, v50, v51, v52
	s_mov_b32 s10, 0xda24260
	s_mov_b32 s17, 0x40e00000
	s_ashr_i32 s3, s2, 1
	s_and_b32 s3, s3, 0xffffc000
	s_and_b32 s12, s2, 0x3fff
	s_nop 1
	v_max_f32_dpp v50, v50, v50 quad_perm:[1,0,3,2] row_mask:0xf bank_mask:0xf
	s_nop 1
	v_max_f32_dpp v50, v50, v50 quad_perm:[2,3,0,1] row_mask:0xf bank_mask:0xf
	s_nop 1
	v_max_f32_dpp v50, v50, v50 row_half_mirror row_mask:0xf bank_mask:0xf
	s_nop 1
	v_max_f32_dpp v50, v50, v50 row_mirror row_mask:0xf bank_mask:0xf
	s_nop 1
	v_readlane_b32 vcc_lo, v50, 0
	v_readlane_b32 vcc_hi, v50, 16
	s_max_u32 vcc_lo, vcc_lo, vcc_hi
	v_readlane_b32 vcc_hi, v50, 32
	s_nop 0
	s_max_u32 vcc_lo, vcc_lo, vcc_hi
	v_readlane_b32 vcc_hi, v50, 48
	s_nop 0
	s_max_u32 vcc_lo, vcc_lo, vcc_hi
	v_mov_b32_e32 v50, vcc_lo
	v_max_f32_e32 v50, s10, v50
	v_div_scale_f32 v51, s[10:11], v50, v50, s17
	v_rcp_f32_e32 v52, v51
	s_or_b32 s10, s3, s12
	s_bitcmp0_b32 s2, 14
	s_mov_b32 s2, 0xc0c00000
	v_fma_f32 v53, -v51, v52, 1.0
	v_fmac_f32_e32 v52, v53, v52
	v_div_scale_f32 v53, vcc, s17, v50, s17
	v_mul_f32_e32 v54, v53, v52
	v_fma_f32 v55, -v51, v54, v53
	v_fmac_f32_e32 v54, v55, v52
	v_fma_f32 v51, -v51, v54, v53
	v_div_fmas_f32 v51, v51, v52, v54
	v_div_fixup_f32 v51, v51, v50, s17
	v_mul_f32_e32 v46, v46, v51
	v_mov_b32_e32 v54, 0x40c00000
	v_med3_f32 v53, v46, s2, v54
	v_mul_f32_e32 v46, v47, v51
	v_med3_f32 v47, v46, s2, v54
	v_mov_b32_e32 v52, 0
	v_mul_f32_e32 v38, v38, v51
	v_mul_f32_e32 v39, v39, v51
	v_cvt_scalef32_pk_fp4_f32 v52, v53, v47, 1.0
	v_med3_f32 v38, v38, s2, v54
	v_med3_f32 v39, v39, s2, v54
	v_mov_b32_e32 v53, 0
	v_mul_f32_e32 v47, v48, v51
	v_mul_f32_e32 v48, v49, v51
	v_cvt_scalef32_pk_fp4_f32 v53, v38, v39, 1.0
	v_mul_f32_e32 v38, v40, v51
	v_mul_f32_e32 v39, v41, v51
	v_med3_f32 v47, v47, s2, v54
	v_med3_f32 v48, v48, s2, v54
	v_mul_f32_e32 v42, v42, v51
	v_mul_f32_e32 v43, v43, v51
	v_med3_f32 v38, v38, s2, v54
	v_med3_f32 v39, v39, s2, v54
	v_mul_f32_e32 v34, v34, v51
	v_mul_f32_e32 v35, v35, v51
	v_cvt_scalef32_pk_fp4_f32 v52, v47, v48, 1.0 op_sel:[0,0,1,0]
	v_med3_f32 v42, v42, s2, v54
	v_med3_f32 v43, v43, s2, v54
	v_cvt_scalef32_pk_fp4_f32 v53, v38, v39, 1.0 op_sel:[0,0,1,0]
	v_med3_f32 v34, v34, s2, v54
	v_med3_f32 v35, v35, s2, v54
	s_cselect_b64 s[12:13], -1, 0
	v_cvt_scalef32_pk_fp4_f32 v52, v42, v43, 1.0 op_sel:[0,0,0,1]
	v_mul_f32_e32 v42, v44, v51
	v_mul_f32_e32 v43, v45, v51
	v_cvt_scalef32_pk_fp4_f32 v53, v34, v35, 1.0 op_sel:[0,0,0,1]
	v_mul_f32_e32 v34, v36, v51
	v_mul_f32_e32 v35, v37, v51
	v_med3_f32 v42, v42, s2, v54
	v_med3_f32 v43, v43, s2, v54
	v_med3_f32 v34, v34, s2, v54
	v_med3_f32 v35, v35, s2, v54
	s_brev_b32 s11, 64
	s_and_b64 s[2:3], s[12:13], exec
	s_cselect_b32 s2, s11, 0x4000000
	s_add_u32 s17, s82, s2
	s_addc_u32 s18, s83, 0
	s_ashr_i32 s11, s10, 31
	s_lshl_b64 s[2:3], s[10:11], 9
	s_add_u32 s2, s17, s2
	v_mov_b32_e32 v46, 0
	v_cvt_scalef32_pk_fp4_f32 v52, v42, v43, 1.0 op_sel:[0,0,1,1]
	v_cvt_scalef32_pk_fp4_f32 v53, v34, v35, 1.0 op_sel:[0,0,1,1]
	s_addc_u32 s3, s18, s3
	v_lshlrev_b32_e32 v34, 3, v1
	global_store_dwordx2 v34, v[52:53], s[2:3]
	s_and_saveexec_b64 s[2:3], s[4:5]
	s_cbranch_execz .LBB0_915
	s_mov_b32 s17, 0x1d00000
	s_and_b64 s[12:13], s[12:13], exec
	s_cselect_b32 s12, s17, 0x1d00004
	s_add_u32 s12, s82, s12
	s_addc_u32 s13, s83, 0
	s_lshl_b64 s[10:11], s[10:11], 3
	s_add_u32 s10, s12, s10
	v_mul_f32_e32 v34, 0x3e124925, v50
	s_addc_u32 s11, s13, s11
	global_store_dword v46, v34, s[10:11]

; #define GAS __attribute__((address_space(1)))
; #define Q4(x) fminf(fmaxf((x) * sc, -6.f), 6.f)
; #define Q4(x) fminf(fmaxf((x) * sc, -6.f), 6.f)
; __device__ __forceinline__ void table_row_to_fp4(const f32x4 (&v)[4], int lane, bool isv, int r, unsigned char* ws) {
;     float m = 0.f;
; #pragma unroll
;     for (int j = 0; j < 4; ++j) m = fmaxf(fmaxf(m, fmaxf(fabsf(v[j].x), fabsf(v[j].y))), fmaxf(fabsf(v[j].z), fabsf(v[j].w)));
; #pragma unroll
;     for (int o = 1; o < 64; o <<= 1) m = fmaxf(m, __shfl_xor(m, o));
;     m = fmaxf(m, 1e-30f);
;     const float sc = 7.f / m;
;     unsigned w0 = 0u, w1 = 0u;
;     ...
;     w0 = __builtin_amdgcn_cvt_scalef32_pk_fp4_f32(w0, Q4(v[0].x), Q4(v[0].y), 1.0f, 0); w0 = __builtin_amdgcn_cvt_scalef32_pk_fp4_f32(w0, Q4(v[0].z), Q4(v[0].w), 1.0f, 1);
;     w0 = __builtin_amdgcn_cvt_scalef32_pk_fp4_f32(w0, Q4(v[1].x), Q4(v[1].y), 1.0f, 2); w0 = __builtin_amdgcn_cvt_scalef32_pk_fp4_f32(w0, Q4(v[1].z), Q4(v[1].w), 1.0f, 3);
;     w1 = __builtin_amdgcn_cvt_scalef32_pk_fp4_f32(w1, Q4(v[2].x), Q4(v[2].y), 1.0f, 0); w1 = __builtin_amdgcn_cvt_scalef32_pk_fp4_f32(w1, Q4(v[2].z), Q4(v[2].w), 1.0f, 1);
;     w1 = __builtin_amdgcn_cvt_scalef32_pk_fp4_f32(w1, Q4(v[3].x), Q4(v[3].y), 1.0f, 2); w1 = __builtin_amdgcn_cvt_scalef32_pk_fp4_f32(w1, Q4(v[3].z), Q4(v[3].w), 1.0f, 3);
;     ...
;     *((GAS v2u*)(ws + (isv ? WS_V8 : WS_U8) + (size_t)r * 512) + lane) = (v2u){w0, w1};
;     if (lane == 0) ((float*)(ws + (isv ? WS_DQV : WS_DQU)))[r] = m * (1.f / 7.f);
.LBB0_916:
	s_andn2_b64 vcc, exec, s[8:9]
	s_cbranch_vccnz .LBB0_921
	s_add_i32 s16, s16, s14
	s_cmp_gt_i32 s16, 0xffff
	s_cbranch_scc1 .LBB0_921
	s_waitcnt vmcnt(0)
	v_max_f32_e64 v34, |v31|, |v31|
	v_max_f32_e64 v35, |v30|, |v30|
	v_max_f32_e32 v34, v35, v34
	v_max_f32_e64 v35, |v33|, |v33|
	v_max_f32_e64 v36, |v32|, |v32|
	v_max_f32_e32 v35, v36, v35
	v_max3_f32 v34, v34, 0, v35
	v_max_f32_e64 v35, |v27|, |v27|
	v_max_f32_e64 v36, |v26|, |v26|
	v_max_f32_e32 v35, v36, v35
	v_max_f32_e64 v36, |v29|, |v29|
	v_max_f32_e64 v37, |v28|, |v28|
	v_max_f32_e32 v36, v37, v36
	v_max3_f32 v34, v34, v35, v36
	v_max_f32_e64 v35, |v23|, |v23|
	v_max_f32_e64 v36, |v22|, |v22|
	v_max_f32_e32 v35, v36, v35
	v_max_f32_e64 v36, |v25|, |v25|
	v_max_f32_e64 v37, |v24|, |v24|
	v_max_f32_e32 v36, v37, v36
	v_max3_f32 v34, v34, v35, v36
	v_max_f32_e64 v35, |v19|, |v19|
	v_max_f32_e64 v36, |v18|, |v18|
	v_max_f32_e32 v35, v36, v35
	v_max_f32_e64 v36, |v21|, |v21|
	v_max_f32_e64 v37, |v20|, |v20|
	v_max_f32_e32 v36, v37, v36
	v_max3_f32 v34, v34, v35, v36
	s_ashr_i32 s2, s16, 1
	s_and_b32 s8, s2, 0xffffc000
	s_mov_b32 s2, 0xda24260
	s_mov_b32 s12, 0x40e00000
	s_and_b32 s9, s16, 0x3fff
	s_or_b32 s8, s8, s9
	s_bitcmp0_b32 s16, 14
	s_cselect_b64 s[10:11], -1, 0
	s_brev_b32 s9, 64
	s_nop 1
	v_max_f32_dpp v34, v34, v34 quad_perm:[1,0,3,2] row_mask:0xf bank_mask:0xf
	s_nop 1
	v_max_f32_dpp v34, v34, v34 quad_perm:[2,3,0,1] row_mask:0xf bank_mask:0xf
	s_nop 1
	v_max_f32_dpp v34, v34, v34 row_half_mirror row_mask:0xf bank_mask:0xf
	s_nop 1
	v_max_f32_dpp v34, v34, v34 row_mirror row_mask:0xf bank_mask:0xf
	s_nop 1
	v_readlane_b32 vcc_lo, v34, 0
	v_readlane_b32 vcc_hi, v34, 16
	s_max_u32 vcc_lo, vcc_lo, vcc_hi
	v_readlane_b32 vcc_hi, v34, 32
	s_nop 0
	s_max_u32 vcc_lo, vcc_lo, vcc_hi
	v_readlane_b32 vcc_hi, v34, 48
	s_nop 0
	s_max_u32 vcc_lo, vcc_lo, vcc_hi
	v_mov_b32_e32 v34, vcc_lo
	v_max_f32_e32 v34, s2, v34
	v_div_scale_f32 v35, s[2:3], v34, v34, s12
	v_rcp_f32_e32 v36, v35
	s_mov_b32 s2, 0xc0c00000
	v_fma_f32 v37, -v35, v36, 1.0
	v_fmac_f32_e32 v36, v37, v36
	v_div_scale_f32 v37, vcc, s12, v34, s12
	v_mul_f32_e32 v38, v37, v36
	v_fma_f32 v39, -v35, v38, v37
	v_fmac_f32_e32 v38, v39, v36
	v_fma_f32 v35, -v35, v38, v37
	v_div_fmas_f32 v35, v35, v36, v38
	v_div_fixup_f32 v35, v35, v34, s12
	v_mul_f32_e32 v30, v30, v35
	v_mov_b32_e32 v38, 0x40c00000
	v_med3_f32 v37, v30, s2, v38
	v_mul_f32_e32 v30, v31, v35
	v_med3_f32 v31, v30, s2, v38
	v_mov_b32_e32 v36, 0
	v_mul_f32_e32 v22, v22, v35
	v_mul_f32_e32 v23, v23, v35
	v_cvt_scalef32_pk_fp4_f32 v36, v37, v31, 1.0
	v_med3_f32 v22, v22, s2, v38
	v_med3_f32 v23, v23, s2, v38
	v_mov_b32_e32 v37, 0
	v_mul_f32_e32 v31, v32, v35
	v_mul_f32_e32 v32, v33, v35
	v_cvt_scalef32_pk_fp4_f32 v37, v22, v23, 1.0
	v_mul_f32_e32 v22, v24, v35
	v_mul_f32_e32 v23, v25, v35
	v_med3_f32 v31, v31, s2, v38
	v_med3_f32 v32, v32, s2, v38
	v_mul_f32_e32 v26, v26, v35
	v_mul_f32_e32 v27, v27, v35
	v_med3_f32 v22, v22, s2, v38
	v_med3_f32 v23, v23, s2, v38
	v_mul_f32_e32 v18, v18, v35
	v_mul_f32_e32 v19, v19, v35
	v_cvt_scalef32_pk_fp4_f32 v36, v31, v32, 1.0 op_sel:[0,0,1,0]
	v_med3_f32 v26, v26, s2, v38
	v_med3_f32 v27, v27, s2, v38
	v_cvt_scalef32_pk_fp4_f32 v37, v22, v23, 1.0 op_sel:[0,0,1,0]
	v_med3_f32 v18, v18, s2, v38
	v_med3_f32 v19, v19, s2, v38
	v_cvt_scalef32_pk_fp4_f32 v36, v26, v27, 1.0 op_sel:[0,0,0,1]
	v_mul_f32_e32 v26, v28, v35
	v_mul_f32_e32 v27, v29, v35
	v_cvt_scalef32_pk_fp4_f32 v37, v18, v19, 1.0 op_sel:[0,0,0,1]
	v_mul_f32_e32 v18, v20, v35
	v_mul_f32_e32 v19, v21, v35
	v_med3_f32 v26, v26, s2, v38
	v_med3_f32 v27, v27, s2, v38
	v_med3_f32 v18, v18, s2, v38
	v_med3_f32 v19, v19, s2, v38
	s_and_b64 s[2:3], s[10:11], exec
	s_cselect_b32 s2, s9, 0x4000000
	s_add_u32 s12, s82, s2
	s_addc_u32 s13, s83, 0
	s_ashr_i32 s9, s8, 31
	s_lshl_b64 s[2:3], s[8:9], 9
	s_add_u32 s2, s12, s2
	v_mov_b32_e32 v30, 0
	v_cvt_scalef32_pk_fp4_f32 v36, v26, v27, 1.0 op_sel:[0,0,1,1]
	v_cvt_scalef32_pk_fp4_f32 v37, v18, v19, 1.0 op_sel:[0,0,1,1]
	s_addc_u32 s3, s13, s3
	v_lshlrev_b32_e32 v18, 3, v1
	global_store_dwordx2 v18, v[36:37], s[2:3]
	s_and_saveexec_b64 s[2:3], s[4:5]
	s_cbranch_execz .LBB0_920
	s_mov_b32 s12, 0x1d00000
	s_and_b64 s[10:11], s[10:11], exec
	s_cselect_b32 s10, s12, 0x1d00004
	s_add_u32 s10, s82, s10
	s_addc_u32 s11, s83, 0
	s_lshl_b64 s[8:9], s[8:9], 3
	s_add_u32 s8, s10, s8
	v_mul_f32_e32 v18, 0x3e124925, v34
	s_addc_u32 s9, s11, s9
	global_store_dword v30, v18, s[8:9]

; #define GAS __attribute__((address_space(1)))
; #define Q4(x) fminf(fmaxf((x) * sc, -6.f), 6.f)
; #define Q4(x) fminf(fmaxf((x) * sc, -6.f), 6.f)
; __device__ __forceinline__ void table_row_to_fp4(const f32x4 (&v)[4], int lane, bool isv, int r, unsigned char* ws) {
;     ...
;     for (int j = 0; j < 4; ++j) m = fmaxf(fmaxf(m, fmaxf(fabsf(v[j].x), fabsf(v[j].y))), fmaxf(fabsf(v[j].z), fabsf(v[j].w)));
; #pragma unroll
;     for (int o = 1; o < 64; o <<= 1) m = fmaxf(m, __shfl_xor(m, o));
;     m = fmaxf(m, 1e-30f);
;     const float sc = 7.f / m;
;     unsigned w0 = 0u, w1 = 0u;
;     ...
;     w0 = __builtin_amdgcn_cvt_scalef32_pk_fp4_f32(w0, Q4(v[0].x), Q4(v[0].y), 1.0f, 0); w0 = __builtin_amdgcn_cvt_scalef32_pk_fp4_f32(w0, Q4(v[0].z), Q4(v[0].w), 1.0f, 1);
;     w0 = __builtin_amdgcn_cvt_scalef32_pk_fp4_f32(w0, Q4(v[1].x), Q4(v[1].y), 1.0f, 2); w0 = __builtin_amdgcn_cvt_scalef32_pk_fp4_f32(w0, Q4(v[1].z), Q4(v[1].w), 1.0f, 3);
;     w1 = __builtin_amdgcn_cvt_scalef32_pk_fp4_f32(w1, Q4(v[2].x), Q4(v[2].y), 1.0f, 0); w1 = __builtin_amdgcn_cvt_scalef32_pk_fp4_f32(w1, Q4(v[2].z), Q4(v[2].w), 1.0f, 1);
;     w1 = __builtin_amdgcn_cvt_scalef32_pk_fp4_f32(w1, Q4(v[3].x), Q4(v[3].y), 1.0f, 2); w1 = __builtin_amdgcn_cvt_scalef32_pk_fp4_f32(w1, Q4(v[3].z), Q4(v[3].w), 1.0f, 3);
;     ...
;     *((GAS v2u*)(ws + (isv ? WS_V8 : WS_U8) + (size_t)r * 512) + lane) = (v2u){w0, w1};
;     if (lane == 0) ((float*)(ws + (isv ? WS_DQV : WS_DQU)))[r] = m * (1.f / 7.f);
; __device__ __forceinline__ void barrier_side_convert(int k, const float* U, const float* V, unsigned char* ws) {
;     ...
;     for (int jj = 0; jj < 3; ++jj) { const int j = wave - 1 + 7 * jj;
;         if (j < RB && g0 + j < glim) { const int g = g0 + j, tb = g >> 14, r = NEXP * (tb >> 1) + (g & (NEXP - 1)); table_row_to_fp4(v[jj], lane, (tb & 1) != 0, r, ws); } }
.LBB0_921:
	s_andn2_b64 vcc, exec, s[0:1]
	s_cbranch_vccnz .LBB0_926
	s_add_i32 s15, s15, s14
	s_cmp_gt_i32 s15, 0xffff
	s_cbranch_scc1 .LBB0_926
	s_waitcnt vmcnt(0)
	v_max_f32_e64 v18, |v15|, |v15|
	v_max_f32_e64 v19, |v14|, |v14|
	v_max_f32_e32 v18, v19, v18
	v_max_f32_e64 v19, |v17|, |v17|
	v_max_f32_e64 v20, |v16|, |v16|
	v_max_f32_e32 v19, v20, v19
	v_max3_f32 v18, v18, 0, v19
	v_max_f32_e64 v19, |v11|, |v11|
	v_max_f32_e64 v20, |v10|, |v10|
	v_max_f32_e32 v19, v20, v19
	v_max_f32_e64 v20, |v13|, |v13|
	v_max_f32_e64 v21, |v12|, |v12|
	v_max_f32_e32 v20, v21, v20
	v_max3_f32 v18, v18, v19, v20
	v_max_f32_e64 v19, |v7|, |v7|
	v_max_f32_e64 v20, |v6|, |v6|
	v_max_f32_e32 v19, v20, v19
	v_max_f32_e64 v20, |v9|, |v9|
	v_max_f32_e64 v21, |v8|, |v8|
	v_max_f32_e32 v20, v21, v20
	v_max3_f32 v18, v18, v19, v20
	v_max_f32_e64 v19, |v3|, |v3|
	v_max_f32_e64 v20, |v2|, |v2|
	v_max_f32_e32 v19, v20, v19
	v_max_f32_e64 v20, |v5|, |v5|
	v_max_f32_e64 v21, |v4|, |v4|
	v_max_f32_e32 v20, v21, v20
	v_max3_f32 v18, v18, v19, v20
	s_ashr_i32 s0, s15, 1
	s_and_b32 s2, s0, 0xffffc000
	s_mov_b32 s0, 0xda24260
	s_mov_b32 s10, 0x40e00000
	s_and_b32 s3, s15, 0x3fff
	v_lshlrev_b32_e32 v1, 3, v1
	s_nop 1
	v_max_f32_dpp v18, v18, v18 quad_perm:[1,0,3,2] row_mask:0xf bank_mask:0xf
	s_nop 1
	v_max_f32_dpp v18, v18, v18 quad_perm:[2,3,0,1] row_mask:0xf bank_mask:0xf
	s_nop 1
	v_max_f32_dpp v18, v18, v18 row_half_mirror row_mask:0xf bank_mask:0xf
	s_nop 1
	v_max_f32_dpp v18, v18, v18 row_mirror row_mask:0xf bank_mask:0xf
	s_nop 1
	v_readlane_b32 vcc_lo, v18, 0
	v_readlane_b32 vcc_hi, v18, 16
	s_max_u32 vcc_lo, vcc_lo, vcc_hi
	v_readlane_b32 vcc_hi, v18, 32
	s_nop 0
	s_max_u32 vcc_lo, vcc_lo, vcc_hi
	v_readlane_b32 vcc_hi, v18, 48
	s_nop 0
	s_max_u32 vcc_lo, vcc_lo, vcc_hi
	v_mov_b32_e32 v18, vcc_lo
	v_max_f32_e32 v18, s0, v18
	v_div_scale_f32 v19, s[0:1], v18, v18, s10
	v_rcp_f32_e32 v20, v19
	s_mov_b32 s1, 0xc0c00000
	s_or_b32 s0, s2, s3
	s_bitcmp0_b32 s15, 14
	v_fma_f32 v21, -v19, v20, 1.0
	v_fmac_f32_e32 v20, v21, v20
	v_div_scale_f32 v21, vcc, s10, v18, s10
	v_mul_f32_e32 v22, v21, v20
	v_fma_f32 v23, -v19, v22, v21
	v_fmac_f32_e32 v22, v23, v20
	v_fma_f32 v19, -v19, v22, v21
	v_div_fmas_f32 v19, v19, v20, v22
	v_div_fixup_f32 v19, v19, v18, s10
	v_mul_f32_e32 v14, v14, v19
	v_mov_b32_e32 v22, 0x40c00000
	v_med3_f32 v21, v14, s1, v22
	v_mul_f32_e32 v14, v15, v19
	v_med3_f32 v15, v14, s1, v22
	v_mov_b32_e32 v20, 0
	v_mul_f32_e32 v6, v6, v19
	v_mul_f32_e32 v7, v7, v19
	v_cvt_scalef32_pk_fp4_f32 v20, v21, v15, 1.0
	v_med3_f32 v6, v6, s1, v22
	v_med3_f32 v7, v7, s1, v22
	v_mov_b32_e32 v21, 0
	v_mul_f32_e32 v15, v16, v19
	v_mul_f32_e32 v16, v17, v19
	v_cvt_scalef32_pk_fp4_f32 v21, v6, v7, 1.0
	v_mul_f32_e32 v6, v8, v19
	v_mul_f32_e32 v7, v9, v19
	v_med3_f32 v15, v15, s1, v22
	v_med3_f32 v16, v16, s1, v22
	v_mul_f32_e32 v10, v10, v19
	v_mul_f32_e32 v11, v11, v19
	v_med3_f32 v6, v6, s1, v22
	v_med3_f32 v7, v7, s1, v22
	v_mul_f32_e32 v2, v2, v19
	v_mul_f32_e32 v3, v3, v19
	v_cvt_scalef32_pk_fp4_f32 v20, v15, v16, 1.0 op_sel:[0,0,1,0]
	v_med3_f32 v10, v10, s1, v22
	v_med3_f32 v11, v11, s1, v22
	v_cvt_scalef32_pk_fp4_f32 v21, v6, v7, 1.0 op_sel:[0,0,1,0]
	v_med3_f32 v2, v2, s1, v22
	v_med3_f32 v3, v3, s1, v22
	s_cselect_b64 s[8:9], -1, 0
	v_cvt_scalef32_pk_fp4_f32 v20, v10, v11, 1.0 op_sel:[0,0,0,1]
	v_mul_f32_e32 v10, v12, v19
	v_mul_f32_e32 v11, v13, v19
	v_cvt_scalef32_pk_fp4_f32 v21, v2, v3, 1.0 op_sel:[0,0,0,1]
	v_mul_f32_e32 v2, v4, v19
	v_mul_f32_e32 v3, v5, v19
	v_med3_f32 v10, v10, s1, v22
	v_med3_f32 v11, v11, s1, v22
	v_med3_f32 v2, v2, s1, v22
	v_med3_f32 v3, v3, s1, v22
	s_brev_b32 s1, 64
	s_and_b64 s[2:3], s[8:9], exec
	s_cselect_b32 s1, s1, 0x4000000
	s_add_u32 s10, s82, s1
	s_addc_u32 s11, s83, 0
	s_ashr_i32 s1, s0, 31
	s_lshl_b64 s[2:3], s[0:1], 9
	s_add_u32 s2, s10, s2
	v_mov_b32_e32 v14, 0
	v_cvt_scalef32_pk_fp4_f32 v20, v10, v11, 1.0 op_sel:[0,0,1,1]
	v_cvt_scalef32_pk_fp4_f32 v21, v2, v3, 1.0 op_sel:[0,0,1,1]
	s_addc_u32 s3, s11, s3
	global_store_dwordx2 v1, v[20:21], s[2:3]
	s_and_saveexec_b64 s[2:3], s[4:5]
	s_cbranch_execz .LBB0_925
	s_mov_b32 s10, 0x1d00000
	s_and_b64 s[4:5], s[8:9], exec
	s_cselect_b32 s4, s10, 0x1d00004
	s_add_u32 s4, s82, s4
	s_addc_u32 s5, s83, 0
	s_lshl_b64 s[0:1], s[0:1], 3
	s_add_u32 s0, s4, s0
	v_mul_f32_e32 v1, 0x3e124925, v18
	s_addc_u32 s1, s5, s1
	global_store_dword v14, v1, s[0:1]

; #define GAS __attribute__((address_space(1)))
; #define Q4(x) fminf(fmaxf((x) * sc, -6.f), 6.f)
; #define Q4(x) fminf(fmaxf((x) * sc, -6.f), 6.f)
; __device__ __forceinline__ void table_row_to_fp4(const f32x4 (&v)[4], int lane, bool isv, int r, unsigned char* ws) {
;     ...
;     for (int j = 0; j < 4; ++j) m = fmaxf(fmaxf(m, fmaxf(fabsf(v[j].x), fabsf(v[j].y))), fmaxf(fabsf(v[j].z), fabsf(v[j].w)));
; #pragma unroll
;     for (int o = 1; o < 64; o <<= 1) m = fmaxf(m, __shfl_xor(m, o));
;     m = fmaxf(m, 1e-30f);
;     const float sc = 7.f / m;
;     unsigned w0 = 0u, w1 = 0u;
;     ...
;     w0 = __builtin_amdgcn_cvt_scalef32_pk_fp4_f32(w0, Q4(v[0].x), Q4(v[0].y), 1.0f, 0); w0 = __builtin_amdgcn_cvt_scalef32_pk_fp4_f32(w0, Q4(v[0].z), Q4(v[0].w), 1.0f, 1);
;     w0 = __builtin_amdgcn_cvt_scalef32_pk_fp4_f32(w0, Q4(v[1].x), Q4(v[1].y), 1.0f, 2); w0 = __builtin_amdgcn_cvt_scalef32_pk_fp4_f32(w0, Q4(v[1].z), Q4(v[1].w), 1.0f, 3);
;     w1 = __builtin_amdgcn_cvt_scalef32_pk_fp4_f32(w1, Q4(v[2].x), Q4(v[2].y), 1.0f, 0); w1 = __builtin_amdgcn_cvt_scalef32_pk_fp4_f32(w1, Q4(v[2].z), Q4(v[2].w), 1.0f, 1);
;     w1 = __builtin_amdgcn_cvt_scalef32_pk_fp4_f32(w1, Q4(v[3].x), Q4(v[3].y), 1.0f, 2); w1 = __builtin_amdgcn_cvt_scalef32_pk_fp4_f32(w1, Q4(v[3].z), Q4(v[3].w), 1.0f, 3);
;     ...
;     *((GAS v2u*)(ws + (isv ? WS_V8 : WS_U8) + (size_t)r * 512) + lane) = (v2u){w0, w1};
;     if (lane == 0) ((float*)(ws + (isv ? WS_DQV : WS_DQU)))[r] = m * (1.f / 7.f);
; __device__ __forceinline__ void barrier_side_convert(int k, const float* U, const float* V, unsigned char* ws) {
;     ...
;     for (int jj = 0; jj < 3; ++jj) { const int j = wave - 1 + 7 * jj;
;         if (j < RB && g0 + j < glim) { const int g = g0 + j, tb = g >> 14, r = NEXP * (tb >> 1) + (g & (NEXP - 1)); table_row_to_fp4(v[jj], lane, (tb & 1) != 0, r, ws); } }
.LBB0_1031:
	s_andn2_b64 vcc, exec, s[6:7]
	s_cbranch_vccnz .LBB0_1036
	s_add_i32 s15, s15, s14
	s_cmp_gt_i32 s15, 0xffff
	s_cbranch_scc1 .LBB0_1036
	s_waitcnt vmcnt(0)
	v_max_f32_e64 v18, |v15|, |v15|
	v_max_f32_e64 v19, |v14|, |v14|
	v_max_f32_e32 v18, v19, v18
	v_max_f32_e64 v19, |v17|, |v17|
	v_max_f32_e64 v20, |v16|, |v16|
	v_max_f32_e32 v19, v20, v19
	v_max3_f32 v18, v18, 0, v19
	v_max_f32_e64 v19, |v11|, |v11|
	v_max_f32_e64 v20, |v10|, |v10|
	v_max_f32_e32 v19, v20, v19
	v_max_f32_e64 v20, |v13|, |v13|
	v_max_f32_e64 v21, |v12|, |v12|
	v_max_f32_e32 v20, v21, v20
	v_max3_f32 v18, v18, v19, v20
	v_max_f32_e64 v19, |v7|, |v7|
	v_max_f32_e64 v20, |v6|, |v6|
	v_max_f32_e32 v19, v20, v19
	v_max_f32_e64 v20, |v9|, |v9|
	v_max_f32_e64 v21, |v8|, |v8|
	v_max_f32_e32 v20, v21, v20
	v_max3_f32 v18, v18, v19, v20
	v_max_f32_e64 v19, |v3|, |v3|
	v_max_f32_e64 v20, |v2|, |v2|
	v_max_f32_e32 v19, v20, v19
	v_max_f32_e64 v20, |v5|, |v5|
	v_max_f32_e64 v21, |v4|, |v4|
	v_max_f32_e32 v20, v21, v20
	v_max3_f32 v18, v18, v19, v20
	s_ashr_i32 s2, s15, 1
	s_and_b32 s6, s2, 0xffffc000
	s_mov_b32 s2, 0xda24260
	s_mov_b32 s10, 0x40e00000
	s_and_b32 s7, s15, 0x3fff
	s_or_b32 s6, s6, s7
	s_bitcmp0_b32 s15, 14
	s_cselect_b64 s[8:9], -1, 0
	s_brev_b32 s7, 64
	v_lshlrev_b32_e32 v1, 3, v1
	s_nop 1
	v_max_f32_dpp v18, v18, v18 quad_perm:[1,0,3,2] row_mask:0xf bank_mask:0xf
	s_nop 1
	v_max_f32_dpp v18, v18, v18 quad_perm:[2,3,0,1] row_mask:0xf bank_mask:0xf
	s_nop 1
	v_max_f32_dpp v18, v18, v18 row_half_mirror row_mask:0xf bank_mask:0xf
	s_nop 1
	v_max_f32_dpp v18, v18, v18 row_mirror row_mask:0xf bank_mask:0xf
	s_nop 1
	v_readlane_b32 vcc_lo, v18, 0
	v_readlane_b32 vcc_hi, v18, 16
	s_max_u32 vcc_lo, vcc_lo, vcc_hi
	v_readlane_b32 vcc_hi, v18, 32
	s_nop 0
	s_max_u32 vcc_lo, vcc_lo, vcc_hi
	v_readlane_b32 vcc_hi, v18, 48
	s_nop 0
	s_max_u32 vcc_lo, vcc_lo, vcc_hi
	v_mov_b32_e32 v18, vcc_lo
	v_max_f32_e32 v18, s2, v18
	v_div_scale_f32 v19, s[2:3], v18, v18, s10
	v_rcp_f32_e32 v20, v19
	s_mov_b32 s2, 0xc0c00000
	v_fma_f32 v21, -v19, v20, 1.0
	v_fmac_f32_e32 v20, v21, v20
	v_div_scale_f32 v21, vcc, s10, v18, s10
	v_mul_f32_e32 v22, v21, v20
	v_fma_f32 v23, -v19, v22, v21
	v_fmac_f32_e32 v22, v23, v20
	v_fma_f32 v19, -v19, v22, v21
	v_div_fmas_f32 v19, v19, v20, v22
	v_div_fixup_f32 v19, v19, v18, s10
	v_mul_f32_e32 v14, v14, v19
	v_mov_b32_e32 v22, 0x40c00000
	v_med3_f32 v21, v14, s2, v22
	v_mul_f32_e32 v14, v15, v19
	v_med3_f32 v15, v14, s2, v22
	v_mov_b32_e32 v20, 0
	v_mul_f32_e32 v6, v6, v19
	v_mul_f32_e32 v7, v7, v19
	v_cvt_scalef32_pk_fp4_f32 v20, v21, v15, 1.0
	v_med3_f32 v6, v6, s2, v22
	v_med3_f32 v7, v7, s2, v22
	v_mov_b32_e32 v21, 0
	v_mul_f32_e32 v15, v16, v19
	v_mul_f32_e32 v16, v17, v19
	v_cvt_scalef32_pk_fp4_f32 v21, v6, v7, 1.0
	v_mul_f32_e32 v6, v8, v19
	v_mul_f32_e32 v7, v9, v19
	v_med3_f32 v15, v15, s2, v22
	v_med3_f32 v16, v16, s2, v22
	v_mul_f32_e32 v10, v10, v19
	v_mul_f32_e32 v11, v11, v19
	v_med3_f32 v6, v6, s2, v22
	v_med3_f32 v7, v7, s2, v22
	v_mul_f32_e32 v2, v2, v19
	v_mul_f32_e32 v3, v3, v19
	v_cvt_scalef32_pk_fp4_f32 v20, v15, v16, 1.0 op_sel:[0,0,1,0]
	v_med3_f32 v10, v10, s2, v22
	v_med3_f32 v11, v11, s2, v22
	v_cvt_scalef32_pk_fp4_f32 v21, v6, v7, 1.0 op_sel:[0,0,1,0]
	v_med3_f32 v2, v2, s2, v22
	v_med3_f32 v3, v3, s2, v22
	v_cvt_scalef32_pk_fp4_f32 v20, v10, v11, 1.0 op_sel:[0,0,0,1]
	v_mul_f32_e32 v10, v12, v19
	v_mul_f32_e32 v11, v13, v19
	v_cvt_scalef32_pk_fp4_f32 v21, v2, v3, 1.0 op_sel:[0,0,0,1]
	v_mul_f32_e32 v2, v4, v19
	v_mul_f32_e32 v3, v5, v19
	v_med3_f32 v10, v10, s2, v22
	v_med3_f32 v11, v11, s2, v22
	v_med3_f32 v2, v2, s2, v22
	v_med3_f32 v3, v3, s2, v22
	s_and_b64 s[2:3], s[8:9], exec
	s_cselect_b32 s2, s7, 0x4000000
	s_add_u32 s10, s82, s2
	s_addc_u32 s11, s83, 0
	s_ashr_i32 s7, s6, 31
	s_lshl_b64 s[2:3], s[6:7], 9
	s_add_u32 s2, s10, s2
	v_mov_b32_e32 v14, 0
	v_cvt_scalef32_pk_fp4_f32 v20, v10, v11, 1.0 op_sel:[0,0,1,1]
	v_cvt_scalef32_pk_fp4_f32 v21, v2, v3, 1.0 op_sel:[0,0,1,1]
	s_addc_u32 s3, s11, s3
	global_store_dwordx2 v1, v[20:21], s[2:3]
	s_and_saveexec_b64 s[2:3], s[4:5]
	s_cbranch_execz .LBB0_1035
	s_mov_b32 s10, 0x1d00000
	s_and_b64 s[4:5], s[8:9], exec
	s_cselect_b32 s4, s10, 0x1d00004
	s_add_u32 s8, s82, s4
	s_addc_u32 s9, s83, 0
	s_lshl_b64 s[4:5], s[6:7], 3
	s_add_u32 s4, s8, s4
	v_mul_f32_e32 v1, 0x3e124925, v18
	s_addc_u32 s5, s9, s5
	global_store_dword v14, v1, s[4:5]

; #define VLOADA(slot, ereg, lsel) { const int ea_ = __builtin_amdgcn_readlane((ereg), (lsel)), eb_ = __builtin_amdgcn_readlane((ereg), (lsel) + 1); const int el_ = hh ? eb_ : ea_; ring[slot] = *(const GAS v4u*)(V4 + (((unsigned)el_ << 9) + laneoff)); }
; template <bool FINAL>
; __device__ __forceinline__ void phase_gather_v_mfma(const bf16* X, const int* EID, const float* COEF, const unsigned char* V4, const float* g, const float* bb, bf16* Ob, float* Of) {
;     ...
;         unsigned short xs[16];
; #pragma unroll
;         for (int r = 0; r < 16; ++r) xs[r] = X[(size_t)t * D + 32 * ((r & 3) + 8 * (r >> 2) + 4 * hh) + n];
;         float cm = fmaxf(fabsf(c0), fabsf(c1));
; #pragma unroll
;         for (int o = 1; o < 64; o <<= 1) cm = fmaxf(cm, __shfl_xor(cm, o));
;         unsigned ex = (__float_as_uint(cm) >> 23) & 0xffu; ex = ex < 8u ? 8u : ex;
;         const float S = __uint_as_float((261u - ex) << 23), invS = __uint_as_float((ex - 7u) << 23);
;         const unsigned wq = (unsigned)__builtin_amdgcn_cvt_pk_fp8_f32(c0 * S, c1 * S, 0, false);
;         const int rep0 = (int)((wq & 0xffu) * 0x01010101u), rep1 = (int)(((wq >> 8) & 0xffu) * 0x01010101u);
;         f32x16 acc;
; #pragma unroll
;         for (int r = 0; r < 16; ++r) acc[r] = 0.f;
; #pragma unroll
;         for (int J = 0; J < 64; ++J) {
;             const int ra = __builtin_amdgcn_readlane((J >> 5) ? rep1 : rep0, (2 * J) & 63), rb = __builtin_amdgcn_readlane((J >> 5) ? rep1 : rep0, ((2 * J) & 63) + 1);
;             v8i A, B;
;             A[0] = (int)ring[J & 15].x; A[1] = (int)ring[J & 15].y; A[2] = (int)ring[J & 15].z; A[3] = (int)ring[J & 15].w; A[4] = 0; A[5] = 0; A[6] = 0; A[7] = 0;
; #pragma unroll
;             for (int d = 0; d < 4; ++d) { B[d] = ra & (int)mask[d]; B[4 + d] = rb & (int)mask[d]; }
;             acc = __builtin_amdgcn_mfma_scale_f32_32x32x64_f8f6f4(A, B, acc, 4, 0, 0, 0x7f7f7f7f, 0, 0x7f7f7f7f);
;             if (J + 16 < 64) { VLOADA(J & 15, ((J + 16) >> 5) ? e1 : e0, (2 * (J + 16)) & 63) }
;             else { VLOADA(J & 15, ne0, 2 * (J + 16 - 64)) }
;             if ((J & 3) == 3) __builtin_amdgcn_sched_barrier(0);
.LBB0_1040:
	s_waitcnt vmcnt(16)
	v_max_f32_e64 v4, |v3|, |v3|
	v_max_f32_e64 v5, |v2|, |v2|
	v_max_f32_e32 v4, v5, v4
	v_mov_b32_e32 v185, 0
	v_readlane_b32 s0, v102, 32
	v_readlane_b32 s1, v102, 33
	v_readlane_b32 s13, v102, 34
	v_mov_b32_e32 v82, s1
	v_mov_b32_e32 v83, s0
	v_readlane_b32 s20, v102, 35
	v_readlane_b32 s21, v102, 36
	v_readlane_b32 s22, v102, 37
	v_readlane_b32 s23, v102, 38
	v_readlane_b32 s24, v102, 39
	v_mov_b32_e32 v84, s20
	v_mov_b32_e32 v85, s13
	v_mov_b32_e32 v86, s22
	v_mov_b32_e32 v87, s21
	v_mov_b32_e32 v88, s24
	v_lshl_add_u64 v[90:91], s[82:83], 0, v[116:117]
	s_nop 1
	v_max_f32_dpp v4, v4, v4 row_shr:1 row_mask:0xf bank_mask:0xf
	s_nop 1
	v_max_f32_dpp v4, v4, v4 row_shr:2 row_mask:0xf bank_mask:0xf
	s_nop 1
	v_max_f32_dpp v4, v4, v4 row_shr:4 row_mask:0xf bank_mask:0xf
	s_nop 1
	v_max_f32_dpp v4, v4, v4 row_shr:8 row_mask:0xf bank_mask:0xf
	s_nop 1
	v_max_f32_dpp v4, v4, v4 row_bcast:15 row_mask:0xa bank_mask:0xf
	s_nop 1
	v_max_f32_dpp v4, v4, v4 row_bcast:31 row_mask:0xc bank_mask:0xf
	s_nop 0
	v_readlane_b32 s98, v4, 63
	s_nop 1
	v_mov_b32_e32 v4, s98
	v_bfe_u32 v4, v4, 23, 8
	v_max_u32_e32 v4, 8, v4
	v_lshlrev_b32_e32 v92, 23, v4
	v_sub_u32_e32 v4, 0x82800000, v92
	v_mul_f32_e32 v3, v3, v4
	v_mul_f32_e32 v2, v2, v4
	v_cvt_pk_fp8_f32 v185, v2, v3
	v_add_u32_e32 v167, 0xfc800000, v92
	v_and_b32_e32 v2, 0xff, v185
	v_mul_lo_u32 v187, v2, s2
	s_nop 0
	v_readlane_b32 s0, v187, 0
	v_readlane_b32 s1, v187, 1
	s_nop 0
	v_and_b32_e32 v2, s0, v150
	v_and_b32_e32 v6, s1, v150
	v_and_b32_e32 v3, s0, v151
	v_and_b32_e32 v7, s1, v151
	v_and_b32_e32 v4, s0, v152
	v_and_b32_e32 v8, s1, v152
	v_and_b32_e32 v5, s0, v153
	v_and_b32_e32 v9, s1, v153
	v_readlane_b32 s0, v187, 2
	v_readlane_b32 s1, v187, 3
	s_waitcnt vmcnt(15)
	v_mfma_scale_f32_32x32x64_f8f6f4 v[2:17], v[22:25], v[2:9], 0, v160, v160 op_sel_hi:[0,0,0] cbsz:4
	v_mov_b32_e32 v22, s23
	v_cndmask_b32_e64 v23, v82, v83, s[4:5]
	v_cndmask_b32_e64 v24, v84, v85, s[4:5]
	v_cndmask_b32_e64 v25, v86, v87, s[4:5]
	v_cndmask_b32_e64 v93, v88, v22, s[4:5]
	v_and_b32_e32 v82, s0, v150
	v_and_b32_e32 v86, s1, v150
	v_and_b32_e32 v83, s0, v151
	v_and_b32_e32 v87, s1, v151
	v_and_b32_e32 v84, s0, v152
	v_and_b32_e32 v88, s1, v152
	v_and_b32_e32 v85, s0, v153
	v_and_b32_e32 v89, s1, v153
	v_readlane_b32 s0, v187, 4
	v_readlane_b32 s1, v187, 5
	s_waitcnt vmcnt(14)
	v_mfma_scale_f32_32x32x64_f8f6f4 v[2:17], v[18:21], v[82:89], v[2:17], v160, v160 op_sel_hi:[0,0,0] cbsz:4
	v_lshl_or_b32 v18, v23, 9, v1
	v_lshl_or_b32 v19, v24, 9, v1
	v_lshl_or_b32 v86, v25, 9, v1
	global_load_dwordx4 v[106:109], v18, s[10:11]
	global_load_dwordx4 v[82:85], v19, s[10:11]
	v_and_b32_e32 v18, s0, v150
	v_and_b32_e32 v22, s1, v150
	v_and_b32_e32 v19, s0, v151
	v_and_b32_e32 v23, s1, v151
	v_and_b32_e32 v20, s0, v152
	v_and_b32_e32 v24, s1, v152
	v_and_b32_e32 v21, s0, v153
	v_and_b32_e32 v25, s1, v153
	v_readlane_b32 s0, v187, 6
	v_readlane_b32 s1, v187, 7
	s_waitcnt vmcnt(15)
	v_mfma_scale_f32_32x32x64_f8f6f4 v[2:17], v[30:33], v[18:25], v[2:17], v160, v160 op_sel_hi:[0,0,0] cbsz:4
	v_lshl_or_b32 v18, v93, 9, v1
	global_load_dwordx4 v[22:25], v86, s[10:11]
	s_nop 0
	global_load_dwordx4 v[18:21], v18, s[10:11]
	s_nop 0
	global_load_ushort v184, v[90:91], off offset:-1024 nt
	global_load_ushort v183, v[90:91], off offset:-960 nt
	global_load_ushort v182, v[90:91], off offset:-896 nt
	global_load_ushort v181, v[90:91], off offset:-832 nt
	global_load_ushort v180, v[90:91], off offset:-512 nt
	global_load_ushort v179, v[90:91], off offset:-448 nt
	global_load_ushort v178, v[90:91], off offset:-384 nt
	global_load_ushort v177, v[90:91], off offset:-320 nt
	global_load_ushort v175, v[90:91], off nt
	global_load_ushort v174, v[90:91], off offset:64 nt
	global_load_ushort v173, v[90:91], off offset:128 nt
	global_load_ushort v172, v[90:91], off offset:192 nt
	global_load_ushort v171, v[90:91], off offset:512 nt
	global_load_ushort v170, v[90:91], off offset:576 nt
	global_load_ushort v169, v[90:91], off offset:640 nt
	global_load_ushort v168, v[90:91], off offset:704 nt
	v_and_b32_e32 v86, s0, v150
	v_and_b32_e32 v90, s1, v150
	v_and_b32_e32 v87, s0, v151
	v_and_b32_e32 v91, s1, v151
	v_and_b32_e32 v88, s0, v152
	v_and_b32_e32 v92, s1, v152
	v_and_b32_e32 v89, s0, v153
	v_and_b32_e32 v93, s1, v153
	s_waitcnt vmcnt(32)
	s_nop 0
	v_mfma_scale_f32_32x32x64_f8f6f4 v[2:17], v[26:29], v[86:93], v[2:17], v160, v160 op_sel_hi:[0,0,0] cbsz:4
	v_readlane_b32 s0, v187, 8
	v_readlane_b32 s1, v187, 9
	s_nop 0
	v_and_b32_e32 v26, s0, v150
	v_and_b32_e32 v30, s1, v150
	v_and_b32_e32 v27, s0, v151
	v_and_b32_e32 v31, s1, v151
	v_and_b32_e32 v28, s0, v152
	v_and_b32_e32 v32, s1, v152
	v_and_b32_e32 v29, s0, v153
	v_and_b32_e32 v33, s1, v153
	v_readlane_b32 s0, v102, 40
	v_readlane_b32 s1, v102, 41
	s_waitcnt vmcnt(31)
	v_mfma_scale_f32_32x32x64_f8f6f4 v[2:17], v[42:45], v[26:33], v[2:17], v160, v160 op_sel_hi:[0,0,0] cbsz:4
	v_mov_b32_e32 v87, s0
	v_mov_b32_e32 v86, s1
	v_cndmask_b32_e64 v26, v86, v87, s[4:5]
	v_readlane_b32 s0, v187, 10
	v_readlane_b32 s1, v187, 11
	v_lshl_or_b32 v42, v26, 9, v1
	v_and_b32_e32 v26, s0, v150
	v_and_b32_e32 v30, s1, v150
	v_and_b32_e32 v27, s0, v151
	v_and_b32_e32 v31, s1, v151
	v_and_b32_e32 v28, s0, v152
	v_and_b32_e32 v32, s1, v152
	v_and_b32_e32 v29, s0, v153
	v_and_b32_e32 v33, s1, v153
	v_readlane_b32 s0, v102, 42
	v_readlane_b32 s1, v102, 43
	s_waitcnt vmcnt(30)
; #define VLOADA(slot, ereg, lsel) { const int ea_ = __builtin_amdgcn_readlane((ereg), (lsel)), eb_ = __builtin_amdgcn_readlane((ereg), (lsel) + 1); const int el_ = hh ? eb_ : ea_; ring[slot] = *(const GAS v4u*)(V4 + (((unsigned)el_ << 9) + laneoff)); }
; template <bool FINAL>
; __device__ __forceinline__ void phase_gather_v_mfma(const bf16* X, const int* EID, const float* COEF, const unsigned char* V4, const float* g, const float* bb, bf16* Ob, float* Of) {
;     ...
;         for (int J = 0; J < 64; ++J) {
;             const int ra = __builtin_amdgcn_readlane((J >> 5) ? rep1 : rep0, (2 * J) & 63), rb = __builtin_amdgcn_readlane((J >> 5) ? rep1 : rep0, ((2 * J) & 63) + 1);
;             v8i A, B;
;             A[0] = (int)ring[J & 15].x; A[1] = (int)ring[J & 15].y; A[2] = (int)ring[J & 15].z; A[3] = (int)ring[J & 15].w; A[4] = 0; A[5] = 0; A[6] = 0; A[7] = 0;
; #pragma unroll
;             for (int d = 0; d < 4; ++d) { B[d] = ra & (int)mask[d]; B[4 + d] = rb & (int)mask[d]; }
;             acc = __builtin_amdgcn_mfma_scale_f32_32x32x64_f8f6f4(A, B, acc, 4, 0, 0, 0x7f7f7f7f, 0, 0x7f7f7f7f);
;             if (J + 16 < 64) { VLOADA(J & 15, ((J + 16) >> 5) ? e1 : e0, (2 * (J + 16)) & 63) }
;             else { VLOADA(J & 15, ne0, 2 * (J + 16 - 64)) }
;             if ((J & 3) == 3) __builtin_amdgcn_sched_barrier(0);
	v_mfma_scale_f32_32x32x64_f8f6f4 v[2:17], v[34:37], v[26:33], v[2:17], v160, v160 op_sel_hi:[0,0,0] cbsz:4
	v_mov_b32_e32 v26, s0
	v_mov_b32_e32 v43, s1
	v_cndmask_b32_e64 v26, v43, v26, s[4:5]
	v_lshl_or_b32 v26, v26, 9, v1
	v_readlane_b32 s0, v187, 12
	v_readlane_b32 s1, v187, 13
	global_load_dwordx4 v[86:89], v42, s[10:11]
	s_nop 0
	global_load_dwordx4 v[42:45], v26, s[10:11]
	v_and_b32_e32 v26, s0, v150
	v_and_b32_e32 v30, s1, v150
	v_and_b32_e32 v27, s0, v151
	v_and_b32_e32 v31, s1, v151
	v_and_b32_e32 v28, s0, v152
	v_and_b32_e32 v32, s1, v152
	v_and_b32_e32 v29, s0, v153
	v_and_b32_e32 v33, s1, v153
	v_readlane_b32 s0, v102, 44
	v_readlane_b32 s1, v102, 45
	s_waitcnt vmcnt(31)
	v_mfma_scale_f32_32x32x64_f8f6f4 v[2:17], v[54:57], v[26:33], v[2:17], v160, v160 op_sel_hi:[0,0,0] cbsz:4
	v_mov_b32_e32 v27, s0
	v_mov_b32_e32 v26, s1
	v_readlane_b32 s0, v102, 46
	v_readlane_b32 s1, v102, 47
	v_cndmask_b32_e64 v26, v26, v27, s[4:5]
	v_mov_b32_e32 v28, s0
	v_mov_b32_e32 v27, s1
	v_cndmask_b32_e64 v27, v27, v28, s[4:5]
	v_lshl_or_b32 v26, v26, 9, v1
	v_lshl_or_b32 v27, v27, 9, v1
	global_load_dwordx4 v[94:97], v26, s[10:11]
	s_nop 0
	global_load_dwordx4 v[26:29], v27, s[10:11]
	v_readlane_b32 s0, v187, 14
	v_readlane_b32 s1, v187, 15
	s_nop 0
	v_and_b32_e32 v30, s0, v150
	v_and_b32_e32 v34, s1, v150
	v_and_b32_e32 v31, s0, v151
	v_and_b32_e32 v35, s1, v151
	v_and_b32_e32 v32, s0, v152
	v_and_b32_e32 v36, s1, v152
	v_and_b32_e32 v33, s0, v153
	v_and_b32_e32 v37, s1, v153
	s_waitcnt vmcnt(32)
	s_nop 0
	v_mfma_scale_f32_32x32x64_f8f6f4 v[2:17], v[38:41], v[30:37], v[2:17], v160, v160 op_sel_hi:[0,0,0] cbsz:4
	v_readlane_b32 s0, v187, 16
	v_readlane_b32 s1, v187, 17
	s_nop 0
	v_and_b32_e32 v30, s0, v150
	v_and_b32_e32 v34, s1, v150
	v_and_b32_e32 v31, s0, v151
	v_and_b32_e32 v35, s1, v151
	v_and_b32_e32 v32, s0, v152
	v_and_b32_e32 v36, s1, v152
	v_and_b32_e32 v33, s0, v153
	v_and_b32_e32 v37, s1, v153
	v_readlane_b32 s0, v102, 48
	v_readlane_b32 s1, v102, 49
	s_waitcnt vmcnt(31)
	v_mfma_scale_f32_32x32x64_f8f6f4 v[2:17], v[58:61], v[30:37], v[2:17], v160, v160 op_sel_hi:[0,0,0] cbsz:4
	v_mov_b32_e32 v39, s0
	v_mov_b32_e32 v38, s1
	v_cndmask_b32_e64 v30, v38, v39, s[4:5]
	v_readlane_b32 s0, v187, 18
	v_readlane_b32 s1, v187, 19
	v_lshl_or_b32 v38, v30, 9, v1
	v_and_b32_e32 v30, s0, v150
	v_and_b32_e32 v34, s1, v150
	v_and_b32_e32 v31, s0, v151
	v_and_b32_e32 v35, s1, v151
	v_and_b32_e32 v32, s0, v152
	v_and_b32_e32 v36, s1, v152
	v_and_b32_e32 v33, s0, v153
	v_and_b32_e32 v37, s1, v153
	v_readlane_b32 s0, v102, 50
	v_readlane_b32 s1, v102, 51
	s_waitcnt vmcnt(30)
	v_mfma_scale_f32_32x32x64_f8f6f4 v[2:17], v[46:49], v[30:37], v[2:17], v160, v160 op_sel_hi:[0,0,0] cbsz:4
	v_mov_b32_e32 v30, s0
	v_mov_b32_e32 v39, s1
	v_cndmask_b32_e64 v30, v39, v30, s[4:5]
	v_lshl_or_b32 v30, v30, 9, v1
	v_readlane_b32 s0, v187, 20
	v_readlane_b32 s1, v187, 21
	global_load_dwordx4 v[90:93], v38, s[10:11]
	global_load_dwordx4 v[46:49], v30, s[10:11]
	v_and_b32_e32 v30, s0, v150
	v_and_b32_e32 v34, s1, v150
	v_and_b32_e32 v31, s0, v151
	v_and_b32_e32 v35, s1, v151
	v_and_b32_e32 v32, s0, v152
	v_and_b32_e32 v36, s1, v152
	v_and_b32_e32 v33, s0, v153
	v_and_b32_e32 v37, s1, v153
	v_readlane_b32 s0, v102, 52
	v_readlane_b32 s1, v102, 53
	s_waitcnt vmcnt(31)
	v_mfma_scale_f32_32x32x64_f8f6f4 v[2:17], v[70:73], v[30:37], v[2:17], v160, v160 op_sel_hi:[0,0,0] cbsz:4
	v_mov_b32_e32 v31, s0
	v_mov_b32_e32 v30, s1
	v_readlane_b32 s0, v102, 54
	v_readlane_b32 s1, v102, 55
	v_cndmask_b32_e64 v30, v30, v31, s[4:5]
	v_mov_b32_e32 v32, s0
	v_mov_b32_e32 v31, s1
	v_cndmask_b32_e64 v31, v31, v32, s[4:5]
	v_lshl_or_b32 v30, v30, 9, v1
	v_lshl_or_b32 v31, v31, 9, v1
	global_load_dwordx4 v[98:101], v30, s[10:11]
	s_nop 0
	global_load_dwordx4 v[30:33], v31, s[10:11]
	v_readlane_b32 s0, v187, 22
	v_readlane_b32 s1, v187, 23
	s_nop 0
	v_and_b32_e32 v34, s0, v150
	v_and_b32_e32 v38, s1, v150
	v_and_b32_e32 v35, s0, v151
	v_and_b32_e32 v39, s1, v151
	v_and_b32_e32 v36, s0, v152
	v_and_b32_e32 v40, s1, v152
	v_and_b32_e32 v37, s0, v153
	v_and_b32_e32 v41, s1, v153
	s_waitcnt vmcnt(32)
	s_nop 0
	v_mfma_scale_f32_32x32x64_f8f6f4 v[2:17], v[50:53], v[34:41], v[2:17], v160, v160 op_sel_hi:[0,0,0] cbsz:4
	v_readlane_b32 s0, v187, 24
	v_readlane_b32 s1, v187, 25
	s_nop 0
	v_and_b32_e32 v34, s0, v150
	v_and_b32_e32 v38, s1, v150
	v_and_b32_e32 v35, s0, v151
	v_and_b32_e32 v39, s1, v151
	v_and_b32_e32 v36, s0, v152
	v_and_b32_e32 v40, s1, v152
	v_and_b32_e32 v37, s0, v153
	v_and_b32_e32 v41, s1, v153
	v_readlane_b32 s0, v102, 56
	v_readlane_b32 s1, v102, 57
	s_waitcnt vmcnt(31)
	v_mfma_scale_f32_32x32x64_f8f6f4 v[2:17], v[74:77], v[34:41], v[2:17], v160, v160 op_sel_hi:[0,0,0] cbsz:4
	v_mov_b32_e32 v51, s0
	v_mov_b32_e32 v50, s1
	v_cndmask_b32_e64 v34, v50, v51, s[4:5]
	v_readlane_b32 s0, v187, 26
	v_readlane_b32 s1, v187, 27
	v_lshl_or_b32 v50, v34, 9, v1
	v_and_b32_e32 v34, s0, v150
	v_and_b32_e32 v38, s1, v150
	v_and_b32_e32 v35, s0, v151
	v_and_b32_e32 v39, s1, v151
	v_and_b32_e32 v36, s0, v152
	v_and_b32_e32 v40, s1, v152
	v_and_b32_e32 v37, s0, v153
	v_and_b32_e32 v41, s1, v153
	v_readlane_b32 s0, v102, 58
	v_readlane_b32 s1, v102, 59
	s_waitcnt vmcnt(30)
	v_mfma_scale_f32_32x32x64_f8f6f4 v[2:17], v[62:65], v[34:41], v[2:17], v160, v160 op_sel_hi:[0,0,0] cbsz:4
	v_mov_b32_e32 v34, s0
	v_mov_b32_e32 v51, s1
	v_cndmask_b32_e64 v34, v51, v34, s[4:5]
	v_lshl_or_b32 v34, v34, 9, v1
	v_readlane_b32 s0, v187, 28
	v_readlane_b32 s1, v187, 29
	global_load_dwordx4 v[70:73], v50, s[10:11]
	s_nop 0
	global_load_dwordx4 v[50:53], v34, s[10:11]
	v_and_b32_e32 v34, s0, v150
	v_and_b32_e32 v38, s1, v150
	v_and_b32_e32 v35, s0, v151
	v_and_b32_e32 v39, s1, v151
	v_and_b32_e32 v36, s0, v152
	v_and_b32_e32 v40, s1, v152
	v_and_b32_e32 v37, s0, v153
	v_and_b32_e32 v41, s1, v153
	v_readlane_b32 s0, v102, 60
	v_readlane_b32 s1, v102, 61
	s_waitcnt vmcnt(31)
; #define VLOADA(slot, ereg, lsel) { const int ea_ = __builtin_amdgcn_readlane((ereg), (lsel)), eb_ = __builtin_amdgcn_readlane((ereg), (lsel) + 1); const int el_ = hh ? eb_ : ea_; ring[slot] = *(const GAS v4u*)(V4 + (((unsigned)el_ << 9) + laneoff)); }
; template <bool FINAL>
; __device__ __forceinline__ void phase_gather_v_mfma(const bf16* X, const int* EID, const float* COEF, const unsigned char* V4, const float* g, const float* bb, bf16* Ob, float* Of) {
;     ...
;         for (int J = 0; J < 64; ++J) {
;             const int ra = __builtin_amdgcn_readlane((J >> 5) ? rep1 : rep0, (2 * J) & 63), rb = __builtin_amdgcn_readlane((J >> 5) ? rep1 : rep0, ((2 * J) & 63) + 1);
;             v8i A, B;
;             A[0] = (int)ring[J & 15].x; A[1] = (int)ring[J & 15].y; A[2] = (int)ring[J & 15].z; A[3] = (int)ring[J & 15].w; A[4] = 0; A[5] = 0; A[6] = 0; A[7] = 0;
; #pragma unroll
;             for (int d = 0; d < 4; ++d) { B[d] = ra & (int)mask[d]; B[4 + d] = rb & (int)mask[d]; }
;             acc = __builtin_amdgcn_mfma_scale_f32_32x32x64_f8f6f4(A, B, acc, 4, 0, 0, 0x7f7f7f7f, 0, 0x7f7f7f7f);
;             if (J + 16 < 64) { VLOADA(J & 15, ((J + 16) >> 5) ? e1 : e0, (2 * (J + 16)) & 63) }
;             else { VLOADA(J & 15, ne0, 2 * (J + 16 - 64)) }
;             if ((J & 3) == 3) __builtin_amdgcn_sched_barrier(0);
	v_mfma_scale_f32_32x32x64_f8f6f4 v[2:17], v[78:81], v[34:41], v[2:17], v160, v160 op_sel_hi:[0,0,0] cbsz:4
	v_mov_b32_e32 v35, s0
	v_mov_b32_e32 v34, s1
	v_readlane_b32 s0, v102, 62
	v_readlane_b32 s1, v102, 63
	v_cndmask_b32_e64 v34, v34, v35, s[4:5]
	v_mov_b32_e32 v36, s0
	v_mov_b32_e32 v35, s1
	v_cndmask_b32_e64 v35, v35, v36, s[4:5]
	v_lshl_or_b32 v34, v34, 9, v1
	v_lshl_or_b32 v35, v35, 9, v1
	global_load_dwordx4 v[102:105], v34, s[10:11]
	s_nop 0
	global_load_dwordx4 v[34:37], v35, s[10:11]
	v_readlane_b32 s0, v187, 30
	v_readlane_b32 s1, v187, 31
	s_nop 0
	v_and_b32_e32 v54, s0, v150
	v_and_b32_e32 v58, s1, v150
	v_and_b32_e32 v55, s0, v151
	v_and_b32_e32 v59, s1, v151
	v_and_b32_e32 v56, s0, v152
	v_and_b32_e32 v60, s1, v152
	v_and_b32_e32 v57, s0, v153
	v_and_b32_e32 v61, s1, v153
	s_waitcnt vmcnt(32)
	s_nop 0
	v_mfma_scale_f32_32x32x64_f8f6f4 v[2:17], v[66:69], v[54:61], v[2:17], v160, v160 op_sel_hi:[0,0,0] cbsz:4
	v_readlane_b32 s0, v187, 32
	v_readlane_b32 s1, v187, 33
	s_nop 0
	v_and_b32_e32 v54, s0, v150
	v_and_b32_e32 v58, s1, v150
	v_and_b32_e32 v55, s0, v151
	v_and_b32_e32 v59, s1, v151
	v_and_b32_e32 v56, s0, v152
	v_and_b32_e32 v60, s1, v152
	v_and_b32_e32 v57, s0, v153
	v_and_b32_e32 v61, s1, v153
	v_readlane_b32 s0, v176, 0
	v_readlane_b32 s1, v176, 1
	s_waitcnt vmcnt(31)
	v_mfma_scale_f32_32x32x64_f8f6f4 v[2:17], v[106:109], v[54:61], v[2:17], v160, v160 op_sel_hi:[0,0,0] cbsz:4
	v_mov_b32_e32 v39, s0
	v_mov_b32_e32 v38, s1
	v_readlane_b32 s0, v187, 34
	v_readlane_b32 s1, v187, 35
	v_cndmask_b32_e64 v38, v38, v39, s[4:5]
	v_and_b32_e32 v54, s0, v150
	v_and_b32_e32 v58, s1, v150
	v_and_b32_e32 v55, s0, v151
	v_and_b32_e32 v59, s1, v151
	v_and_b32_e32 v56, s0, v152
	v_and_b32_e32 v60, s1, v152
	v_and_b32_e32 v57, s0, v153
	v_and_b32_e32 v61, s1, v153
	v_readlane_b32 s0, v176, 2
	v_readlane_b32 s1, v176, 3
	s_waitcnt vmcnt(30)
	v_mfma_scale_f32_32x32x64_f8f6f4 v[2:17], v[82:85], v[54:61], v[2:17], v160, v160 op_sel_hi:[0,0,0] cbsz:4
	v_mov_b32_e32 v40, s0
	v_mov_b32_e32 v39, s1
	v_readlane_b32 s0, v187, 36
	v_readlane_b32 s1, v187, 37
	v_lshl_or_b32 v38, v38, 9, v1
	v_and_b32_e32 v58, s0, v150
	v_and_b32_e32 v62, s1, v150
	v_and_b32_e32 v59, s0, v151
	v_and_b32_e32 v63, s1, v151
	v_and_b32_e32 v60, s0, v152
	v_and_b32_e32 v64, s1, v152
	v_and_b32_e32 v61, s0, v153
	v_and_b32_e32 v65, s1, v153
	v_readlane_b32 s0, v176, 4
	v_readlane_b32 s1, v176, 5
	s_waitcnt vmcnt(29)
	v_mfma_scale_f32_32x32x64_f8f6f4 v[2:17], v[22:25], v[58:65], v[2:17], v160, v160 op_sel_hi:[0,0,0] cbsz:4
	v_mov_b32_e32 v23, s0
	v_mov_b32_e32 v22, s1
	v_readlane_b32 s0, v176, 6
	v_readlane_b32 s1, v176, 7
	v_cndmask_b32_e64 v22, v22, v23, s[4:5]
	v_mov_b32_e32 v24, s0
	v_mov_b32_e32 v23, s1
	v_cndmask_b32_e64 v23, v23, v24, s[4:5]
	v_cndmask_b32_e64 v39, v39, v40, s[4:5]
	v_lshl_or_b32 v22, v22, 9, v1
	v_lshl_or_b32 v23, v23, 9, v1
	v_lshl_or_b32 v39, v39, 9, v1
	global_load_dwordx4 v[74:77], v38, s[10:11]
	global_load_dwordx4 v[54:57], v39, s[10:11]
	global_load_dwordx4 v[78:81], v22, s[10:11]
	s_nop 0
	global_load_dwordx4 v[22:25], v23, s[10:11]
	v_readlane_b32 s0, v187, 38
	v_readlane_b32 s1, v187, 39
	s_nop 0
	v_and_b32_e32 v58, s0, v150
	v_and_b32_e32 v62, s1, v150
	v_and_b32_e32 v59, s0, v151
	v_and_b32_e32 v63, s1, v151
	v_and_b32_e32 v60, s0, v152
	v_and_b32_e32 v64, s1, v152
	v_and_b32_e32 v61, s0, v153
	v_and_b32_e32 v65, s1, v153
	s_waitcnt vmcnt(32)
	s_nop 0
	v_mfma_scale_f32_32x32x64_f8f6f4 v[2:17], v[18:21], v[58:65], v[2:17], v160, v160 op_sel_hi:[0,0,0] cbsz:4
	v_readlane_b32 s0, v187, 40
	v_readlane_b32 s1, v187, 41
	s_nop 0
	v_and_b32_e32 v58, s0, v150
	v_and_b32_e32 v62, s1, v150
	v_and_b32_e32 v59, s0, v151
	v_and_b32_e32 v63, s1, v151
	v_and_b32_e32 v60, s0, v152
	v_and_b32_e32 v64, s1, v152
	v_and_b32_e32 v61, s0, v153
	v_and_b32_e32 v65, s1, v153
	v_readlane_b32 s0, v176, 8
	v_readlane_b32 s1, v176, 9
	s_waitcnt vmcnt(15)
	v_mfma_scale_f32_32x32x64_f8f6f4 v[2:17], v[86:89], v[58:65], v[2:17], v160, v160 op_sel_hi:[0,0,0] cbsz:4
	v_mov_b32_e32 v19, s0
	v_mov_b32_e32 v18, s1
	v_readlane_b32 s0, v187, 42
	v_readlane_b32 s1, v187, 43
	v_cndmask_b32_e64 v18, v18, v19, s[4:5]
	v_and_b32_e32 v58, s0, v150
	v_and_b32_e32 v62, s1, v150
	v_and_b32_e32 v59, s0, v151
	v_and_b32_e32 v63, s1, v151
	v_and_b32_e32 v60, s0, v152
	v_and_b32_e32 v64, s1, v152
	v_and_b32_e32 v61, s0, v153
	v_and_b32_e32 v65, s1, v153
	v_readlane_b32 s0, v176, 10
	v_readlane_b32 s1, v176, 11
	v_lshl_or_b32 v18, v18, 9, v1
	v_mov_b32_e32 v20, s0
	v_mov_b32_e32 v19, s1
	v_cndmask_b32_e64 v19, v19, v20, s[4:5]
	v_readlane_b32 s0, v187, 44
	v_readlane_b32 s1, v187, 45
	s_waitcnt vmcnt(14)
	v_mfma_scale_f32_32x32x64_f8f6f4 v[2:17], v[42:45], v[58:65], v[2:17], v160, v160 op_sel_hi:[0,0,0] cbsz:4
	v_lshl_or_b32 v19, v19, 9, v1
	v_and_b32_e32 v62, s0, v150
	v_and_b32_e32 v66, s1, v150
	v_and_b32_e32 v63, s0, v151
	v_and_b32_e32 v67, s1, v151
	v_and_b32_e32 v64, s0, v152
	v_and_b32_e32 v68, s1, v152
	v_and_b32_e32 v65, s0, v153
	v_and_b32_e32 v69, s1, v153
	v_readlane_b32 s0, v176, 12
	v_readlane_b32 s1, v176, 13
	global_load_dwordx4 v[58:61], v18, s[10:11]
	global_load_dwordx4 v[38:41], v19, s[10:11]
	v_mov_b32_e32 v18, s1
	v_mov_b32_e32 v19, s0
	v_readlane_b32 s0, v176, 14
	v_readlane_b32 s1, v176, 15
	v_cndmask_b32_e64 v18, v18, v19, s[4:5]
	v_mov_b32_e32 v20, s0
	v_mov_b32_e32 v19, s1
	v_cndmask_b32_e64 v19, v19, v20, s[4:5]
	v_lshl_or_b32 v18, v18, 9, v1
	v_lshl_or_b32 v19, v19, 9, v1
	global_load_dwordx4 v[82:85], v18, s[10:11]
	s_nop 0
	global_load_dwordx4 v[18:21], v19, s[10:11]
	s_waitcnt vmcnt(17)
; #define VLOADA(slot, ereg, lsel) { const int ea_ = __builtin_amdgcn_readlane((ereg), (lsel)), eb_ = __builtin_amdgcn_readlane((ereg), (lsel) + 1); const int el_ = hh ? eb_ : ea_; ring[slot] = *(const GAS v4u*)(V4 + (((unsigned)el_ << 9) + laneoff)); }
; template <bool FINAL>
; __device__ __forceinline__ void phase_gather_v_mfma(const bf16* X, const int* EID, const float* COEF, const unsigned char* V4, const float* g, const float* bb, bf16* Ob, float* Of) {
;     ...
;         for (int J = 0; J < 64; ++J) {
;             const int ra = __builtin_amdgcn_readlane((J >> 5) ? rep1 : rep0, (2 * J) & 63), rb = __builtin_amdgcn_readlane((J >> 5) ? rep1 : rep0, ((2 * J) & 63) + 1);
;             v8i A, B;
;             A[0] = (int)ring[J & 15].x; A[1] = (int)ring[J & 15].y; A[2] = (int)ring[J & 15].z; A[3] = (int)ring[J & 15].w; A[4] = 0; A[5] = 0; A[6] = 0; A[7] = 0;
; #pragma unroll
;             for (int d = 0; d < 4; ++d) { B[d] = ra & (int)mask[d]; B[4 + d] = rb & (int)mask[d]; }
;             acc = __builtin_amdgcn_mfma_scale_f32_32x32x64_f8f6f4(A, B, acc, 4, 0, 0, 0x7f7f7f7f, 0, 0x7f7f7f7f);
;             if (J + 16 < 64) { VLOADA(J & 15, ((J + 16) >> 5) ? e1 : e0, (2 * (J + 16)) & 63) }
;             else { VLOADA(J & 15, ne0, 2 * (J + 16 - 64)) }
;             if ((J & 3) == 3) __builtin_amdgcn_sched_barrier(0);
	v_mfma_scale_f32_32x32x64_f8f6f4 v[2:17], v[94:97], v[62:69], v[2:17], v160, v160 op_sel_hi:[0,0,0] cbsz:4
	v_readlane_b32 s0, v187, 46
	v_readlane_b32 s1, v187, 47
	s_nop 0
	v_and_b32_e32 v62, s0, v150
	v_and_b32_e32 v66, s1, v150
	v_and_b32_e32 v63, s0, v151
	v_and_b32_e32 v67, s1, v151
	v_and_b32_e32 v64, s0, v152
	v_and_b32_e32 v68, s1, v152
	v_and_b32_e32 v65, s0, v153
	v_and_b32_e32 v69, s1, v153
	s_waitcnt vmcnt(16)
	s_nop 0
	v_mfma_scale_f32_32x32x64_f8f6f4 v[2:17], v[26:29], v[62:69], v[2:17], v160, v160 op_sel_hi:[0,0,0] cbsz:4
	v_readlane_b32 s0, v187, 48
	v_readlane_b32 s1, v187, 49
	s_nop 0
	v_and_b32_e32 v62, s0, v150
	v_and_b32_e32 v66, s1, v150
	v_and_b32_e32 v63, s0, v151
	v_and_b32_e32 v67, s1, v151
	v_and_b32_e32 v64, s0, v152
	v_and_b32_e32 v68, s1, v152
	v_and_b32_e32 v65, s0, v153
	v_and_b32_e32 v69, s1, v153
	v_readlane_b32 s0, v176, 16
	v_readlane_b32 s1, v176, 17
	s_waitcnt vmcnt(15)
	v_mfma_scale_f32_32x32x64_f8f6f4 v[2:17], v[90:93], v[62:69], v[2:17], v160, v160 op_sel_hi:[0,0,0] cbsz:4
	v_mov_b32_e32 v27, s0
	v_mov_b32_e32 v26, s1
	v_readlane_b32 s0, v187, 50
	v_readlane_b32 s1, v187, 51
	v_cndmask_b32_e64 v26, v26, v27, s[4:5]
	v_and_b32_e32 v62, s0, v150
	v_and_b32_e32 v66, s1, v150
	v_and_b32_e32 v63, s0, v151
	v_and_b32_e32 v67, s1, v151
	v_and_b32_e32 v64, s0, v152
	v_and_b32_e32 v68, s1, v152
	v_and_b32_e32 v65, s0, v153
	v_and_b32_e32 v69, s1, v153
	v_readlane_b32 s0, v176, 18
	v_readlane_b32 s1, v176, 19
	s_waitcnt vmcnt(14)
	v_mfma_scale_f32_32x32x64_f8f6f4 v[2:17], v[46:49], v[62:69], v[2:17], v160, v160 op_sel_hi:[0,0,0] cbsz:4
	v_mov_b32_e32 v28, s0
	v_mov_b32_e32 v27, s1
	v_cndmask_b32_e64 v27, v27, v28, s[4:5]
	v_readlane_b32 s0, v187, 52
	v_readlane_b32 s1, v187, 53
	v_lshl_or_b32 v26, v26, 9, v1
	v_lshl_or_b32 v27, v27, 9, v1
	v_and_b32_e32 v86, s0, v150
	v_and_b32_e32 v90, s1, v150
	v_and_b32_e32 v87, s0, v151
	v_and_b32_e32 v91, s1, v151
	v_and_b32_e32 v88, s0, v152
	v_and_b32_e32 v92, s1, v152
	v_and_b32_e32 v89, s0, v153
	v_and_b32_e32 v93, s1, v153
	v_readlane_b32 s0, v176, 20
	v_readlane_b32 s1, v176, 21
	global_load_dwordx4 v[62:65], v26, s[10:11]
	global_load_dwordx4 v[42:45], v27, s[10:11]
	v_mov_b32_e32 v26, s1
	v_mov_b32_e32 v27, s0
	v_readlane_b32 s0, v176, 22
	v_readlane_b32 s1, v176, 23
	v_cndmask_b32_e64 v26, v26, v27, s[4:5]
	v_mov_b32_e32 v28, s0
	v_mov_b32_e32 v27, s1
	v_cndmask_b32_e64 v27, v27, v28, s[4:5]
	v_lshl_or_b32 v26, v26, 9, v1
	v_lshl_or_b32 v27, v27, 9, v1
	s_waitcnt vmcnt(15)
	v_mfma_scale_f32_32x32x64_f8f6f4 v[2:17], v[98:101], v[86:93], v[2:17], v160, v160 op_sel_hi:[0,0,0] cbsz:4
	global_load_dwordx4 v[86:89], v26, s[10:11]
	s_nop 0
	global_load_dwordx4 v[26:29], v27, s[10:11]
	v_readlane_b32 s0, v187, 54
	v_readlane_b32 s1, v187, 55
	s_nop 0
	v_and_b32_e32 v90, s0, v150
	v_and_b32_e32 v94, s1, v150
	v_and_b32_e32 v91, s0, v151
	v_and_b32_e32 v95, s1, v151
	v_and_b32_e32 v92, s0, v152
	v_and_b32_e32 v96, s1, v152
	v_and_b32_e32 v93, s0, v153
	v_and_b32_e32 v97, s1, v153
	s_waitcnt vmcnt(16)
	s_nop 0
	v_mfma_scale_f32_32x32x64_f8f6f4 v[2:17], v[30:33], v[90:97], v[2:17], v160, v160 op_sel_hi:[0,0,0] cbsz:4
	v_readlane_b32 s0, v187, 56
	v_readlane_b32 s1, v187, 57
	s_nop 0
	v_and_b32_e32 v90, s0, v150
	v_and_b32_e32 v94, s1, v150
	v_and_b32_e32 v91, s0, v151
	v_and_b32_e32 v95, s1, v151
	v_and_b32_e32 v92, s0, v152
	v_and_b32_e32 v96, s1, v152
	v_and_b32_e32 v93, s0, v153
	v_and_b32_e32 v97, s1, v153
	v_readlane_b32 s0, v176, 24
	v_readlane_b32 s1, v176, 25
	s_waitcnt vmcnt(15)
	v_mfma_scale_f32_32x32x64_f8f6f4 v[2:17], v[70:73], v[90:97], v[2:17], v160, v160 op_sel_hi:[0,0,0] cbsz:4
	v_mov_b32_e32 v31, s0
	v_mov_b32_e32 v30, s1
	v_readlane_b32 s0, v187, 58
	v_readlane_b32 s1, v187, 59
	v_cndmask_b32_e64 v30, v30, v31, s[4:5]
	v_and_b32_e32 v66, s0, v150
	v_and_b32_e32 v70, s1, v150
	v_and_b32_e32 v67, s0, v151
	v_and_b32_e32 v71, s1, v151
	v_and_b32_e32 v68, s0, v152
	v_and_b32_e32 v72, s1, v152
	v_and_b32_e32 v69, s0, v153
	v_and_b32_e32 v73, s1, v153
	v_readlane_b32 s0, v176, 26
	v_readlane_b32 s1, v176, 27
	s_waitcnt vmcnt(14)
	v_mfma_scale_f32_32x32x64_f8f6f4 v[2:17], v[50:53], v[66:73], v[2:17], v160, v160 op_sel_hi:[0,0,0] cbsz:4
	v_mov_b32_e32 v32, s0
	v_mov_b32_e32 v31, s1
	v_cndmask_b32_e64 v31, v31, v32, s[4:5]
	v_readlane_b32 s0, v187, 60
	v_readlane_b32 s1, v187, 61
	v_lshl_or_b32 v30, v30, 9, v1
	v_lshl_or_b32 v31, v31, 9, v1
	v_and_b32_e32 v90, s0, v150
	v_and_b32_e32 v94, s1, v150
	v_and_b32_e32 v91, s0, v151
	v_and_b32_e32 v95, s1, v151
	v_and_b32_e32 v92, s0, v152
	v_and_b32_e32 v96, s1, v152
	v_and_b32_e32 v93, s0, v153
	v_and_b32_e32 v97, s1, v153
	v_readlane_b32 s0, v176, 28
	v_readlane_b32 s1, v176, 29
	global_load_dwordx4 v[66:69], v30, s[10:11]
	global_load_dwordx4 v[50:53], v31, s[10:11]
	v_mov_b32_e32 v30, s1
	v_mov_b32_e32 v31, s0
	v_readlane_b32 s0, v176, 30
	v_readlane_b32 s1, v176, 31
	v_cndmask_b32_e64 v30, v30, v31, s[4:5]
	v_mov_b32_e32 v32, s0
	v_mov_b32_e32 v31, s1
	v_cndmask_b32_e64 v31, v31, v32, s[4:5]
	v_lshl_or_b32 v30, v30, 9, v1
	v_lshl_or_b32 v31, v31, 9, v1
	s_waitcnt vmcnt(15)
	v_mfma_scale_f32_32x32x64_f8f6f4 v[2:17], v[102:105], v[90:97], v[2:17], v160, v160 op_sel_hi:[0,0,0] cbsz:4
	global_load_dwordx4 v[90:93], v30, s[10:11]
	s_nop 0
	global_load_dwordx4 v[30:33], v31, s[10:11]
	v_readlane_b32 s0, v187, 62
	v_readlane_b32 s1, v187, 63
	s_nop 0
	v_and_b32_e32 v94, s0, v150
	v_and_b32_e32 v98, s1, v150
	v_and_b32_e32 v95, s0, v151
	v_and_b32_e32 v99, s1, v151
	v_and_b32_e32 v96, s0, v152
	v_and_b32_e32 v100, s1, v152
	v_and_b32_e32 v97, s0, v153
	v_and_b32_e32 v101, s1, v153
	s_waitcnt vmcnt(16)
; #define VLOADA(slot, ereg, lsel) { const int ea_ = __builtin_amdgcn_readlane((ereg), (lsel)), eb_ = __builtin_amdgcn_readlane((ereg), (lsel) + 1); const int el_ = hh ? eb_ : ea_; ring[slot] = *(const GAS v4u*)(V4 + (((unsigned)el_ << 9) + laneoff)); }
; template <bool FINAL>
; __device__ __forceinline__ void phase_gather_v_mfma(const bf16* X, const int* EID, const float* COEF, const unsigned char* V4, const float* g, const float* bb, bf16* Ob, float* Of) {
;     ...
;         for (int J = 0; J < 64; ++J) {
;             const int ra = __builtin_amdgcn_readlane((J >> 5) ? rep1 : rep0, (2 * J) & 63), rb = __builtin_amdgcn_readlane((J >> 5) ? rep1 : rep0, ((2 * J) & 63) + 1);
;             v8i A, B;
;             A[0] = (int)ring[J & 15].x; A[1] = (int)ring[J & 15].y; A[2] = (int)ring[J & 15].z; A[3] = (int)ring[J & 15].w; A[4] = 0; A[5] = 0; A[6] = 0; A[7] = 0;
; #pragma unroll
;             for (int d = 0; d < 4; ++d) { B[d] = ra & (int)mask[d]; B[4 + d] = rb & (int)mask[d]; }
;             acc = __builtin_amdgcn_mfma_scale_f32_32x32x64_f8f6f4(A, B, acc, 4, 0, 0, 0x7f7f7f7f, 0, 0x7f7f7f7f);
;             if (J + 16 < 64) { VLOADA(J & 15, ((J + 16) >> 5) ? e1 : e0, (2 * (J + 16)) & 63) }
;             else { VLOADA(J & 15, ne0, 2 * (J + 16 - 64)) }
;             if ((J & 3) == 3) __builtin_amdgcn_sched_barrier(0);
	s_nop 0
	v_mfma_scale_f32_32x32x64_f8f6f4 v[2:17], v[34:37], v[94:101], v[2:17], v160, v160 op_sel_hi:[0,0,0] cbsz:4
	v_bfe_u32 v34, v185, 8, 8
	v_mul_lo_u32 v106, v34, s2
	s_nop 0
	v_readlane_b32 s0, v106, 0
	v_readlane_b32 s1, v106, 1
	s_nop 0
	v_and_b32_e32 v94, s0, v150
	v_and_b32_e32 v98, s1, v150
	v_and_b32_e32 v95, s0, v151
	v_and_b32_e32 v99, s1, v151
	v_and_b32_e32 v96, s0, v152
	v_and_b32_e32 v100, s1, v152
	v_and_b32_e32 v97, s0, v153
	v_and_b32_e32 v101, s1, v153
	v_readlane_b32 s0, v176, 32
	v_readlane_b32 s1, v176, 33
	s_waitcnt vmcnt(15)
	v_mfma_scale_f32_32x32x64_f8f6f4 v[2:17], v[74:77], v[94:101], v[2:17], v160, v160 op_sel_hi:[0,0,0] cbsz:4
	v_mov_b32_e32 v35, s0
	v_mov_b32_e32 v34, s1
	v_readlane_b32 s0, v106, 2
	v_readlane_b32 s1, v106, 3
	v_cndmask_b32_e64 v34, v34, v35, s[4:5]
	v_and_b32_e32 v70, s0, v150
	v_and_b32_e32 v74, s1, v150
	v_and_b32_e32 v71, s0, v151
	v_and_b32_e32 v75, s1, v151
	v_and_b32_e32 v72, s0, v152
	v_and_b32_e32 v76, s1, v152
	v_and_b32_e32 v73, s0, v153
	v_and_b32_e32 v77, s1, v153
	v_readlane_b32 s0, v176, 34
	v_readlane_b32 s1, v176, 35
	s_waitcnt vmcnt(14)
	v_mfma_scale_f32_32x32x64_f8f6f4 v[2:17], v[54:57], v[70:77], v[2:17], v160, v160 op_sel_hi:[0,0,0] cbsz:4
	v_mov_b32_e32 v36, s0
	v_mov_b32_e32 v35, s1
	v_cndmask_b32_e64 v35, v35, v36, s[4:5]
	v_readlane_b32 s0, v106, 4
	v_readlane_b32 s1, v106, 5
	v_lshl_or_b32 v34, v34, 9, v1
	v_lshl_or_b32 v35, v35, 9, v1
	v_and_b32_e32 v94, s0, v150
	v_and_b32_e32 v98, s1, v150
	v_and_b32_e32 v95, s0, v151
	v_and_b32_e32 v99, s1, v151
	v_and_b32_e32 v96, s0, v152
	v_and_b32_e32 v100, s1, v152
	v_and_b32_e32 v97, s0, v153
	v_and_b32_e32 v101, s1, v153
	v_readlane_b32 s0, v176, 36
	v_readlane_b32 s1, v176, 37
	global_load_dwordx4 v[70:73], v34, s[10:11]
	global_load_dwordx4 v[54:57], v35, s[10:11]
	v_mov_b32_e32 v34, s1
	v_mov_b32_e32 v35, s0
	v_readlane_b32 s0, v176, 38
	v_readlane_b32 s1, v176, 39
	v_cndmask_b32_e64 v34, v34, v35, s[4:5]
	v_mov_b32_e32 v36, s0
	v_mov_b32_e32 v35, s1
	v_cndmask_b32_e64 v35, v35, v36, s[4:5]
	v_lshl_or_b32 v34, v34, 9, v1
	v_lshl_or_b32 v35, v35, 9, v1
	s_waitcnt vmcnt(15)
	v_mfma_scale_f32_32x32x64_f8f6f4 v[2:17], v[78:81], v[94:101], v[2:17], v160, v160 op_sel_hi:[0,0,0] cbsz:4
	global_load_dwordx4 v[94:97], v34, s[10:11]
	s_nop 0
	global_load_dwordx4 v[34:37], v35, s[10:11]
	v_readlane_b32 s0, v106, 6
	v_readlane_b32 s1, v106, 7
	s_nop 0
	v_and_b32_e32 v74, s0, v150
	v_and_b32_e32 v78, s1, v150
	v_and_b32_e32 v75, s0, v151
	v_and_b32_e32 v79, s1, v151
	v_and_b32_e32 v76, s0, v152
	v_and_b32_e32 v80, s1, v152
	v_and_b32_e32 v77, s0, v153
	v_and_b32_e32 v81, s1, v153
	s_waitcnt vmcnt(16)
	s_nop 0
	v_mfma_scale_f32_32x32x64_f8f6f4 v[2:17], v[22:25], v[74:81], v[2:17], v160, v160 op_sel_hi:[0,0,0] cbsz:4
	v_readlane_b32 s0, v106, 8
	v_readlane_b32 s1, v106, 9
	s_nop 0
	v_and_b32_e32 v74, s0, v150
	v_and_b32_e32 v78, s1, v150
	v_and_b32_e32 v75, s0, v151
	v_and_b32_e32 v79, s1, v151
	v_and_b32_e32 v76, s0, v152
	v_and_b32_e32 v80, s1, v152
	v_and_b32_e32 v77, s0, v153
	v_and_b32_e32 v81, s1, v153
	v_readlane_b32 s0, v176, 40
	v_readlane_b32 s1, v176, 41
	s_waitcnt vmcnt(15)
	v_mfma_scale_f32_32x32x64_f8f6f4 v[2:17], v[58:61], v[74:81], v[2:17], v160, v160 op_sel_hi:[0,0,0] cbsz:4
	v_mov_b32_e32 v23, s0
	v_mov_b32_e32 v22, s1
	v_readlane_b32 s0, v106, 10
	v_readlane_b32 s1, v106, 11
	v_cndmask_b32_e64 v22, v22, v23, s[4:5]
	v_and_b32_e32 v74, s0, v150
	v_and_b32_e32 v78, s1, v150
	v_and_b32_e32 v75, s0, v151
	v_and_b32_e32 v79, s1, v151
	v_and_b32_e32 v76, s0, v152
	v_and_b32_e32 v80, s1, v152
	v_and_b32_e32 v77, s0, v153
	v_and_b32_e32 v81, s1, v153
	v_readlane_b32 s0, v176, 42
	v_readlane_b32 s1, v176, 43
	s_waitcnt vmcnt(14)
	v_mfma_scale_f32_32x32x64_f8f6f4 v[2:17], v[38:41], v[74:81], v[2:17], v160, v160 op_sel_hi:[0,0,0] cbsz:4
	v_mov_b32_e32 v24, s0
	v_mov_b32_e32 v23, s1
	v_cndmask_b32_e64 v23, v23, v24, s[4:5]
	v_readlane_b32 s0, v106, 12
	v_readlane_b32 s1, v106, 13
	v_lshl_or_b32 v22, v22, 9, v1
	v_lshl_or_b32 v23, v23, 9, v1
	v_and_b32_e32 v98, s0, v150
	v_and_b32_e32 v102, s1, v150
	v_and_b32_e32 v99, s0, v151
	v_and_b32_e32 v103, s1, v151
	v_and_b32_e32 v100, s0, v152
	v_and_b32_e32 v104, s1, v152
	v_and_b32_e32 v101, s0, v153
	v_and_b32_e32 v105, s1, v153
	v_readlane_b32 s0, v176, 44
	v_readlane_b32 s1, v176, 45
	global_load_dwordx4 v[74:77], v22, s[10:11]
	global_load_dwordx4 v[38:41], v23, s[10:11]
	v_mov_b32_e32 v22, s1
	v_mov_b32_e32 v23, s0
	v_readlane_b32 s0, v176, 46
	v_readlane_b32 s1, v176, 47
	v_cndmask_b32_e64 v22, v22, v23, s[4:5]
	v_mov_b32_e32 v24, s0
	v_mov_b32_e32 v23, s1
	v_lshl_or_b32 v22, v22, 9, v1
	v_cndmask_b32_e64 v23, v23, v24, s[4:5]
	s_waitcnt vmcnt(15)
	v_mfma_scale_f32_32x32x64_f8f6f4 v[2:17], v[82:85], v[98:105], v[2:17], v160, v160 op_sel_hi:[0,0,0] cbsz:4
	v_lshl_or_b32 v23, v23, 9, v1
	global_load_dwordx4 v[98:101], v22, s[10:11]
	global_load_dwordx4 v[46:49], v23, s[10:11]
	v_readlane_b32 s0, v106, 14
	v_readlane_b32 s1, v106, 15
	s_nop 0
	v_and_b32_e32 v78, s0, v150
	v_and_b32_e32 v82, s1, v150
	v_and_b32_e32 v79, s0, v151
	v_and_b32_e32 v83, s1, v151
	v_and_b32_e32 v80, s0, v152
	v_and_b32_e32 v84, s1, v152
	v_and_b32_e32 v81, s0, v153
	v_and_b32_e32 v85, s1, v153
	s_waitcnt vmcnt(16)
	s_nop 0
	v_mfma_scale_f32_32x32x64_f8f6f4 v[2:17], v[18:21], v[78:85], v[2:17], v160, v160 op_sel_hi:[0,0,0] cbsz:4
	v_readlane_b32 s0, v106, 16
	v_readlane_b32 s1, v106, 17
	s_nop 0
	v_and_b32_e32 v18, s0, v150
	v_and_b32_e32 v22, s1, v150
	v_and_b32_e32 v19, s0, v151
	v_and_b32_e32 v23, s1, v151
	v_and_b32_e32 v20, s0, v152
	v_and_b32_e32 v24, s1, v152
	v_and_b32_e32 v21, s0, v153
	v_and_b32_e32 v25, s1, v153
	v_readlane_b32 s0, v176, 48
	v_readlane_b32 s1, v176, 49
	s_waitcnt vmcnt(15)
; #define VLOADA(slot, ereg, lsel) { const int ea_ = __builtin_amdgcn_readlane((ereg), (lsel)), eb_ = __builtin_amdgcn_readlane((ereg), (lsel) + 1); const int el_ = hh ? eb_ : ea_; ring[slot] = *(const GAS v4u*)(V4 + (((unsigned)el_ << 9) + laneoff)); }
; template <bool FINAL>
; __device__ __forceinline__ void phase_gather_v_mfma(const bf16* X, const int* EID, const float* COEF, const unsigned char* V4, const float* g, const float* bb, bf16* Ob, float* Of) {
;     ...
;         for (int J = 0; J < 64; ++J) {
;             const int ra = __builtin_amdgcn_readlane((J >> 5) ? rep1 : rep0, (2 * J) & 63), rb = __builtin_amdgcn_readlane((J >> 5) ? rep1 : rep0, ((2 * J) & 63) + 1);
;             v8i A, B;
;             A[0] = (int)ring[J & 15].x; A[1] = (int)ring[J & 15].y; A[2] = (int)ring[J & 15].z; A[3] = (int)ring[J & 15].w; A[4] = 0; A[5] = 0; A[6] = 0; A[7] = 0;
; #pragma unroll
;             for (int d = 0; d < 4; ++d) { B[d] = ra & (int)mask[d]; B[4 + d] = rb & (int)mask[d]; }
;             acc = __builtin_amdgcn_mfma_scale_f32_32x32x64_f8f6f4(A, B, acc, 4, 0, 0, 0x7f7f7f7f, 0, 0x7f7f7f7f);
;             if (J + 16 < 64) { VLOADA(J & 15, ((J + 16) >> 5) ? e1 : e0, (2 * (J + 16)) & 63) }
;             else { VLOADA(J & 15, ne0, 2 * (J + 16 - 64)) }
;             if ((J & 3) == 3) __builtin_amdgcn_sched_barrier(0);
	v_mfma_scale_f32_32x32x64_f8f6f4 v[2:17], v[62:65], v[18:25], v[2:17], v160, v160 op_sel_hi:[0,0,0] cbsz:4
	v_mov_b32_e32 v59, s0
	v_mov_b32_e32 v58, s1
	v_cndmask_b32_e64 v18, v58, v59, s[4:5]
	v_readlane_b32 s0, v106, 18
	v_readlane_b32 s1, v106, 19
	v_lshl_or_b32 v58, v18, 9, v1
	v_and_b32_e32 v18, s0, v150
	v_and_b32_e32 v22, s1, v150
	v_and_b32_e32 v19, s0, v151
	v_and_b32_e32 v23, s1, v151
	v_and_b32_e32 v20, s0, v152
	v_and_b32_e32 v24, s1, v152
	v_and_b32_e32 v21, s0, v153
	v_and_b32_e32 v25, s1, v153
	v_readlane_b32 s0, v176, 50
	v_readlane_b32 s1, v176, 51
	s_waitcnt vmcnt(14)
	v_mfma_scale_f32_32x32x64_f8f6f4 v[2:17], v[42:45], v[18:25], v[2:17], v160, v160 op_sel_hi:[0,0,0] cbsz:4
	v_mov_b32_e32 v18, s0
	v_mov_b32_e32 v59, s1
	v_cndmask_b32_e64 v18, v59, v18, s[4:5]
	v_lshl_or_b32 v18, v18, 9, v1
	v_readlane_b32 s0, v106, 20
	v_readlane_b32 s1, v106, 21
	global_load_dwordx4 v[78:81], v58, s[10:11]
	s_nop 0
	global_load_dwordx4 v[58:61], v18, s[10:11]
	v_and_b32_e32 v18, s0, v150
	v_and_b32_e32 v22, s1, v150
	v_and_b32_e32 v19, s0, v151
	v_and_b32_e32 v23, s1, v151
	v_and_b32_e32 v20, s0, v152
	v_and_b32_e32 v24, s1, v152
	v_and_b32_e32 v21, s0, v153
	v_and_b32_e32 v25, s1, v153
	v_readlane_b32 s0, v176, 52
	v_readlane_b32 s1, v176, 53
	s_waitcnt vmcnt(15)
	v_mfma_scale_f32_32x32x64_f8f6f4 v[2:17], v[86:89], v[18:25], v[2:17], v160, v160 op_sel_hi:[0,0,0] cbsz:4
	v_mov_b32_e32 v19, s0
	v_mov_b32_e32 v18, s1
	v_readlane_b32 s0, v176, 54
	v_readlane_b32 s1, v176, 55
	v_cndmask_b32_e64 v18, v18, v19, s[4:5]
	v_mov_b32_e32 v20, s0
	v_mov_b32_e32 v19, s1
	v_lshl_or_b32 v18, v18, 9, v1
	v_cndmask_b32_e64 v19, v19, v20, s[4:5]
	v_lshl_or_b32 v19, v19, 9, v1
	global_load_dwordx4 v[102:105], v18, s[10:11]
	global_load_dwordx4 v[62:65], v19, s[10:11]
	v_readlane_b32 s0, v106, 22
	v_readlane_b32 s1, v106, 23
	s_nop 0
	v_and_b32_e32 v18, s0, v150
	v_and_b32_e32 v22, s1, v150
	v_and_b32_e32 v19, s0, v151
	v_and_b32_e32 v23, s1, v151
	v_and_b32_e32 v20, s0, v152
	v_and_b32_e32 v24, s1, v152
	v_and_b32_e32 v21, s0, v153
	v_and_b32_e32 v25, s1, v153
	s_waitcnt vmcnt(16)
	s_nop 0
	v_mfma_scale_f32_32x32x64_f8f6f4 v[2:17], v[26:29], v[18:25], v[2:17], v160, v160 op_sel_hi:[0,0,0] cbsz:4
	v_readlane_b32 s0, v106, 24
	v_readlane_b32 s1, v106, 25
	s_nop 0
	v_and_b32_e32 v18, s0, v150
	v_and_b32_e32 v22, s1, v150
	v_and_b32_e32 v19, s0, v151
	v_and_b32_e32 v23, s1, v151
	v_and_b32_e32 v20, s0, v152
	v_and_b32_e32 v24, s1, v152
	v_and_b32_e32 v21, s0, v153
	v_and_b32_e32 v25, s1, v153
	v_readlane_b32 s0, v176, 56
	v_readlane_b32 s1, v176, 57
	s_waitcnt vmcnt(15)
	v_mfma_scale_f32_32x32x64_f8f6f4 v[2:17], v[66:69], v[18:25], v[2:17], v160, v160 op_sel_hi:[0,0,0] cbsz:4
	v_mov_b32_e32 v27, s0
	v_mov_b32_e32 v26, s1
	v_cndmask_b32_e64 v18, v26, v27, s[4:5]
	v_readlane_b32 s0, v106, 26
	v_readlane_b32 s1, v106, 27
	v_lshl_or_b32 v26, v18, 9, v1
	v_and_b32_e32 v18, s0, v150
	v_and_b32_e32 v22, s1, v150
	v_and_b32_e32 v19, s0, v151
	v_and_b32_e32 v23, s1, v151
	v_and_b32_e32 v20, s0, v152
	v_and_b32_e32 v24, s1, v152
	v_and_b32_e32 v21, s0, v153
	v_and_b32_e32 v25, s1, v153
	v_readlane_b32 s0, v176, 58
	v_readlane_b32 s1, v176, 59
	s_waitcnt vmcnt(14)
	v_mfma_scale_f32_32x32x64_f8f6f4 v[2:17], v[50:53], v[18:25], v[2:17], v160, v160 op_sel_hi:[0,0,0] cbsz:4
	v_mov_b32_e32 v18, s0
	v_mov_b32_e32 v27, s1
	v_cndmask_b32_e64 v18, v27, v18, s[4:5]
	v_lshl_or_b32 v18, v18, 9, v1
	v_readlane_b32 s0, v106, 28
	v_readlane_b32 s1, v106, 29
	global_load_dwordx4 v[86:89], v26, s[10:11]
	global_load_dwordx4 v[66:69], v18, s[10:11]
	v_and_b32_e32 v18, s0, v150
	v_and_b32_e32 v22, s1, v150
	v_and_b32_e32 v19, s0, v151
	v_and_b32_e32 v23, s1, v151
	v_and_b32_e32 v20, s0, v152
	v_and_b32_e32 v24, s1, v152
	v_and_b32_e32 v21, s0, v153
	v_and_b32_e32 v25, s1, v153
	v_readlane_b32 s0, v176, 60
	v_readlane_b32 s1, v176, 61
	s_waitcnt vmcnt(15)
	v_mfma_scale_f32_32x32x64_f8f6f4 v[2:17], v[90:93], v[18:25], v[2:17], v160, v160 op_sel_hi:[0,0,0] cbsz:4
	v_mov_b32_e32 v19, s0
	v_mov_b32_e32 v18, s1
	v_readlane_b32 s0, v176, 62
	v_readlane_b32 s1, v176, 63
	v_cndmask_b32_e64 v18, v18, v19, s[4:5]
	v_mov_b32_e32 v20, s0
	v_mov_b32_e32 v19, s1
	v_lshl_or_b32 v18, v18, 9, v1
	v_cndmask_b32_e64 v19, v19, v20, s[4:5]
	v_lshl_or_b32 v19, v19, 9, v1
	global_load_dwordx4 v[90:93], v18, s[10:11]
	global_load_dwordx4 v[82:85], v19, s[10:11]
	v_readlane_b32 s0, v106, 30
	v_readlane_b32 s1, v106, 31
	s_nop 0
	v_and_b32_e32 v18, s0, v150
	v_and_b32_e32 v22, s1, v150
	v_and_b32_e32 v19, s0, v151
	v_and_b32_e32 v23, s1, v151
	v_and_b32_e32 v20, s0, v152
	v_and_b32_e32 v24, s1, v152
	v_and_b32_e32 v21, s0, v153
	v_and_b32_e32 v25, s1, v153
	s_waitcnt vmcnt(16)
	s_nop 0
	v_mfma_scale_f32_32x32x64_f8f6f4 v[2:17], v[30:33], v[18:25], v[2:17], v160, v160 op_sel_hi:[0,0,0] cbsz:4
	v_readlane_b32 s0, v106, 32
	v_readlane_b32 s1, v106, 33
	s_nop 0
	v_and_b32_e32 v18, s0, v150
	v_and_b32_e32 v22, s1, v150
	v_and_b32_e32 v19, s0, v151
	v_and_b32_e32 v23, s1, v151
	v_and_b32_e32 v20, s0, v152
	v_and_b32_e32 v24, s1, v152
	v_and_b32_e32 v21, s0, v153
	v_and_b32_e32 v25, s1, v153
	v_readlane_b32 s0, v164, 0
	v_readlane_b32 s1, v164, 1
	s_waitcnt vmcnt(15)
	v_mfma_scale_f32_32x32x64_f8f6f4 v[2:17], v[70:73], v[18:25], v[2:17], v160, v160 op_sel_hi:[0,0,0] cbsz:4
	v_mov_b32_e32 v27, s0
	v_mov_b32_e32 v26, s1
	v_cndmask_b32_e64 v18, v26, v27, s[4:5]
	v_readlane_b32 s0, v106, 34
	v_readlane_b32 s1, v106, 35
	v_lshl_or_b32 v26, v18, 9, v1
	v_and_b32_e32 v18, s0, v150
	v_and_b32_e32 v22, s1, v150
	v_and_b32_e32 v19, s0, v151
	v_and_b32_e32 v23, s1, v151
	v_and_b32_e32 v20, s0, v152
	v_and_b32_e32 v24, s1, v152
	v_and_b32_e32 v21, s0, v153
	v_and_b32_e32 v25, s1, v153
	v_readlane_b32 s0, v164, 2
	v_readlane_b32 s1, v164, 3
	s_waitcnt vmcnt(14)
; #define VLOADA(slot, ereg, lsel) { const int ea_ = __builtin_amdgcn_readlane((ereg), (lsel)), eb_ = __builtin_amdgcn_readlane((ereg), (lsel) + 1); const int el_ = hh ? eb_ : ea_; ring[slot] = *(const GAS v4u*)(V4 + (((unsigned)el_ << 9) + laneoff)); }
; template <bool FINAL>
; __device__ __forceinline__ void phase_gather_v_mfma(const bf16* X, const int* EID, const float* COEF, const unsigned char* V4, const float* g, const float* bb, bf16* Ob, float* Of) {
;     ...
;         for (int J = 0; J < 64; ++J) {
;             const int ra = __builtin_amdgcn_readlane((J >> 5) ? rep1 : rep0, (2 * J) & 63), rb = __builtin_amdgcn_readlane((J >> 5) ? rep1 : rep0, ((2 * J) & 63) + 1);
;             v8i A, B;
;             A[0] = (int)ring[J & 15].x; A[1] = (int)ring[J & 15].y; A[2] = (int)ring[J & 15].z; A[3] = (int)ring[J & 15].w; A[4] = 0; A[5] = 0; A[6] = 0; A[7] = 0;
; #pragma unroll
;             for (int d = 0; d < 4; ++d) { B[d] = ra & (int)mask[d]; B[4 + d] = rb & (int)mask[d]; }
;             acc = __builtin_amdgcn_mfma_scale_f32_32x32x64_f8f6f4(A, B, acc, 4, 0, 0, 0x7f7f7f7f, 0, 0x7f7f7f7f);
;             if (J + 16 < 64) { VLOADA(J & 15, ((J + 16) >> 5) ? e1 : e0, (2 * (J + 16)) & 63) }
;             else { VLOADA(J & 15, ne0, 2 * (J + 16 - 64)) }
;             if ((J & 3) == 3) __builtin_amdgcn_sched_barrier(0);
	v_mfma_scale_f32_32x32x64_f8f6f4 v[2:17], v[54:57], v[18:25], v[2:17], v160, v160 op_sel_hi:[0,0,0] cbsz:4
	v_mov_b32_e32 v18, s0
	v_mov_b32_e32 v27, s1
	v_cndmask_b32_e64 v18, v27, v18, s[4:5]
	v_lshl_or_b32 v18, v18, 9, v1
	v_readlane_b32 s0, v106, 36
	v_readlane_b32 s1, v106, 37
	global_load_dwordx4 v[22:25], v26, s[10:11]
	s_nop 0
	global_load_dwordx4 v[18:21], v18, s[10:11]
	v_and_b32_e32 v26, s0, v150
	v_and_b32_e32 v30, s1, v150
	v_and_b32_e32 v27, s0, v151
	v_and_b32_e32 v31, s1, v151
	v_and_b32_e32 v28, s0, v152
	v_and_b32_e32 v32, s1, v152
	v_and_b32_e32 v29, s0, v153
	v_and_b32_e32 v33, s1, v153
	v_readlane_b32 s0, v164, 4
	v_readlane_b32 s1, v164, 5
	s_waitcnt vmcnt(15)
	v_mfma_scale_f32_32x32x64_f8f6f4 v[2:17], v[94:97], v[26:33], v[2:17], v160, v160 op_sel_hi:[0,0,0] cbsz:4
	v_mov_b32_e32 v27, s0
	v_mov_b32_e32 v26, s1
	v_readlane_b32 s0, v164, 6
	v_readlane_b32 s1, v164, 7
	v_cndmask_b32_e64 v26, v26, v27, s[4:5]
	v_mov_b32_e32 v28, s0
	v_mov_b32_e32 v27, s1
	v_cndmask_b32_e64 v27, v27, v28, s[4:5]
	v_lshl_or_b32 v26, v26, 9, v1
	v_lshl_or_b32 v27, v27, 9, v1
	global_load_dwordx4 v[30:33], v26, s[10:11]
	s_nop 0
	global_load_dwordx4 v[26:29], v27, s[10:11]
	v_readlane_b32 s0, v106, 38
	v_readlane_b32 s1, v106, 39
	s_nop 0
	v_and_b32_e32 v50, s0, v150
	v_and_b32_e32 v54, s1, v150
	v_and_b32_e32 v51, s0, v151
	v_and_b32_e32 v55, s1, v151
	v_and_b32_e32 v52, s0, v152
	v_and_b32_e32 v56, s1, v152
	v_and_b32_e32 v53, s0, v153
	v_and_b32_e32 v57, s1, v153
	s_waitcnt vmcnt(16)
	s_nop 0
	v_mfma_scale_f32_32x32x64_f8f6f4 v[2:17], v[34:37], v[50:57], v[2:17], v160, v160 op_sel_hi:[0,0,0] cbsz:4
	v_readlane_b32 s0, v106, 40
	v_readlane_b32 s1, v106, 41
	s_nop 0
	v_and_b32_e32 v50, s0, v150
	v_and_b32_e32 v54, s1, v150
	v_and_b32_e32 v51, s0, v151
	v_and_b32_e32 v55, s1, v151
	v_and_b32_e32 v52, s0, v152
	v_and_b32_e32 v56, s1, v152
	v_and_b32_e32 v53, s0, v153
	v_and_b32_e32 v57, s1, v153
	v_readlane_b32 s0, v164, 8
	v_readlane_b32 s1, v164, 9
	s_waitcnt vmcnt(15)
	v_mfma_scale_f32_32x32x64_f8f6f4 v[2:17], v[74:77], v[50:57], v[2:17], v160, v160 op_sel_hi:[0,0,0] cbsz:4
	v_mov_b32_e32 v35, s0
	v_mov_b32_e32 v34, s1
	v_readlane_b32 s0, v106, 42
	v_readlane_b32 s1, v106, 43
	v_cndmask_b32_e64 v34, v34, v35, s[4:5]
	v_and_b32_e32 v50, s0, v150
	v_and_b32_e32 v54, s1, v150
	v_and_b32_e32 v51, s0, v151
	v_and_b32_e32 v55, s1, v151
	v_and_b32_e32 v52, s0, v152
	v_and_b32_e32 v56, s1, v152
	v_and_b32_e32 v53, s0, v153
	v_and_b32_e32 v57, s1, v153
	v_readlane_b32 s0, v164, 10
	v_readlane_b32 s1, v164, 11
	s_waitcnt vmcnt(14)
	v_mfma_scale_f32_32x32x64_f8f6f4 v[2:17], v[38:41], v[50:57], v[2:17], v160, v160 op_sel_hi:[0,0,0] cbsz:4
	v_mov_b32_e32 v36, s0
	v_mov_b32_e32 v35, s1
	v_readlane_b32 s0, v106, 44
	v_readlane_b32 s1, v106, 45
	v_cndmask_b32_e64 v35, v35, v36, s[4:5]
	v_and_b32_e32 v50, s0, v150
	v_and_b32_e32 v54, s1, v150
	v_and_b32_e32 v51, s0, v151
	v_and_b32_e32 v55, s1, v151
	v_and_b32_e32 v52, s0, v152
	v_and_b32_e32 v56, s1, v152
	v_and_b32_e32 v53, s0, v153
	v_and_b32_e32 v57, s1, v153
	v_readlane_b32 s0, v164, 12
	v_readlane_b32 s1, v164, 13
	v_lshl_or_b32 v34, v34, 9, v1
	v_mov_b32_e32 v39, s0
	v_mov_b32_e32 v38, s1
	v_readlane_b32 s0, v164, 14
	v_readlane_b32 s1, v164, 15
	v_cndmask_b32_e64 v38, v38, v39, s[4:5]
	v_mov_b32_e32 v40, s0
	v_mov_b32_e32 v39, s1
	v_cndmask_b32_e64 v39, v39, v40, s[4:5]
	v_lshl_or_b32 v35, v35, 9, v1
	v_lshl_or_b32 v38, v38, 9, v1
	v_lshl_or_b32 v39, v39, 9, v1
	global_load_dwordx4 v[42:45], v34, s[10:11]
	s_nop 0
	global_load_dwordx4 v[34:37], v35, s[10:11]
	s_waitcnt vmcnt(15)
	v_mfma_scale_f32_32x32x64_f8f6f4 v[2:17], v[98:101], v[50:57], v[2:17], v160, v160 op_sel_hi:[0,0,0] cbsz:4
	global_load_dwordx4 v[54:57], v38, s[10:11]
	s_nop 0
	global_load_dwordx4 v[38:41], v39, s[10:11]
	v_readlane_b32 s0, v106, 46
	v_readlane_b32 s1, v106, 47
	s_nop 0
	v_and_b32_e32 v70, s0, v150
	v_and_b32_e32 v74, s1, v150
	v_and_b32_e32 v71, s0, v151
	v_and_b32_e32 v75, s1, v151
	v_and_b32_e32 v72, s0, v152
	v_and_b32_e32 v76, s1, v152
	v_and_b32_e32 v73, s0, v153
	v_and_b32_e32 v77, s1, v153
	s_waitcnt vmcnt(16)
	s_nop 0
	v_mfma_scale_f32_32x32x64_f8f6f4 v[2:17], v[46:49], v[70:77], v[2:17], v160, v160 op_sel_hi:[0,0,0] cbsz:4
	v_readlane_b32 s0, v106, 48
	v_readlane_b32 s1, v106, 49
	s_nop 0
	v_and_b32_e32 v46, s0, v150
	v_and_b32_e32 v50, s1, v150
	v_and_b32_e32 v47, s0, v151
	v_and_b32_e32 v51, s1, v151
	v_and_b32_e32 v48, s0, v152
	v_and_b32_e32 v52, s1, v152
	v_and_b32_e32 v49, s0, v153
	v_and_b32_e32 v53, s1, v153
	v_readlane_b32 s0, v164, 16
	v_readlane_b32 s1, v164, 17
	s_waitcnt vmcnt(15)
	v_mfma_scale_f32_32x32x64_f8f6f4 v[2:17], v[78:81], v[46:53], v[2:17], v160, v160 op_sel_hi:[0,0,0] cbsz:4
	v_mov_b32_e32 v71, s0
	v_mov_b32_e32 v70, s1
	v_cndmask_b32_e64 v46, v70, v71, s[4:5]
	v_readlane_b32 s0, v106, 50
	v_readlane_b32 s1, v106, 51
	v_lshl_or_b32 v70, v46, 9, v1
	v_and_b32_e32 v46, s0, v150
	v_and_b32_e32 v50, s1, v150
	v_and_b32_e32 v47, s0, v151
	v_and_b32_e32 v51, s1, v151
	v_and_b32_e32 v48, s0, v152
	v_and_b32_e32 v52, s1, v152
	v_and_b32_e32 v49, s0, v153
	v_and_b32_e32 v53, s1, v153
	v_readlane_b32 s0, v164, 18
	v_readlane_b32 s1, v164, 19
	s_waitcnt vmcnt(14)
	v_mfma_scale_f32_32x32x64_f8f6f4 v[2:17], v[58:61], v[46:53], v[2:17], v160, v160 op_sel_hi:[0,0,0] cbsz:4
	v_mov_b32_e32 v46, s0
	v_mov_b32_e32 v71, s1
	v_cndmask_b32_e64 v46, v71, v46, s[4:5]
	v_lshl_or_b32 v46, v46, 9, v1
	v_readlane_b32 s0, v106, 52
	v_readlane_b32 s1, v106, 53
	global_load_dwordx4 v[58:61], v70, s[10:11]
	s_nop 0
	global_load_dwordx4 v[46:49], v46, s[10:11]
	v_and_b32_e32 v70, s0, v150
	v_and_b32_e32 v74, s1, v150
	v_and_b32_e32 v71, s0, v151
	v_and_b32_e32 v75, s1, v151
	v_and_b32_e32 v72, s0, v152
	v_and_b32_e32 v76, s1, v152
	v_and_b32_e32 v73, s0, v153
	v_and_b32_e32 v77, s1, v153
	v_readlane_b32 s0, v164, 20
	v_readlane_b32 s1, v164, 21
	s_waitcnt vmcnt(15)
; #define VLOADA(slot, ereg, lsel) { const int ea_ = __builtin_amdgcn_readlane((ereg), (lsel)), eb_ = __builtin_amdgcn_readlane((ereg), (lsel) + 1); const int el_ = hh ? eb_ : ea_; ring[slot] = *(const GAS v4u*)(V4 + (((unsigned)el_ << 9) + laneoff)); }
; template <bool FINAL>
; __device__ __forceinline__ void phase_gather_v_mfma(const bf16* X, const int* EID, const float* COEF, const unsigned char* V4, const float* g, const float* bb, bf16* Ob, float* Of) {
;     ...
;         for (int J = 0; J < 64; ++J) {
;             const int ra = __builtin_amdgcn_readlane((J >> 5) ? rep1 : rep0, (2 * J) & 63), rb = __builtin_amdgcn_readlane((J >> 5) ? rep1 : rep0, ((2 * J) & 63) + 1);
;             v8i A, B;
;             A[0] = (int)ring[J & 15].x; A[1] = (int)ring[J & 15].y; A[2] = (int)ring[J & 15].z; A[3] = (int)ring[J & 15].w; A[4] = 0; A[5] = 0; A[6] = 0; A[7] = 0;
; #pragma unroll
;             for (int d = 0; d < 4; ++d) { B[d] = ra & (int)mask[d]; B[4 + d] = rb & (int)mask[d]; }
;             acc = __builtin_amdgcn_mfma_scale_f32_32x32x64_f8f6f4(A, B, acc, 4, 0, 0, 0x7f7f7f7f, 0, 0x7f7f7f7f);
;             if (J + 16 < 64) { VLOADA(J & 15, ((J + 16) >> 5) ? e1 : e0, (2 * (J + 16)) & 63) }
;             else { VLOADA(J & 15, ne0, 2 * (J + 16 - 64)) }
;             if ((J & 3) == 3) __builtin_amdgcn_sched_barrier(0);
;         }
;         float z[16]; float sm = 0.f;
; #pragma unroll
;         for (int r = 0; r < 16; ++r) { const float av = acc[r]; z[r] = ALPHA * bf2f(xs[r]) + av * invS; sm += z[r]; }
;         const float mean = wave_sum(sm) * (1.f / D); float s2 = 0.f;
	v_mfma_scale_f32_32x32x64_f8f6f4 v[2:17], v[102:105], v[70:77], v[2:17], v160, v160 op_sel_hi:[0,0,0] cbsz:4
	v_mov_b32_e32 v51, s0
	v_mov_b32_e32 v50, s1
	v_readlane_b32 s0, v164, 22
	v_readlane_b32 s1, v164, 23
	v_cndmask_b32_e64 v50, v50, v51, s[4:5]
	v_mov_b32_e32 v52, s0
	v_mov_b32_e32 v51, s1
	v_cndmask_b32_e64 v51, v51, v52, s[4:5]
	v_lshl_or_b32 v50, v50, 9, v1
	v_lshl_or_b32 v51, v51, 9, v1
	global_load_dwordx4 v[70:73], v50, s[10:11]
	s_nop 0
	global_load_dwordx4 v[50:53], v51, s[10:11]
	v_readlane_b32 s0, v106, 54
	v_readlane_b32 s1, v106, 55
	s_nop 0
	v_and_b32_e32 v74, s0, v150
	v_and_b32_e32 v78, s1, v150
	v_and_b32_e32 v75, s0, v151
	v_and_b32_e32 v79, s1, v151
	v_and_b32_e32 v76, s0, v152
	v_and_b32_e32 v80, s1, v152
	v_and_b32_e32 v77, s0, v153
	v_and_b32_e32 v81, s1, v153
	s_waitcnt vmcnt(16)
	s_nop 0
	v_mfma_scale_f32_32x32x64_f8f6f4 v[2:17], v[62:65], v[74:81], v[2:17], v160, v160 op_sel_hi:[0,0,0] cbsz:4
	v_readlane_b32 s0, v106, 56
	v_readlane_b32 s1, v106, 57
	s_nop 0
	v_and_b32_e32 v74, s0, v150
	v_and_b32_e32 v78, s1, v150
	v_and_b32_e32 v75, s0, v151
	v_and_b32_e32 v79, s1, v151
	v_and_b32_e32 v76, s0, v152
	v_and_b32_e32 v80, s1, v152
	v_and_b32_e32 v77, s0, v153
	v_and_b32_e32 v81, s1, v153
	v_readlane_b32 s0, v164, 24
	v_readlane_b32 s1, v164, 25
	s_waitcnt vmcnt(15)
	v_mfma_scale_f32_32x32x64_f8f6f4 v[2:17], v[86:89], v[74:81], v[2:17], v160, v160 op_sel_hi:[0,0,0] cbsz:4
	v_mov_b32_e32 v63, s0
	v_mov_b32_e32 v62, s1
	v_readlane_b32 s0, v106, 58
	v_readlane_b32 s1, v106, 59
	v_cndmask_b32_e64 v62, v62, v63, s[4:5]
	v_and_b32_e32 v74, s0, v150
	v_and_b32_e32 v78, s1, v150
	v_and_b32_e32 v75, s0, v151
	v_and_b32_e32 v79, s1, v151
	v_and_b32_e32 v76, s0, v152
	v_and_b32_e32 v80, s1, v152
	v_and_b32_e32 v77, s0, v153
	v_and_b32_e32 v81, s1, v153
	v_readlane_b32 s0, v164, 26
	v_readlane_b32 s1, v164, 27
	s_waitcnt vmcnt(14)
	v_mfma_scale_f32_32x32x64_f8f6f4 v[2:17], v[66:69], v[74:81], v[2:17], v160, v160 op_sel_hi:[0,0,0] cbsz:4
	v_mov_b32_e32 v64, s0
	v_mov_b32_e32 v63, s1
	v_readlane_b32 s0, v106, 60
	v_readlane_b32 s1, v106, 61
	v_cndmask_b32_e64 v63, v63, v64, s[4:5]
	v_and_b32_e32 v94, s0, v150
	v_and_b32_e32 v98, s1, v150
	v_and_b32_e32 v95, s0, v151
	v_and_b32_e32 v99, s1, v151
	v_and_b32_e32 v96, s0, v152
	v_and_b32_e32 v100, s1, v152
	v_and_b32_e32 v97, s0, v153
	v_and_b32_e32 v101, s1, v153
	v_readlane_b32 s0, v164, 28
	v_readlane_b32 s1, v164, 29
	v_lshl_or_b32 v62, v62, 9, v1
	v_mov_b32_e32 v67, s0
	v_mov_b32_e32 v66, s1
	v_readlane_b32 s0, v164, 30
	v_readlane_b32 s1, v164, 31
	v_cndmask_b32_e64 v66, v66, v67, s[4:5]
	v_mov_b32_e32 v68, s0
	v_mov_b32_e32 v67, s1
	v_cndmask_b32_e64 v67, v67, v68, s[4:5]
	v_lshl_or_b32 v63, v63, 9, v1
	v_lshl_or_b32 v66, v66, 9, v1
	v_lshl_or_b32 v67, v67, 9, v1
	global_load_dwordx4 v[74:77], v62, s[10:11]
	s_nop 0
	global_load_dwordx4 v[62:65], v63, s[10:11]
	s_nop 0
	global_load_dwordx4 v[78:81], v66, s[10:11]
	s_nop 0
	global_load_dwordx4 v[66:69], v67, s[10:11]
	s_waitcnt vmcnt(17)
	v_mfma_scale_f32_32x32x64_f8f6f4 v[2:17], v[90:93], v[94:101], v[2:17], v160, v160 op_sel_hi:[0,0,0] cbsz:4
	v_readlane_b32 s0, v106, 62
	v_readlane_b32 s1, v106, 63
	s_nop 0
	v_and_b32_e32 v86, s0, v150
	v_and_b32_e32 v90, s1, v150
	v_and_b32_e32 v87, s0, v151
	v_and_b32_e32 v91, s1, v151
	v_and_b32_e32 v88, s0, v152
	v_and_b32_e32 v92, s1, v152
	v_and_b32_e32 v89, s0, v153
	v_and_b32_e32 v93, s1, v153
	s_waitcnt vmcnt(16)
	s_nop 0
	v_mfma_scale_f32_32x32x64_f8f6f4 v[2:17], v[82:85], v[86:93], v[2:17], v160, v160 op_sel_hi:[0,0,0] cbsz:4
	v_lshlrev_b32_e32 v82, 16, v184
	s_nop 15
	s_nop 2
	v_mul_f32_e32 v2, v2, v167
	v_fmac_f32_e32 v2, 0x3fb504f3, v82
	v_lshlrev_b32_e32 v83, 16, v183
	v_mul_f32_e32 v84, v3, v167
	v_add_f32_e32 v82, 0, v2
	v_fmac_f32_e32 v84, 0x3fb504f3, v83
	v_add_f32_e32 v3, v84, v82
	v_lshlrev_b32_e32 v82, 16, v182
	v_mul_f32_e32 v4, v4, v167
	v_fmac_f32_e32 v4, 0x3fb504f3, v82
	v_lshlrev_b32_e32 v82, 16, v181
	v_mul_f32_e32 v5, v5, v167
	v_add_f32_e32 v3, v4, v3
	v_fmac_f32_e32 v5, 0x3fb504f3, v82
	v_lshlrev_b32_e32 v82, 16, v180
	v_mul_f32_e32 v6, v6, v167
	v_add_f32_e32 v3, v5, v3
	v_fmac_f32_e32 v6, 0x3fb504f3, v82
	v_lshlrev_b32_e32 v82, 16, v179
	v_mul_f32_e32 v7, v7, v167
	v_add_f32_e32 v3, v6, v3
	v_fmac_f32_e32 v7, 0x3fb504f3, v82
	v_lshlrev_b32_e32 v82, 16, v178
	v_mul_f32_e32 v8, v8, v167
	v_add_f32_e32 v3, v7, v3
	v_fmac_f32_e32 v8, 0x3fb504f3, v82
	v_lshlrev_b32_e32 v82, 16, v177
	v_mul_f32_e32 v9, v9, v167
	v_add_f32_e32 v3, v8, v3
	v_fmac_f32_e32 v9, 0x3fb504f3, v82
	v_lshlrev_b32_e32 v82, 16, v175
	v_mul_f32_e32 v10, v10, v167
	v_add_f32_e32 v3, v9, v3
	v_fmac_f32_e32 v10, 0x3fb504f3, v82
	v_lshlrev_b32_e32 v82, 16, v174
	v_mul_f32_e32 v11, v11, v167
	v_add_f32_e32 v3, v10, v3
	v_fmac_f32_e32 v11, 0x3fb504f3, v82
	v_lshlrev_b32_e32 v82, 16, v173
	v_mul_f32_e32 v12, v12, v167
	v_add_f32_e32 v3, v11, v3
	v_fmac_f32_e32 v12, 0x3fb504f3, v82
	v_lshlrev_b32_e32 v82, 16, v172
	v_mul_f32_e32 v13, v13, v167
	v_add_f32_e32 v3, v12, v3
	v_fmac_f32_e32 v13, 0x3fb504f3, v82
	v_lshlrev_b32_e32 v82, 16, v171
	v_mul_f32_e32 v14, v14, v167
	v_add_f32_e32 v3, v13, v3
	v_fmac_f32_e32 v14, 0x3fb504f3, v82
	v_lshlrev_b32_e32 v82, 16, v170
	v_mul_f32_e32 v15, v15, v167
	v_add_f32_e32 v3, v14, v3
	v_fmac_f32_e32 v15, 0x3fb504f3, v82
	v_lshlrev_b32_e32 v82, 16, v169
	v_mul_f32_e32 v16, v16, v167
	v_add_f32_e32 v3, v15, v3
	v_fmac_f32_e32 v16, 0x3fb504f3, v82
	v_lshlrev_b32_e32 v82, 16, v168
	v_mul_f32_e32 v17, v17, v167
	v_add_f32_e32 v3, v16, v3
	v_fmac_f32_e32 v17, 0x3fb504f3, v82
	v_add_f32_e32 v3, v17, v3
	v_lshl_add_u64 v[110:111], v[110:111], 0, s[14:15]
; __device__ __forceinline__ unsigned f2bf(float f) { return pk2(f, 0.f) & 0xffffu; }
; __device__ __forceinline__ float wave_sum(float v) {
; #pragma unroll
;     for (int o = 1; o < 64; o <<= 1) v += __shfl_xor(v, o);
;     return v;
; template <bool FINAL>
; __device__ __forceinline__ void phase_gather_v_mfma(const bf16* X, const int* EID, const float* COEF, const unsigned char* V4, const float* g, const float* bb, bf16* Ob, float* Of) {
;     ...
;         for (int r = 0; r < 16; ++r) { const float av = acc[r]; z[r] = ALPHA * bf2f(xs[r]) + av * invS; sm += z[r]; }
;         const float mean = wave_sum(sm) * (1.f / D); float s2 = 0.f;
; #pragma unroll
;         for (int r = 0; r < 16; ++r) { z[r] -= mean; s2 += z[r] * z[r]; }
;         const float rstd = 1.f / sqrtf(wave_sum(s2) * (1.f / D) + LN_EPS);
; #pragma unroll
;         for (int r = 0; r < 16; ++r) { const int col = 32 * ((r & 3) + 8 * (r >> 2) + 4 * hh) + n; const float o = z[r] * rstd * gl[r] + bl[r];
;             if (FINAL) Of[(size_t)t * D + col] = o; else Ob[(size_t)t * D + col] = (bf16)f2bf(o); }
	v_lshl_add_u64 v[116:117], v[116:117], 0, s[16:17]
	v_mov_b32_e32 v176, v163
	v_mov_b32_e32 v102, v164
	s_nop 1
	v_add_f32_dpp v3, v3, v3 row_shr:1 row_mask:0xf bank_mask:0xf
	s_nop 1
	v_add_f32_dpp v3, v3, v3 row_shr:2 row_mask:0xf bank_mask:0xf
	s_nop 1
	v_add_f32_dpp v3, v3, v3 row_shr:4 row_mask:0xf bank_mask:0xf
	s_nop 1
	v_add_f32_dpp v3, v3, v3 row_shr:8 row_mask:0xf bank_mask:0xf
	s_nop 1
	v_add_f32_dpp v3, v3, v3 row_bcast:15 row_mask:0xa bank_mask:0xf
	s_nop 1
	v_add_f32_dpp v3, v3, v3 row_bcast:31 row_mask:0xc bank_mask:0xf
	s_nop 0
	v_readlane_b32 s98, v3, 63
	s_nop 1
	v_mov_b32_e32 v3, s98
	v_fmac_f32_e32 v84, 0xba800000, v3
	v_fmac_f32_e32 v2, 0xba800000, v3
	v_mul_f32_e32 v82, v84, v84
	v_fmac_f32_e32 v82, v2, v2
	v_fmac_f32_e32 v4, 0xba800000, v3
	v_fmac_f32_e32 v82, v4, v4
	v_fmac_f32_e32 v5, 0xba800000, v3
	v_fmac_f32_e32 v82, v5, v5
	v_fmac_f32_e32 v6, 0xba800000, v3
	v_fmac_f32_e32 v82, v6, v6
	v_fmac_f32_e32 v7, 0xba800000, v3
	v_fmac_f32_e32 v82, v7, v7
	v_fmac_f32_e32 v8, 0xba800000, v3
	v_fmac_f32_e32 v82, v8, v8
	v_fmac_f32_e32 v9, 0xba800000, v3
	v_fmac_f32_e32 v82, v9, v9
	v_fmac_f32_e32 v10, 0xba800000, v3
	v_fmac_f32_e32 v82, v10, v10
	v_fmac_f32_e32 v11, 0xba800000, v3
	v_fmac_f32_e32 v82, v11, v11
	v_fmac_f32_e32 v12, 0xba800000, v3
	v_fmac_f32_e32 v82, v12, v12
	v_fmac_f32_e32 v13, 0xba800000, v3
	v_fmac_f32_e32 v82, v13, v13
	v_fmac_f32_e32 v14, 0xba800000, v3
	v_fmac_f32_e32 v82, v14, v14
	v_fmac_f32_e32 v15, 0xba800000, v3
	v_fmac_f32_e32 v82, v15, v15
	v_fmac_f32_e32 v16, 0xba800000, v3
	v_fmac_f32_e32 v82, v16, v16
	v_fmac_f32_e32 v17, 0xba800000, v3
	v_fmac_f32_e32 v82, v17, v17
	s_nop 1
	v_add_f32_dpp v82, v82, v82 row_shr:1 row_mask:0xf bank_mask:0xf
	s_nop 1
	v_add_f32_dpp v82, v82, v82 row_shr:2 row_mask:0xf bank_mask:0xf
	s_nop 1
	v_add_f32_dpp v82, v82, v82 row_shr:4 row_mask:0xf bank_mask:0xf
	s_nop 1
	v_add_f32_dpp v82, v82, v82 row_shr:8 row_mask:0xf bank_mask:0xf
	s_nop 1
	v_add_f32_dpp v82, v82, v82 row_bcast:15 row_mask:0xa bank_mask:0xf
	s_nop 1
	v_add_f32_dpp v82, v82, v82 row_bcast:31 row_mask:0xc bank_mask:0xf
	s_nop 0
	v_readlane_b32 s98, v82, 63
	s_nop 1
	v_mov_b32_e32 v3, s98
	v_fmamk_f32 v3, v3, 0x3a800000, v161
	v_mul_f32_e32 v82, 0x4f800000, v3
	v_cmp_gt_f32_e32 vcc, s3, v3
	s_nop 1
	v_cndmask_b32_e32 v3, v3, v82, vcc
	v_sqrt_f32_e32 v82, v3
	s_nop 0
	v_add_u32_e32 v83, -1, v82
	v_fma_f32 v85, -v83, v82, v3
	v_cmp_ge_f32_e64 s[0:1], 0, v85
	v_add_u32_e32 v85, 1, v82
	s_nop 0
	v_cndmask_b32_e64 v83, v82, v83, s[0:1]
	v_fma_f32 v82, -v85, v82, v3
	v_cmp_lt_f32_e64 s[0:1], 0, v82
	s_nop 1
	v_cndmask_b32_e64 v82, v83, v85, s[0:1]
	v_mul_f32_e32 v83, 0x37800000, v82
	v_cndmask_b32_e32 v82, v82, v83, vcc
	v_cmp_class_f32_e32 vcc, v3, v162
	s_nop 1
	v_cndmask_b32_e32 v3, v82, v3, vcc
	v_div_scale_f32 v82, s[0:1], v3, v3, 1.0
	v_rcp_f32_e32 v83, v82
	s_nop 0
	v_fma_f32 v85, -v82, v83, 1.0
	v_fmac_f32_e32 v83, v85, v83
	v_div_scale_f32 v85, vcc, 1.0, v3, 1.0
	v_mul_f32_e32 v86, v85, v83
	v_fma_f32 v87, -v82, v86, v85
	v_fmac_f32_e32 v86, v87, v83
	v_fma_f32 v82, -v82, v86, v85
	v_div_fmas_f32 v82, v82, v83, v86
	v_div_fixup_f32 v82, v82, v3, 1.0
	v_mul_f32_e32 v2, v2, v82
	v_fma_f32 v2, v118, v2, v119
	v_cvt_pk_bf16_f32 v83, v2, s0
	v_lshl_add_u64 v[2:3], s[82:83], 0, v[114:115]
	global_store_short v[2:3], v83, off nt
	v_mul_f32_e32 v2, v84, v82
	v_fma_f32 v2, v120, v2, v121
	v_cvt_pk_bf16_f32 v83, v2, s0
	v_lshl_add_u64 v[2:3], s[82:83], 0, v[112:113]
	v_mul_f32_e32 v4, v4, v82
	v_add_co_u32_e32 v2, vcc, s9, v2
	v_fma_f32 v4, v122, v4, v123
	s_nop 0
	v_addc_co_u32_e32 v3, vcc, 0, v3, vcc
	v_cvt_pk_bf16_f32 v4, v4, s0
	global_store_short v[2:3], v4, off offset:128 nt
	v_mul_f32_e32 v4, v5, v82
	v_fma_f32 v4, v124, v4, v125
	v_cvt_pk_bf16_f32 v4, v4, s0
	global_store_short v[2:3], v4, off offset:192 nt
	v_mul_f32_e32 v4, v6, v82
	v_fma_f32 v4, v126, v4, v127
	v_cvt_pk_bf16_f32 v4, v4, s0
	global_store_short v[2:3], v4, off offset:512 nt
	v_mul_f32_e32 v4, v7, v82
	v_fma_f32 v4, v128, v4, v129
	v_cvt_pk_bf16_f32 v4, v4, s0
	global_store_short v[2:3], v4, off offset:576 nt
	v_mul_f32_e32 v4, v8, v82
	v_fma_f32 v4, v130, v4, v131
	v_cvt_pk_bf16_f32 v4, v4, s0
	global_store_short v[2:3], v4, off offset:640 nt
	v_mul_f32_e32 v4, v9, v82
	v_fma_f32 v4, v132, v4, v133
	v_cvt_pk_bf16_f32 v4, v4, s0
	global_store_short v[2:3], v4, off offset:704 nt
	v_mul_f32_e32 v4, v10, v82
	v_fma_f32 v4, v134, v4, v135
	v_cvt_pk_bf16_f32 v4, v4, s0
	global_store_short v[2:3], v4, off offset:1024 nt
	v_mul_f32_e32 v4, v11, v82
	v_fma_f32 v4, v136, v4, v137
	v_cvt_pk_bf16_f32 v4, v4, s0
	global_store_short v[2:3], v4, off offset:1088 nt
	v_mul_f32_e32 v4, v12, v82
	v_fma_f32 v4, v138, v4, v139
	v_cvt_pk_bf16_f32 v4, v4, s0
	global_store_short v[2:3], v4, off offset:1152 nt
	v_mul_f32_e32 v4, v13, v82
	v_fma_f32 v4, v140, v4, v141
	v_cvt_pk_bf16_f32 v4, v4, s0
	global_store_short v[2:3], v4, off offset:1216 nt
	v_mul_f32_e32 v4, v14, v82
	v_fma_f32 v4, v142, v4, v143
	v_cvt_pk_bf16_f32 v4, v4, s0
	global_store_short v[2:3], v4, off offset:1536 nt
	v_mul_f32_e32 v4, v15, v82
	v_fma_f32 v4, v144, v4, v145
	v_cvt_pk_bf16_f32 v4, v4, s0
	global_store_short v[2:3], v4, off offset:1600 nt
	v_mul_f32_e32 v4, v16, v82
	v_fma_f32 v4, v146, v4, v147
	v_cvt_pk_bf16_f32 v4, v4, s0
	global_store_short v[2:3], v4, off offset:1664 nt
	v_mul_f32_e32 v4, v17, v82
	v_fma_f32 v4, v148, v4, v149
	v_cvt_pk_bf16_f32 v4, v4, s0
	global_store_short v[2:3], v83, off offset:64 nt
	global_store_short v[2:3], v4, off offset:1728 nt
	v_lshl_add_u64 v[114:115], v[114:115], 0, s[16:17]
	v_lshl_add_u64 v[112:113], v[112:113], 0, s[16:17]
	s_andn2_b64 vcc, exec, s[18:19]
	v_mov_b32_e32 v3, v166
	v_mov_b32_e32 v2, v165
	s_cbranch_vccz .LBB0_1043

; #define LAS __attribute__((address_space(3)))
; __device__ __forceinline__ void phase_hgrn_scan(LAS unsigned char* lds, unsigned char* ws, const float* scratch) {
;     ...
;             if (wave == 0) {
;                 LAS unsigned char* bp = lds + (n % 3) * BUF; LAS unsigned char* pi = lds + O_P + (n & 1) * 2560;
;                 const size_t t0 = ((size_t)b * 128 + n) * 32;
;                 bf16x8 vf[2];
;                 f32x16 o;
; #pragma unroll
;                 for (int r = 0; r < 16; ++r) o[r] = 0.f;
;                 bf16x8 pf[2], qf[8], sf[8];
; #pragma unroll
;                 for (int ks = 0; ks < 2; ++ks) { pf[ks] = *(const LAS bf16x8*)(pi + c * 80 + (16 * ks + 8 * hh) * 2);
;                     typedef short v4s_ __attribute__((ext_vector_type(4)));
;                     LAS unsigned char* va = bp + O_VT + (16 * ks + 8 * hh + ((lane & 15) >> 2)) * 64 + (16 * ((lane >> 4) & 1) + 4 * (lane & 3)) * 2;
;                     const v4s_ t0v = __builtin_amdgcn_ds_read_tr16_b64_v4i16((LAS v4s_*)va), t1v = __builtin_amdgcn_ds_read_tr16_b64_v4i16((LAS v4s_*)(va + 4 * 64));
;                     vf[ks] = (bf16x8){t0v.x, t0v.y, t0v.z, t0v.w, t1v.x, t1v.y, t1v.z, t1v.w}; }
; #pragma unroll
;                 for (int ks = 0; ks < 8; ++ks) { const int blk = ks >> 1, s8 = 8 * (ks & 1);
;                     const LAS unsigned char* qa = bp + O_QI + c * 272 + (32 * blk + 2 * s8 + 4 * hh) * 2;
;                     const v2u qlo = *(const LAS v2u*)qa, qhi = *(const LAS v2u*)(qa + 16);
;                     qf[ks] = __builtin_bit_cast(bf16x8, (v4u){qlo.x, qlo.y, qhi.x, qhi.y});
;                     sf[ks] = __builtin_bit_cast(bf16x8, (v4u){pk2(S[blk][s8 + 0], S[blk][s8 + 1]), pk2(S[blk][s8 + 2], S[blk][s8 + 3]), pk2(S[blk][s8 + 4], S[blk][s8 + 5]), pk2(S[blk][s8 + 6], S[blk][s8 + 7])}); }
;                 __builtin_amdgcn_sched_barrier(0);
; #pragma unroll
;                 for (int ks = 0; ks < 2; ++ks) o = __builtin_amdgcn_mfma_f32_32x32x16_bf16(pf[ks], vf[ks], o, 0, 0, 0);
;                 { f32x16 o2;
; #pragma unroll
;                   for (int r = 0; r < 16; ++r) o2[r] = 0.f;
; #pragma unroll
;                   for (int ks = 0; ks < 4; ++ks) { o = __builtin_amdgcn_mfma_f32_32x32x16_bf16(qf[2 * ks], sf[2 * ks], o, 0, 0, 0); o2 = __builtin_amdgcn_mfma_f32_32x32x16_bf16(qf[2 * ks + 1], sf[2 * ks + 1], o2, 0, 0, 0); }
;                   o = o + o2; }
.LBB0_1308:
	s_and_b32 s2, s56, 0xff
	s_mulk_i32 s2, 0xab
	s_lshr_b32 s2, s2, 9
	s_mul_i32 s2, s2, 3
	s_sub_i32 s2, s56, s2
	s_and_b32 s2, s2, 0xff
	s_mul_i32 s3, s2, 0x7800
	s_and_b32 s2, s56, 1
	s_add_i32 s3, s3, 0
	s_mul_i32 s49, s2, 0xa00
	v_add_u32_e32 v2, s49, v146
	v_add_u32_e32 v68, s3, v147
	v_add3_u32 v72, v68, v148, v150
	ds_read_b128 v[68:71], v2
	ds_read_b128 v[84:87], v2 offset:32
	ds_read_b64_tr_b16 v[124:125], v72 offset:27648
	ds_read_b64_tr_b16 v[126:127], v72 offset:27904
	ds_read_b64_tr_b16 v[120:121], v72 offset:28672
	ds_read_b64_tr_b16 v[122:123], v72 offset:28928
	v_add3_u32 v2, s3, v138, v143
	v_add_u32_e32 v2, 0x2000, v2
	ds_read2_b64 v[88:91], v2 offset0:64 offset1:66
	ds_read2_b64 v[92:95], v2 offset0:68 offset1:70
	ds_read2_b64 v[164:167], v2 offset0:72 offset1:74
	ds_read2_b64 v[172:175], v2 offset0:76 offset1:78
	ds_read2_b64 v[180:183], v2 offset0:80 offset1:82
	ds_read2_b64 v[192:195], v2 offset0:84 offset1:86
	ds_read2_b64 v[200:203], v2 offset0:88 offset1:90
	ds_read2_b64 v[208:211], v2 offset0:92 offset1:94
	v_add_u32_e32 v248, s3, v140
	v_add_u32_e32 v249, v248, v142
	ds_read_b128 v[100:103], v248 offset:30208
	ds_read_b128 v[104:107], v248 offset:30240
	ds_read_b128 v[108:111], v248 offset:30272
	ds_read_b128 v[112:115], v248 offset:30304
	ds_read_b128 v[216:219], v248 offset:30336
	ds_read_b128 v[220:223], v248 offset:30368
	ds_read_b128 v[224:227], v248 offset:30400
	ds_read_b128 v[228:231], v248 offset:30432
	ds_read_b128 v[232:235], v249 offset:17408
	ds_read_b128 v[236:239], v249 offset:17440
	ds_read_b128 v[240:243], v249 offset:19968
	ds_read_b128 v[244:247], v249 offset:20000
	v_cvt_pk_bf16_f32 v96, v4, v5
	v_cvt_pk_bf16_f32 v97, v6, v7
	v_cvt_pk_bf16_f32 v98, v8, v9
	v_cvt_pk_bf16_f32 v99, v10, v11
	v_cvt_pk_bf16_f32 v160, v12, v13
	v_cvt_pk_bf16_f32 v161, v14, v15
	v_cvt_pk_bf16_f32 v162, v16, v17
	v_cvt_pk_bf16_f32 v163, v18, v19
	v_cvt_pk_bf16_f32 v168, v20, v21
	v_cvt_pk_bf16_f32 v169, v22, v23
	v_cvt_pk_bf16_f32 v170, v24, v25
	v_cvt_pk_bf16_f32 v171, v26, v27
	v_cvt_pk_bf16_f32 v176, v28, v29
	v_cvt_pk_bf16_f32 v177, v30, v31
	v_cvt_pk_bf16_f32 v178, v32, v33
	v_cvt_pk_bf16_f32 v179, v34, v35
	v_cvt_pk_bf16_f32 v188, v36, v37
	v_cvt_pk_bf16_f32 v189, v38, v39
	v_cvt_pk_bf16_f32 v190, v40, v41
	v_cvt_pk_bf16_f32 v191, v42, v43
	v_cvt_pk_bf16_f32 v196, v44, v45
	v_cvt_pk_bf16_f32 v197, v46, v47
	v_cvt_pk_bf16_f32 v198, v48, v49
	v_cvt_pk_bf16_f32 v199, v50, v51
	v_cvt_pk_bf16_f32 v204, v52, v53
	v_cvt_pk_bf16_f32 v205, v54, v55
	v_cvt_pk_bf16_f32 v206, v56, v57
	v_cvt_pk_bf16_f32 v207, v58, v59
	v_cvt_pk_bf16_f32 v212, v60, v61
	v_cvt_pk_bf16_f32 v213, v62, v63
	v_cvt_pk_bf16_f32 v214, v64, v65
	v_cvt_pk_bf16_f32 v215, v66, v67
	s_waitcnt lgkmcnt(15)
	v_mfma_f32_32x32x16_bf16 v[68:83], v[68:71], v[124:127], 0
	v_mfma_f32_32x32x16_bf16 v[68:83], v[84:87], v[120:123], v[68:83]
	v_mfma_f32_32x32x16_bf16 v[68:83], v[88:91], v[96:99], v[68:83]
	s_waitcnt lgkmcnt(11)
	v_mul_f32_e32 v4, v4, v100
	v_mul_f32_e32 v5, v5, v101
	v_mul_f32_e32 v6, v6, v102
	v_mul_f32_e32 v7, v7, v103
	v_mfma_f32_32x32x16_bf16 v[84:99], v[92:95], v[160:163], 0
	s_waitcnt lgkmcnt(10)
	v_mul_f32_e32 v8, v8, v104
	v_mul_f32_e32 v9, v9, v105
	v_mul_f32_e32 v10, v10, v106
	v_mul_f32_e32 v11, v11, v107
	v_mfma_f32_32x32x16_bf16 v[68:83], v[164:167], v[168:171], v[68:83]
	s_waitcnt lgkmcnt(9)
	v_mul_f32_e32 v12, v12, v108
	v_mul_f32_e32 v13, v13, v109
	v_mul_f32_e32 v14, v14, v110
	v_mul_f32_e32 v15, v15, v111
	v_mfma_f32_32x32x16_bf16 v[84:99], v[172:175], v[176:179], v[84:99]
	ds_read_b128 v[164:167], v248 offset:30464
	ds_read_b128 v[168:171], v248 offset:30496
	ds_read_b128 v[172:175], v248 offset:30528
	ds_read_b128 v[176:179], v248 offset:30560
	s_waitcnt lgkmcnt(12)
; #define LAS __attribute__((address_space(3)))
; __device__ __forceinline__ void phase_hgrn_scan(LAS unsigned char* lds, unsigned char* ws, const float* scratch) {
;     ...
; #pragma unroll
;                 for (int hb = 0; hb < 2; ++hb) {
;                     bf16x8 af[2][2]; f32x16 dvec[2];
; #pragma unroll
;                     for (int bi = 0; bi < 2; ++bi) { const int blk = 2 * hb + bi;
; #pragma unroll
;                         for (int ks = 0; ks < 2; ++ks) af[bi][ks] = *(const LAS bf16x8*)(bp + O_KOT + (32 * blk + c) * 80 + (16 * ks + 8 * hh) * 2);
; #pragma unroll
;                         for (int g4 = 0; g4 < 4; ++g4) { const f32x4 dv = *(const LAS f32x4*)(bp + O_DEC + (32 * blk + 8 * g4 + 4 * hh) * 4);
;                             dvec[bi][4 * g4 + 0] = dv.x; dvec[bi][4 * g4 + 1] = dv.y; dvec[bi][4 * g4 + 2] = dv.z; dvec[bi][4 * g4 + 3] = dv.w; }
;                     }
;                     __builtin_amdgcn_sched_barrier(0);
; #pragma unroll
;                     for (int bi = 0; bi < 2; ++bi) S[2 * hb + bi] = S[2 * hb + bi] * dvec[bi];
; #pragma unroll
;                     for (int ks = 0; ks < 2; ++ks)
; #pragma unroll
;                         for (int bi = 0; bi < 2; ++bi) S[2 * hb + bi] = __builtin_amdgcn_mfma_f32_32x32x16_bf16(af[bi][ks], vf[ks], S[2 * hb + bi], 0, 0, 0);
;                     __builtin_amdgcn_sched_barrier(0);
;                     if (hb == 0) {
; #pragma unroll
;                         for (int r = 0; r < 16; ++r) { const float ov = o[r]; *(LAS float*)(lds + O_OB + (n & 1) * 4096 + ((r & 3) + 8 * (r >> 2) + 4 * hh) * 128 + 4 * c) = ov; }
;                     }
	v_mul_f32_e32 v16, v16, v112
	v_mul_f32_e32 v17, v17, v113
	v_mul_f32_e32 v18, v18, v114
	v_mul_f32_e32 v19, v19, v115
	v_mfma_f32_32x32x16_bf16 v[68:83], v[180:183], v[188:191], v[68:83]
	s_waitcnt lgkmcnt(11)
	v_mul_f32_e32 v20, v20, v216
	v_mul_f32_e32 v21, v21, v217
	v_mul_f32_e32 v22, v22, v218
	v_mul_f32_e32 v23, v23, v219
	v_mfma_f32_32x32x16_bf16 v[84:99], v[192:195], v[196:199], v[84:99]
	ds_read_b128 v[180:183], v248 offset:30592
	ds_read_b128 v[188:191], v248 offset:30624
	ds_read_b128 v[192:195], v248 offset:30656
	ds_read_b128 v[196:199], v248 offset:30688
	s_waitcnt lgkmcnt(14)
	v_mul_f32_e32 v24, v24, v220
	v_mul_f32_e32 v25, v25, v221
	v_mul_f32_e32 v26, v26, v222
	v_mul_f32_e32 v27, v27, v223
	v_mfma_f32_32x32x16_bf16 v[68:83], v[200:203], v[204:207], v[68:83]
	s_waitcnt lgkmcnt(13)
	v_mul_f32_e32 v28, v28, v224
	v_mul_f32_e32 v29, v29, v225
	v_mul_f32_e32 v30, v30, v226
	v_mul_f32_e32 v31, v31, v227
	v_mfma_f32_32x32x16_bf16 v[84:99], v[208:211], v[212:215], v[84:99]
	ds_read_b128 v[200:203], v249 offset:22528
	ds_read_b128 v[204:207], v249 offset:22560
	ds_read_b128 v[208:211], v249 offset:25088
	ds_read_b128 v[212:215], v249 offset:25120
	s_waitcnt lgkmcnt(15)
	v_mul_f32_e32 v32, v32, v228
	v_mul_f32_e32 v33, v33, v229
	v_mul_f32_e32 v34, v34, v230
	v_mul_f32_e32 v35, v35, v231
	s_waitcnt lgkmcnt(12)
	v_mfma_f32_32x32x16_bf16 v[4:19], v[232:235], v[124:127], v[4:19]
	s_waitcnt lgkmcnt(8)
	v_mul_f32_e32 v36, v36, v164
	v_mul_f32_e32 v37, v37, v165
	v_mul_f32_e32 v38, v38, v166
	v_mul_f32_e32 v39, v39, v167
	v_mul_f32_e32 v40, v40, v168
	v_mul_f32_e32 v41, v41, v169
	v_mul_f32_e32 v42, v42, v170
	v_mul_f32_e32 v43, v43, v171
	v_mfma_f32_32x32x16_bf16 v[20:35], v[240:243], v[124:127], v[20:35]
	v_mul_f32_e32 v44, v44, v172
	v_mul_f32_e32 v45, v45, v173
	v_mul_f32_e32 v46, v46, v174
	v_mul_f32_e32 v47, v47, v175
	v_mul_f32_e32 v48, v48, v176
	v_mul_f32_e32 v49, v49, v177
	v_mul_f32_e32 v50, v50, v178
	v_mul_f32_e32 v51, v51, v179
	v_mfma_f32_32x32x16_bf16 v[4:19], v[236:239], v[120:123], v[4:19]
	s_waitcnt lgkmcnt(4)
	v_mul_f32_e32 v52, v52, v180
	v_mul_f32_e32 v53, v53, v181
	v_mul_f32_e32 v54, v54, v182
	v_mul_f32_e32 v55, v55, v183
	v_mul_f32_e32 v56, v56, v188
	v_mul_f32_e32 v57, v57, v189
	v_mul_f32_e32 v58, v58, v190
	v_mul_f32_e32 v59, v59, v191
	v_mfma_f32_32x32x16_bf16 v[20:35], v[244:247], v[120:123], v[20:35]
	v_mul_f32_e32 v60, v60, v192
	v_mul_f32_e32 v61, v61, v193
	v_mul_f32_e32 v62, v62, v194
	v_mul_f32_e32 v63, v63, v195
	v_mul_f32_e32 v64, v64, v196
	v_mul_f32_e32 v65, v65, v197
	v_mul_f32_e32 v66, v66, v198
	v_mul_f32_e32 v67, v67, v199
	v_lshl_add_u32 v250, s2, 12, v149
	s_waitcnt lgkmcnt(0)
	v_mfma_f32_32x32x16_bf16 v[36:51], v[200:203], v[124:127], v[36:51]
	v_add_f32_e32 v68, v68, v84
	v_add_f32_e32 v69, v69, v85
	v_add_f32_e32 v70, v70, v86
	v_add_f32_e32 v71, v71, v87
	ds_write2_b32 v250, v68, v69 offset1:32
	ds_write2_b32 v250, v70, v71 offset0:64 offset1:96
	v_mfma_f32_32x32x16_bf16 v[52:67], v[208:211], v[124:127], v[52:67]
	v_add_f32_e32 v72, v72, v88
	v_add_f32_e32 v73, v73, v89
	v_add_f32_e32 v74, v74, v90
	v_add_f32_e32 v75, v75, v91
	v_add_u32_e32 v251, 0x400, v250
	ds_write2_b32 v251, v72, v73 offset1:32
	ds_write2_b32 v251, v74, v75 offset0:64 offset1:96
	v_mfma_f32_32x32x16_bf16 v[36:51], v[204:207], v[120:123], v[36:51]
	v_add_f32_e32 v76, v76, v92
	v_add_f32_e32 v77, v77, v93
	v_add_f32_e32 v78, v78, v94
	v_add_f32_e32 v79, v79, v95
	v_add_u32_e32 v251, 0x800, v250
	ds_write2_b32 v251, v76, v77 offset1:32
	ds_write2_b32 v251, v78, v79 offset0:64 offset1:96
	v_mfma_f32_32x32x16_bf16 v[52:67], v[212:215], v[120:123], v[52:67]
	v_add_f32_e32 v80, v80, v96
	v_add_f32_e32 v81, v81, v97
	v_add_f32_e32 v82, v82, v98
	v_add_f32_e32 v83, v83, v99
	v_add_u32_e32 v251, 0xc00, v250
	ds_write2_b32 v251, v80, v81 offset1:32
	ds_write2_b32 v251, v82, v83 offset0:64 offset1:96

; #define VLOADA(slot, ereg, lsel) { const int ea_ = __builtin_amdgcn_readlane((ereg), (lsel)), eb_ = __builtin_amdgcn_readlane((ereg), (lsel) + 1); const int el_ = hh ? eb_ : ea_; ring[slot] = *(const GAS v4u*)(V4 + (((unsigned)el_ << 9) + laneoff)); }
; template <bool FINAL>
; __device__ __forceinline__ void phase_gather_v_mfma(const bf16* X, const int* EID, const float* COEF, const unsigned char* V4, const float* g, const float* bb, bf16* Ob, float* Of) {
;     ...
;         unsigned short xs[16];
; #pragma unroll
;         for (int r = 0; r < 16; ++r) xs[r] = X[(size_t)t * D + 32 * ((r & 3) + 8 * (r >> 2) + 4 * hh) + n];
;         float cm = fmaxf(fabsf(c0), fabsf(c1));
; #pragma unroll
;         for (int o = 1; o < 64; o <<= 1) cm = fmaxf(cm, __shfl_xor(cm, o));
;         unsigned ex = (__float_as_uint(cm) >> 23) & 0xffu; ex = ex < 8u ? 8u : ex;
;         const float S = __uint_as_float((261u - ex) << 23), invS = __uint_as_float((ex - 7u) << 23);
;         const unsigned wq = (unsigned)__builtin_amdgcn_cvt_pk_fp8_f32(c0 * S, c1 * S, 0, false);
;         const int rep0 = (int)((wq & 0xffu) * 0x01010101u), rep1 = (int)(((wq >> 8) & 0xffu) * 0x01010101u);
;         f32x16 acc;
; #pragma unroll
;         for (int r = 0; r < 16; ++r) acc[r] = 0.f;
; #pragma unroll
;         for (int J = 0; J < 64; ++J) {
;             const int ra = __builtin_amdgcn_readlane((J >> 5) ? rep1 : rep0, (2 * J) & 63), rb = __builtin_amdgcn_readlane((J >> 5) ? rep1 : rep0, ((2 * J) & 63) + 1);
;             v8i A, B;
;             A[0] = (int)ring[J & 15].x; A[1] = (int)ring[J & 15].y; A[2] = (int)ring[J & 15].z; A[3] = (int)ring[J & 15].w; A[4] = 0; A[5] = 0; A[6] = 0; A[7] = 0;
; #pragma unroll
;             for (int d = 0; d < 4; ++d) { B[d] = ra & (int)mask[d]; B[4 + d] = rb & (int)mask[d]; }
;             acc = __builtin_amdgcn_mfma_scale_f32_32x32x64_f8f6f4(A, B, acc, 4, 0, 0, 0x7f7f7f7f, 0, 0x7f7f7f7f);
;             if (J + 16 < 64) { VLOADA(J & 15, ((J + 16) >> 5) ? e1 : e0, (2 * (J + 16)) & 63) }
;             else { VLOADA(J & 15, ne0, 2 * (J + 16 - 64)) }
;             if ((J & 3) == 3) __builtin_amdgcn_sched_barrier(0);
.LBB0_2006:
	s_waitcnt vmcnt(16)
	v_max_f32_e64 v4, |v3|, |v3|
	v_max_f32_e64 v5, |v2|, |v2|
	v_max_f32_e32 v4, v5, v4
	v_mov_b32_e32 v183, 0
	v_readlane_b32 s0, v102, 32
	v_readlane_b32 s1, v102, 33
	v_readlane_b32 s9, v102, 34
	v_mov_b32_e32 v82, s1
	v_mov_b32_e32 v83, s0
	v_readlane_b32 s13, v102, 35
	v_readlane_b32 s24, v102, 36
	v_readlane_b32 s25, v102, 37
	v_readlane_b32 s26, v102, 38
	v_readlane_b32 s27, v102, 39
	v_mov_b32_e32 v84, s13
	v_mov_b32_e32 v85, s9
	v_mov_b32_e32 v86, s25
	v_mov_b32_e32 v87, s24
	v_mov_b32_e32 v88, s27
	v_lshl_add_u64 v[90:91], s[82:83], 0, v[114:115]
	s_nop 1
	v_max_f32_dpp v4, v4, v4 row_shr:1 row_mask:0xf bank_mask:0xf
	s_nop 1
	v_max_f32_dpp v4, v4, v4 row_shr:2 row_mask:0xf bank_mask:0xf
	s_nop 1
	v_max_f32_dpp v4, v4, v4 row_shr:4 row_mask:0xf bank_mask:0xf
	s_nop 1
	v_max_f32_dpp v4, v4, v4 row_shr:8 row_mask:0xf bank_mask:0xf
	s_nop 1
	v_max_f32_dpp v4, v4, v4 row_bcast:15 row_mask:0xa bank_mask:0xf
	s_nop 1
	v_max_f32_dpp v4, v4, v4 row_bcast:31 row_mask:0xc bank_mask:0xf
	s_nop 0
	v_readlane_b32 s98, v4, 63
	s_nop 1
	v_mov_b32_e32 v4, s98
	v_bfe_u32 v4, v4, 23, 8
	v_max_u32_e32 v4, 8, v4
	v_lshlrev_b32_e32 v92, 23, v4
	v_sub_u32_e32 v4, 0x82800000, v92
	v_mul_f32_e32 v3, v3, v4
	v_mul_f32_e32 v2, v2, v4
	v_cvt_pk_fp8_f32 v183, v2, v3
	v_add_u32_e32 v165, 0xfc800000, v92
	v_and_b32_e32 v2, 0xff, v183
	v_mul_lo_u32 v184, v2, s2
	s_nop 0
	v_readlane_b32 s0, v184, 0
	v_readlane_b32 s1, v184, 1
	s_nop 0
	v_and_b32_e32 v2, s0, v148
	v_and_b32_e32 v6, s1, v148
	v_and_b32_e32 v3, s0, v149
	v_and_b32_e32 v7, s1, v149
	v_and_b32_e32 v4, s0, v150
	v_and_b32_e32 v8, s1, v150
	v_and_b32_e32 v5, s0, v151
	v_and_b32_e32 v9, s1, v151
	v_readlane_b32 s0, v184, 2
	v_readlane_b32 s1, v184, 3
	s_waitcnt vmcnt(15)
	v_mfma_scale_f32_32x32x64_f8f6f4 v[2:17], v[22:25], v[2:9], 0, v158, v158 op_sel_hi:[0,0,0] cbsz:4
	v_mov_b32_e32 v22, s26
	v_cndmask_b32_e64 v23, v82, v83, s[4:5]
	v_cndmask_b32_e64 v24, v84, v85, s[4:5]
	v_cndmask_b32_e64 v25, v86, v87, s[4:5]
	v_cndmask_b32_e64 v93, v88, v22, s[4:5]
	v_and_b32_e32 v82, s0, v148
	v_and_b32_e32 v86, s1, v148
	v_and_b32_e32 v83, s0, v149
	v_and_b32_e32 v87, s1, v149
	v_and_b32_e32 v84, s0, v150
	v_and_b32_e32 v88, s1, v150
	v_and_b32_e32 v85, s0, v151
	v_and_b32_e32 v89, s1, v151
	v_readlane_b32 s0, v184, 4
	v_readlane_b32 s1, v184, 5
	s_waitcnt vmcnt(14)
	v_mfma_scale_f32_32x32x64_f8f6f4 v[2:17], v[18:21], v[82:89], v[2:17], v158, v158 op_sel_hi:[0,0,0] cbsz:4
	v_lshl_or_b32 v18, v23, 9, v1
	v_lshl_or_b32 v19, v24, 9, v1
	v_lshl_or_b32 v86, v25, 9, v1
	global_load_dwordx4 v[106:109], v18, s[10:11]
	global_load_dwordx4 v[82:85], v19, s[10:11]
	v_and_b32_e32 v18, s0, v148
	v_and_b32_e32 v22, s1, v148
	v_and_b32_e32 v19, s0, v149
	v_and_b32_e32 v23, s1, v149
	v_and_b32_e32 v20, s0, v150
	v_and_b32_e32 v24, s1, v150
	v_and_b32_e32 v21, s0, v151
	v_and_b32_e32 v25, s1, v151
	v_readlane_b32 s0, v184, 6
	v_readlane_b32 s1, v184, 7
	s_waitcnt vmcnt(15)
	v_mfma_scale_f32_32x32x64_f8f6f4 v[2:17], v[30:33], v[18:25], v[2:17], v158, v158 op_sel_hi:[0,0,0] cbsz:4
	v_lshl_or_b32 v18, v93, 9, v1
	global_load_dwordx4 v[22:25], v86, s[10:11]
	s_nop 0
	global_load_dwordx4 v[18:21], v18, s[10:11]
	s_nop 0
	global_load_ushort v182, v[90:91], off offset:-1024 nt
	global_load_ushort v181, v[90:91], off offset:-960 nt
	global_load_ushort v180, v[90:91], off offset:-896 nt
	global_load_ushort v179, v[90:91], off offset:-832 nt
	global_load_ushort v178, v[90:91], off offset:-512 nt
	global_load_ushort v177, v[90:91], off offset:-448 nt
	global_load_ushort v176, v[90:91], off offset:-384 nt
	global_load_ushort v175, v[90:91], off offset:-320 nt
	global_load_ushort v173, v[90:91], off nt
	global_load_ushort v172, v[90:91], off offset:64 nt
	global_load_ushort v171, v[90:91], off offset:128 nt
	global_load_ushort v170, v[90:91], off offset:192 nt
	global_load_ushort v169, v[90:91], off offset:512 nt
	global_load_ushort v168, v[90:91], off offset:576 nt
	global_load_ushort v167, v[90:91], off offset:640 nt
	global_load_ushort v166, v[90:91], off offset:704 nt
	v_and_b32_e32 v86, s0, v148
	v_and_b32_e32 v90, s1, v148
	v_and_b32_e32 v87, s0, v149
	v_and_b32_e32 v91, s1, v149
	v_and_b32_e32 v88, s0, v150
	v_and_b32_e32 v92, s1, v150
	v_and_b32_e32 v89, s0, v151
	v_and_b32_e32 v93, s1, v151
	s_waitcnt vmcnt(32)
	s_nop 0
	v_mfma_scale_f32_32x32x64_f8f6f4 v[2:17], v[26:29], v[86:93], v[2:17], v158, v158 op_sel_hi:[0,0,0] cbsz:4
	v_readlane_b32 s0, v184, 8
	v_readlane_b32 s1, v184, 9
	s_nop 0
	v_and_b32_e32 v26, s0, v148
	v_and_b32_e32 v30, s1, v148
	v_and_b32_e32 v27, s0, v149
	v_and_b32_e32 v31, s1, v149
	v_and_b32_e32 v28, s0, v150
	v_and_b32_e32 v32, s1, v150
	v_and_b32_e32 v29, s0, v151
	v_and_b32_e32 v33, s1, v151
	v_readlane_b32 s0, v102, 40
	v_readlane_b32 s1, v102, 41
	s_waitcnt vmcnt(31)
	v_mfma_scale_f32_32x32x64_f8f6f4 v[2:17], v[42:45], v[26:33], v[2:17], v158, v158 op_sel_hi:[0,0,0] cbsz:4
	v_mov_b32_e32 v87, s0
	v_mov_b32_e32 v86, s1
	v_cndmask_b32_e64 v26, v86, v87, s[4:5]
	v_readlane_b32 s0, v184, 10
	v_readlane_b32 s1, v184, 11
	v_lshl_or_b32 v42, v26, 9, v1
	v_and_b32_e32 v26, s0, v148
	v_and_b32_e32 v30, s1, v148
	v_and_b32_e32 v27, s0, v149
	v_and_b32_e32 v31, s1, v149
	v_and_b32_e32 v28, s0, v150
	v_and_b32_e32 v32, s1, v150
	v_and_b32_e32 v29, s0, v151
	v_and_b32_e32 v33, s1, v151
	v_readlane_b32 s0, v102, 42
	v_readlane_b32 s1, v102, 43
	s_waitcnt vmcnt(30)
; #define VLOADA(slot, ereg, lsel) { const int ea_ = __builtin_amdgcn_readlane((ereg), (lsel)), eb_ = __builtin_amdgcn_readlane((ereg), (lsel) + 1); const int el_ = hh ? eb_ : ea_; ring[slot] = *(const GAS v4u*)(V4 + (((unsigned)el_ << 9) + laneoff)); }
; template <bool FINAL>
; __device__ __forceinline__ void phase_gather_v_mfma(const bf16* X, const int* EID, const float* COEF, const unsigned char* V4, const float* g, const float* bb, bf16* Ob, float* Of) {
;     ...
;         for (int J = 0; J < 64; ++J) {
;             const int ra = __builtin_amdgcn_readlane((J >> 5) ? rep1 : rep0, (2 * J) & 63), rb = __builtin_amdgcn_readlane((J >> 5) ? rep1 : rep0, ((2 * J) & 63) + 1);
;             v8i A, B;
;             A[0] = (int)ring[J & 15].x; A[1] = (int)ring[J & 15].y; A[2] = (int)ring[J & 15].z; A[3] = (int)ring[J & 15].w; A[4] = 0; A[5] = 0; A[6] = 0; A[7] = 0;
; #pragma unroll
;             for (int d = 0; d < 4; ++d) { B[d] = ra & (int)mask[d]; B[4 + d] = rb & (int)mask[d]; }
;             acc = __builtin_amdgcn_mfma_scale_f32_32x32x64_f8f6f4(A, B, acc, 4, 0, 0, 0x7f7f7f7f, 0, 0x7f7f7f7f);
;             if (J + 16 < 64) { VLOADA(J & 15, ((J + 16) >> 5) ? e1 : e0, (2 * (J + 16)) & 63) }
;             else { VLOADA(J & 15, ne0, 2 * (J + 16 - 64)) }
;             if ((J & 3) == 3) __builtin_amdgcn_sched_barrier(0);
	v_mfma_scale_f32_32x32x64_f8f6f4 v[2:17], v[34:37], v[26:33], v[2:17], v158, v158 op_sel_hi:[0,0,0] cbsz:4
	v_mov_b32_e32 v26, s0
	v_mov_b32_e32 v43, s1
	v_cndmask_b32_e64 v26, v43, v26, s[4:5]
	v_lshl_or_b32 v26, v26, 9, v1
	v_readlane_b32 s0, v184, 12
	v_readlane_b32 s1, v184, 13
	global_load_dwordx4 v[86:89], v42, s[10:11]
	s_nop 0
	global_load_dwordx4 v[42:45], v26, s[10:11]
	v_and_b32_e32 v26, s0, v148
	v_and_b32_e32 v30, s1, v148
	v_and_b32_e32 v27, s0, v149
	v_and_b32_e32 v31, s1, v149
	v_and_b32_e32 v28, s0, v150
	v_and_b32_e32 v32, s1, v150
	v_and_b32_e32 v29, s0, v151
	v_and_b32_e32 v33, s1, v151
	v_readlane_b32 s0, v102, 44
	v_readlane_b32 s1, v102, 45
	s_waitcnt vmcnt(31)
	v_mfma_scale_f32_32x32x64_f8f6f4 v[2:17], v[54:57], v[26:33], v[2:17], v158, v158 op_sel_hi:[0,0,0] cbsz:4
	v_mov_b32_e32 v27, s0
	v_mov_b32_e32 v26, s1
	v_readlane_b32 s0, v102, 46
	v_readlane_b32 s1, v102, 47
	v_cndmask_b32_e64 v26, v26, v27, s[4:5]
	v_mov_b32_e32 v28, s0
	v_mov_b32_e32 v27, s1
	v_cndmask_b32_e64 v27, v27, v28, s[4:5]
	v_lshl_or_b32 v26, v26, 9, v1
	v_lshl_or_b32 v27, v27, 9, v1
	global_load_dwordx4 v[94:97], v26, s[10:11]
	s_nop 0
	global_load_dwordx4 v[26:29], v27, s[10:11]
	v_readlane_b32 s0, v184, 14
	v_readlane_b32 s1, v184, 15
	s_nop 0
	v_and_b32_e32 v30, s0, v148
	v_and_b32_e32 v34, s1, v148
	v_and_b32_e32 v31, s0, v149
	v_and_b32_e32 v35, s1, v149
	v_and_b32_e32 v32, s0, v150
	v_and_b32_e32 v36, s1, v150
	v_and_b32_e32 v33, s0, v151
	v_and_b32_e32 v37, s1, v151
	s_waitcnt vmcnt(32)
	s_nop 0
	v_mfma_scale_f32_32x32x64_f8f6f4 v[2:17], v[38:41], v[30:37], v[2:17], v158, v158 op_sel_hi:[0,0,0] cbsz:4
	v_readlane_b32 s0, v184, 16
	v_readlane_b32 s1, v184, 17
	s_nop 0
	v_and_b32_e32 v30, s0, v148
	v_and_b32_e32 v34, s1, v148
	v_and_b32_e32 v31, s0, v149
	v_and_b32_e32 v35, s1, v149
	v_and_b32_e32 v32, s0, v150
	v_and_b32_e32 v36, s1, v150
	v_and_b32_e32 v33, s0, v151
	v_and_b32_e32 v37, s1, v151
	v_readlane_b32 s0, v102, 48
	v_readlane_b32 s1, v102, 49
	s_waitcnt vmcnt(31)
	v_mfma_scale_f32_32x32x64_f8f6f4 v[2:17], v[58:61], v[30:37], v[2:17], v158, v158 op_sel_hi:[0,0,0] cbsz:4
	v_mov_b32_e32 v39, s0
	v_mov_b32_e32 v38, s1
	v_cndmask_b32_e64 v30, v38, v39, s[4:5]
	v_readlane_b32 s0, v184, 18
	v_readlane_b32 s1, v184, 19
	v_lshl_or_b32 v38, v30, 9, v1
	v_and_b32_e32 v30, s0, v148
	v_and_b32_e32 v34, s1, v148
	v_and_b32_e32 v31, s0, v149
	v_and_b32_e32 v35, s1, v149
	v_and_b32_e32 v32, s0, v150
	v_and_b32_e32 v36, s1, v150
	v_and_b32_e32 v33, s0, v151
	v_and_b32_e32 v37, s1, v151
	v_readlane_b32 s0, v102, 50
	v_readlane_b32 s1, v102, 51
	s_waitcnt vmcnt(30)
	v_mfma_scale_f32_32x32x64_f8f6f4 v[2:17], v[46:49], v[30:37], v[2:17], v158, v158 op_sel_hi:[0,0,0] cbsz:4
	v_mov_b32_e32 v30, s0
	v_mov_b32_e32 v39, s1
	v_cndmask_b32_e64 v30, v39, v30, s[4:5]
	v_lshl_or_b32 v30, v30, 9, v1
	v_readlane_b32 s0, v184, 20
	v_readlane_b32 s1, v184, 21
	global_load_dwordx4 v[90:93], v38, s[10:11]
	global_load_dwordx4 v[46:49], v30, s[10:11]
	v_and_b32_e32 v30, s0, v148
	v_and_b32_e32 v34, s1, v148
	v_and_b32_e32 v31, s0, v149
	v_and_b32_e32 v35, s1, v149
	v_and_b32_e32 v32, s0, v150
	v_and_b32_e32 v36, s1, v150
	v_and_b32_e32 v33, s0, v151
	v_and_b32_e32 v37, s1, v151
	v_readlane_b32 s0, v102, 52
	v_readlane_b32 s1, v102, 53
	s_waitcnt vmcnt(31)
	v_mfma_scale_f32_32x32x64_f8f6f4 v[2:17], v[70:73], v[30:37], v[2:17], v158, v158 op_sel_hi:[0,0,0] cbsz:4
	v_mov_b32_e32 v31, s0
	v_mov_b32_e32 v30, s1
	v_readlane_b32 s0, v102, 54
	v_readlane_b32 s1, v102, 55
	v_cndmask_b32_e64 v30, v30, v31, s[4:5]
	v_mov_b32_e32 v32, s0
	v_mov_b32_e32 v31, s1
	v_cndmask_b32_e64 v31, v31, v32, s[4:5]
	v_lshl_or_b32 v30, v30, 9, v1
	v_lshl_or_b32 v31, v31, 9, v1
	global_load_dwordx4 v[98:101], v30, s[10:11]
	s_nop 0
	global_load_dwordx4 v[30:33], v31, s[10:11]
	v_readlane_b32 s0, v184, 22
	v_readlane_b32 s1, v184, 23
	s_nop 0
	v_and_b32_e32 v34, s0, v148
	v_and_b32_e32 v38, s1, v148
	v_and_b32_e32 v35, s0, v149
	v_and_b32_e32 v39, s1, v149
	v_and_b32_e32 v36, s0, v150
	v_and_b32_e32 v40, s1, v150
	v_and_b32_e32 v37, s0, v151
	v_and_b32_e32 v41, s1, v151
	s_waitcnt vmcnt(32)
	s_nop 0
	v_mfma_scale_f32_32x32x64_f8f6f4 v[2:17], v[50:53], v[34:41], v[2:17], v158, v158 op_sel_hi:[0,0,0] cbsz:4
	v_readlane_b32 s0, v184, 24
	v_readlane_b32 s1, v184, 25
	s_nop 0
	v_and_b32_e32 v34, s0, v148
	v_and_b32_e32 v38, s1, v148
	v_and_b32_e32 v35, s0, v149
	v_and_b32_e32 v39, s1, v149
	v_and_b32_e32 v36, s0, v150
	v_and_b32_e32 v40, s1, v150
	v_and_b32_e32 v37, s0, v151
	v_and_b32_e32 v41, s1, v151
	v_readlane_b32 s0, v102, 56
	v_readlane_b32 s1, v102, 57
	s_waitcnt vmcnt(31)
	v_mfma_scale_f32_32x32x64_f8f6f4 v[2:17], v[74:77], v[34:41], v[2:17], v158, v158 op_sel_hi:[0,0,0] cbsz:4
	v_mov_b32_e32 v51, s0
	v_mov_b32_e32 v50, s1
	v_cndmask_b32_e64 v34, v50, v51, s[4:5]
	v_readlane_b32 s0, v184, 26
	v_readlane_b32 s1, v184, 27
	v_lshl_or_b32 v50, v34, 9, v1
	v_and_b32_e32 v34, s0, v148
	v_and_b32_e32 v38, s1, v148
	v_and_b32_e32 v35, s0, v149
	v_and_b32_e32 v39, s1, v149
	v_and_b32_e32 v36, s0, v150
	v_and_b32_e32 v40, s1, v150
	v_and_b32_e32 v37, s0, v151
	v_and_b32_e32 v41, s1, v151
	v_readlane_b32 s0, v102, 58
	v_readlane_b32 s1, v102, 59
	s_waitcnt vmcnt(30)
	v_mfma_scale_f32_32x32x64_f8f6f4 v[2:17], v[62:65], v[34:41], v[2:17], v158, v158 op_sel_hi:[0,0,0] cbsz:4
	v_mov_b32_e32 v34, s0
	v_mov_b32_e32 v51, s1
	v_cndmask_b32_e64 v34, v51, v34, s[4:5]
	v_lshl_or_b32 v34, v34, 9, v1
	v_readlane_b32 s0, v184, 28
	v_readlane_b32 s1, v184, 29
	global_load_dwordx4 v[70:73], v50, s[10:11]
	s_nop 0
	global_load_dwordx4 v[50:53], v34, s[10:11]
	v_and_b32_e32 v34, s0, v148
	v_and_b32_e32 v38, s1, v148
	v_and_b32_e32 v35, s0, v149
	v_and_b32_e32 v39, s1, v149
	v_and_b32_e32 v36, s0, v150
	v_and_b32_e32 v40, s1, v150
	v_and_b32_e32 v37, s0, v151
	v_and_b32_e32 v41, s1, v151
	v_readlane_b32 s0, v102, 60
	v_readlane_b32 s1, v102, 61
	s_waitcnt vmcnt(31)
; #define VLOADA(slot, ereg, lsel) { const int ea_ = __builtin_amdgcn_readlane((ereg), (lsel)), eb_ = __builtin_amdgcn_readlane((ereg), (lsel) + 1); const int el_ = hh ? eb_ : ea_; ring[slot] = *(const GAS v4u*)(V4 + (((unsigned)el_ << 9) + laneoff)); }
; template <bool FINAL>
; __device__ __forceinline__ void phase_gather_v_mfma(const bf16* X, const int* EID, const float* COEF, const unsigned char* V4, const float* g, const float* bb, bf16* Ob, float* Of) {
;     ...
;         for (int J = 0; J < 64; ++J) {
;             const int ra = __builtin_amdgcn_readlane((J >> 5) ? rep1 : rep0, (2 * J) & 63), rb = __builtin_amdgcn_readlane((J >> 5) ? rep1 : rep0, ((2 * J) & 63) + 1);
;             v8i A, B;
;             A[0] = (int)ring[J & 15].x; A[1] = (int)ring[J & 15].y; A[2] = (int)ring[J & 15].z; A[3] = (int)ring[J & 15].w; A[4] = 0; A[5] = 0; A[6] = 0; A[7] = 0;
; #pragma unroll
;             for (int d = 0; d < 4; ++d) { B[d] = ra & (int)mask[d]; B[4 + d] = rb & (int)mask[d]; }
;             acc = __builtin_amdgcn_mfma_scale_f32_32x32x64_f8f6f4(A, B, acc, 4, 0, 0, 0x7f7f7f7f, 0, 0x7f7f7f7f);
;             if (J + 16 < 64) { VLOADA(J & 15, ((J + 16) >> 5) ? e1 : e0, (2 * (J + 16)) & 63) }
;             else { VLOADA(J & 15, ne0, 2 * (J + 16 - 64)) }
;             if ((J & 3) == 3) __builtin_amdgcn_sched_barrier(0);
	v_mfma_scale_f32_32x32x64_f8f6f4 v[2:17], v[78:81], v[34:41], v[2:17], v158, v158 op_sel_hi:[0,0,0] cbsz:4
	v_mov_b32_e32 v35, s0
	v_mov_b32_e32 v34, s1
	v_readlane_b32 s0, v102, 62
	v_readlane_b32 s1, v102, 63
	v_cndmask_b32_e64 v34, v34, v35, s[4:5]
	v_mov_b32_e32 v36, s0
	v_mov_b32_e32 v35, s1
	v_cndmask_b32_e64 v35, v35, v36, s[4:5]
	v_lshl_or_b32 v34, v34, 9, v1
	v_lshl_or_b32 v35, v35, 9, v1
	global_load_dwordx4 v[102:105], v34, s[10:11]
	s_nop 0
	global_load_dwordx4 v[34:37], v35, s[10:11]
	v_readlane_b32 s0, v184, 30
	v_readlane_b32 s1, v184, 31
	s_nop 0
	v_and_b32_e32 v54, s0, v148
	v_and_b32_e32 v58, s1, v148
	v_and_b32_e32 v55, s0, v149
	v_and_b32_e32 v59, s1, v149
	v_and_b32_e32 v56, s0, v150
	v_and_b32_e32 v60, s1, v150
	v_and_b32_e32 v57, s0, v151
	v_and_b32_e32 v61, s1, v151
	s_waitcnt vmcnt(32)
	s_nop 0
	v_mfma_scale_f32_32x32x64_f8f6f4 v[2:17], v[66:69], v[54:61], v[2:17], v158, v158 op_sel_hi:[0,0,0] cbsz:4
	v_readlane_b32 s0, v184, 32
	v_readlane_b32 s1, v184, 33
	s_nop 0
	v_and_b32_e32 v54, s0, v148
	v_and_b32_e32 v58, s1, v148
	v_and_b32_e32 v55, s0, v149
	v_and_b32_e32 v59, s1, v149
	v_and_b32_e32 v56, s0, v150
	v_and_b32_e32 v60, s1, v150
	v_and_b32_e32 v57, s0, v151
	v_and_b32_e32 v61, s1, v151
	v_readlane_b32 s0, v174, 0
	v_readlane_b32 s1, v174, 1
	s_waitcnt vmcnt(31)
	v_mfma_scale_f32_32x32x64_f8f6f4 v[2:17], v[106:109], v[54:61], v[2:17], v158, v158 op_sel_hi:[0,0,0] cbsz:4
	v_mov_b32_e32 v39, s0
	v_mov_b32_e32 v38, s1
	v_readlane_b32 s0, v184, 34
	v_readlane_b32 s1, v184, 35
	v_cndmask_b32_e64 v38, v38, v39, s[4:5]
	v_and_b32_e32 v54, s0, v148
	v_and_b32_e32 v58, s1, v148
	v_and_b32_e32 v55, s0, v149
	v_and_b32_e32 v59, s1, v149
	v_and_b32_e32 v56, s0, v150
	v_and_b32_e32 v60, s1, v150
	v_and_b32_e32 v57, s0, v151
	v_and_b32_e32 v61, s1, v151
	v_readlane_b32 s0, v174, 2
	v_readlane_b32 s1, v174, 3
	s_waitcnt vmcnt(30)
	v_mfma_scale_f32_32x32x64_f8f6f4 v[2:17], v[82:85], v[54:61], v[2:17], v158, v158 op_sel_hi:[0,0,0] cbsz:4
	v_mov_b32_e32 v40, s0
	v_mov_b32_e32 v39, s1
	v_readlane_b32 s0, v184, 36
	v_readlane_b32 s1, v184, 37
	v_lshl_or_b32 v38, v38, 9, v1
	v_and_b32_e32 v58, s0, v148
	v_and_b32_e32 v62, s1, v148
	v_and_b32_e32 v59, s0, v149
	v_and_b32_e32 v63, s1, v149
	v_and_b32_e32 v60, s0, v150
	v_and_b32_e32 v64, s1, v150
	v_and_b32_e32 v61, s0, v151
	v_and_b32_e32 v65, s1, v151
	v_readlane_b32 s0, v174, 4
	v_readlane_b32 s1, v174, 5
	s_waitcnt vmcnt(29)
	v_mfma_scale_f32_32x32x64_f8f6f4 v[2:17], v[22:25], v[58:65], v[2:17], v158, v158 op_sel_hi:[0,0,0] cbsz:4
	v_mov_b32_e32 v23, s0
	v_mov_b32_e32 v22, s1
	v_readlane_b32 s0, v174, 6
	v_readlane_b32 s1, v174, 7
	v_cndmask_b32_e64 v22, v22, v23, s[4:5]
	v_mov_b32_e32 v24, s0
	v_mov_b32_e32 v23, s1
	v_cndmask_b32_e64 v23, v23, v24, s[4:5]
	v_cndmask_b32_e64 v39, v39, v40, s[4:5]
	v_lshl_or_b32 v22, v22, 9, v1
	v_lshl_or_b32 v23, v23, 9, v1
	v_lshl_or_b32 v39, v39, 9, v1
	global_load_dwordx4 v[74:77], v38, s[10:11]
	global_load_dwordx4 v[54:57], v39, s[10:11]
	global_load_dwordx4 v[78:81], v22, s[10:11]
	s_nop 0
	global_load_dwordx4 v[22:25], v23, s[10:11]
	v_readlane_b32 s0, v184, 38
	v_readlane_b32 s1, v184, 39
	s_nop 0
	v_and_b32_e32 v58, s0, v148
	v_and_b32_e32 v62, s1, v148
	v_and_b32_e32 v59, s0, v149
	v_and_b32_e32 v63, s1, v149
	v_and_b32_e32 v60, s0, v150
	v_and_b32_e32 v64, s1, v150
	v_and_b32_e32 v61, s0, v151
	v_and_b32_e32 v65, s1, v151
	s_waitcnt vmcnt(32)
	s_nop 0
	v_mfma_scale_f32_32x32x64_f8f6f4 v[2:17], v[18:21], v[58:65], v[2:17], v158, v158 op_sel_hi:[0,0,0] cbsz:4
	v_readlane_b32 s0, v184, 40
	v_readlane_b32 s1, v184, 41
	s_nop 0
	v_and_b32_e32 v58, s0, v148
	v_and_b32_e32 v62, s1, v148
	v_and_b32_e32 v59, s0, v149
	v_and_b32_e32 v63, s1, v149
	v_and_b32_e32 v60, s0, v150
	v_and_b32_e32 v64, s1, v150
	v_and_b32_e32 v61, s0, v151
	v_and_b32_e32 v65, s1, v151
	v_readlane_b32 s0, v174, 8
	v_readlane_b32 s1, v174, 9
	s_waitcnt vmcnt(15)
	v_mfma_scale_f32_32x32x64_f8f6f4 v[2:17], v[86:89], v[58:65], v[2:17], v158, v158 op_sel_hi:[0,0,0] cbsz:4
	v_mov_b32_e32 v19, s0
	v_mov_b32_e32 v18, s1
	v_readlane_b32 s0, v184, 42
	v_readlane_b32 s1, v184, 43
	v_cndmask_b32_e64 v18, v18, v19, s[4:5]
	v_and_b32_e32 v58, s0, v148
	v_and_b32_e32 v62, s1, v148
	v_and_b32_e32 v59, s0, v149
	v_and_b32_e32 v63, s1, v149
	v_and_b32_e32 v60, s0, v150
	v_and_b32_e32 v64, s1, v150
	v_and_b32_e32 v61, s0, v151
	v_and_b32_e32 v65, s1, v151
	v_readlane_b32 s0, v174, 10
	v_readlane_b32 s1, v174, 11
	v_lshl_or_b32 v18, v18, 9, v1
	v_mov_b32_e32 v20, s0
	v_mov_b32_e32 v19, s1
	v_cndmask_b32_e64 v19, v19, v20, s[4:5]
	v_readlane_b32 s0, v184, 44
	v_readlane_b32 s1, v184, 45
	s_waitcnt vmcnt(14)
	v_mfma_scale_f32_32x32x64_f8f6f4 v[2:17], v[42:45], v[58:65], v[2:17], v158, v158 op_sel_hi:[0,0,0] cbsz:4
	v_lshl_or_b32 v19, v19, 9, v1
	v_and_b32_e32 v62, s0, v148
	v_and_b32_e32 v66, s1, v148
	v_and_b32_e32 v63, s0, v149
	v_and_b32_e32 v67, s1, v149
	v_and_b32_e32 v64, s0, v150
	v_and_b32_e32 v68, s1, v150
	v_and_b32_e32 v65, s0, v151
	v_and_b32_e32 v69, s1, v151
	v_readlane_b32 s0, v174, 12
	v_readlane_b32 s1, v174, 13
	global_load_dwordx4 v[58:61], v18, s[10:11]
	global_load_dwordx4 v[38:41], v19, s[10:11]
	v_mov_b32_e32 v18, s1
	v_mov_b32_e32 v19, s0
	v_readlane_b32 s0, v174, 14
	v_readlane_b32 s1, v174, 15
	v_cndmask_b32_e64 v18, v18, v19, s[4:5]
	v_mov_b32_e32 v20, s0
	v_mov_b32_e32 v19, s1
	v_cndmask_b32_e64 v19, v19, v20, s[4:5]
	v_lshl_or_b32 v18, v18, 9, v1
	v_lshl_or_b32 v19, v19, 9, v1
	global_load_dwordx4 v[82:85], v18, s[10:11]
	s_nop 0
	global_load_dwordx4 v[18:21], v19, s[10:11]
	s_waitcnt vmcnt(17)
; #define VLOADA(slot, ereg, lsel) { const int ea_ = __builtin_amdgcn_readlane((ereg), (lsel)), eb_ = __builtin_amdgcn_readlane((ereg), (lsel) + 1); const int el_ = hh ? eb_ : ea_; ring[slot] = *(const GAS v4u*)(V4 + (((unsigned)el_ << 9) + laneoff)); }
; template <bool FINAL>
; __device__ __forceinline__ void phase_gather_v_mfma(const bf16* X, const int* EID, const float* COEF, const unsigned char* V4, const float* g, const float* bb, bf16* Ob, float* Of) {
;     ...
;         for (int J = 0; J < 64; ++J) {
;             const int ra = __builtin_amdgcn_readlane((J >> 5) ? rep1 : rep0, (2 * J) & 63), rb = __builtin_amdgcn_readlane((J >> 5) ? rep1 : rep0, ((2 * J) & 63) + 1);
;             v8i A, B;
;             A[0] = (int)ring[J & 15].x; A[1] = (int)ring[J & 15].y; A[2] = (int)ring[J & 15].z; A[3] = (int)ring[J & 15].w; A[4] = 0; A[5] = 0; A[6] = 0; A[7] = 0;
; #pragma unroll
;             for (int d = 0; d < 4; ++d) { B[d] = ra & (int)mask[d]; B[4 + d] = rb & (int)mask[d]; }
;             acc = __builtin_amdgcn_mfma_scale_f32_32x32x64_f8f6f4(A, B, acc, 4, 0, 0, 0x7f7f7f7f, 0, 0x7f7f7f7f);
;             if (J + 16 < 64) { VLOADA(J & 15, ((J + 16) >> 5) ? e1 : e0, (2 * (J + 16)) & 63) }
;             else { VLOADA(J & 15, ne0, 2 * (J + 16 - 64)) }
;             if ((J & 3) == 3) __builtin_amdgcn_sched_barrier(0);
	v_mfma_scale_f32_32x32x64_f8f6f4 v[2:17], v[94:97], v[62:69], v[2:17], v158, v158 op_sel_hi:[0,0,0] cbsz:4
	v_readlane_b32 s0, v184, 46
	v_readlane_b32 s1, v184, 47
	s_nop 0
	v_and_b32_e32 v62, s0, v148
	v_and_b32_e32 v66, s1, v148
	v_and_b32_e32 v63, s0, v149
	v_and_b32_e32 v67, s1, v149
	v_and_b32_e32 v64, s0, v150
	v_and_b32_e32 v68, s1, v150
	v_and_b32_e32 v65, s0, v151
	v_and_b32_e32 v69, s1, v151
	s_waitcnt vmcnt(16)
	s_nop 0
	v_mfma_scale_f32_32x32x64_f8f6f4 v[2:17], v[26:29], v[62:69], v[2:17], v158, v158 op_sel_hi:[0,0,0] cbsz:4
	v_readlane_b32 s0, v184, 48
	v_readlane_b32 s1, v184, 49
	s_nop 0
	v_and_b32_e32 v62, s0, v148
	v_and_b32_e32 v66, s1, v148
	v_and_b32_e32 v63, s0, v149
	v_and_b32_e32 v67, s1, v149
	v_and_b32_e32 v64, s0, v150
	v_and_b32_e32 v68, s1, v150
	v_and_b32_e32 v65, s0, v151
	v_and_b32_e32 v69, s1, v151
	v_readlane_b32 s0, v174, 16
	v_readlane_b32 s1, v174, 17
	s_waitcnt vmcnt(15)
	v_mfma_scale_f32_32x32x64_f8f6f4 v[2:17], v[90:93], v[62:69], v[2:17], v158, v158 op_sel_hi:[0,0,0] cbsz:4
	v_mov_b32_e32 v27, s0
	v_mov_b32_e32 v26, s1
	v_readlane_b32 s0, v184, 50
	v_readlane_b32 s1, v184, 51
	v_cndmask_b32_e64 v26, v26, v27, s[4:5]
	v_and_b32_e32 v62, s0, v148
	v_and_b32_e32 v66, s1, v148
	v_and_b32_e32 v63, s0, v149
	v_and_b32_e32 v67, s1, v149
	v_and_b32_e32 v64, s0, v150
	v_and_b32_e32 v68, s1, v150
	v_and_b32_e32 v65, s0, v151
	v_and_b32_e32 v69, s1, v151
	v_readlane_b32 s0, v174, 18
	v_readlane_b32 s1, v174, 19
	s_waitcnt vmcnt(14)
	v_mfma_scale_f32_32x32x64_f8f6f4 v[2:17], v[46:49], v[62:69], v[2:17], v158, v158 op_sel_hi:[0,0,0] cbsz:4
	v_mov_b32_e32 v28, s0
	v_mov_b32_e32 v27, s1
	v_cndmask_b32_e64 v27, v27, v28, s[4:5]
	v_readlane_b32 s0, v184, 52
	v_readlane_b32 s1, v184, 53
	v_lshl_or_b32 v26, v26, 9, v1
	v_lshl_or_b32 v27, v27, 9, v1
	v_and_b32_e32 v86, s0, v148
	v_and_b32_e32 v90, s1, v148
	v_and_b32_e32 v87, s0, v149
	v_and_b32_e32 v91, s1, v149
	v_and_b32_e32 v88, s0, v150
	v_and_b32_e32 v92, s1, v150
	v_and_b32_e32 v89, s0, v151
	v_and_b32_e32 v93, s1, v151
	v_readlane_b32 s0, v174, 20
	v_readlane_b32 s1, v174, 21
	global_load_dwordx4 v[62:65], v26, s[10:11]
	global_load_dwordx4 v[42:45], v27, s[10:11]
	v_mov_b32_e32 v26, s1
	v_mov_b32_e32 v27, s0
	v_readlane_b32 s0, v174, 22
	v_readlane_b32 s1, v174, 23
	v_cndmask_b32_e64 v26, v26, v27, s[4:5]
	v_mov_b32_e32 v28, s0
	v_mov_b32_e32 v27, s1
	v_cndmask_b32_e64 v27, v27, v28, s[4:5]
	v_lshl_or_b32 v26, v26, 9, v1
	v_lshl_or_b32 v27, v27, 9, v1
	s_waitcnt vmcnt(15)
	v_mfma_scale_f32_32x32x64_f8f6f4 v[2:17], v[98:101], v[86:93], v[2:17], v158, v158 op_sel_hi:[0,0,0] cbsz:4
	global_load_dwordx4 v[86:89], v26, s[10:11]
	s_nop 0
	global_load_dwordx4 v[26:29], v27, s[10:11]
	v_readlane_b32 s0, v184, 54
	v_readlane_b32 s1, v184, 55
	s_nop 0
	v_and_b32_e32 v90, s0, v148
	v_and_b32_e32 v94, s1, v148
	v_and_b32_e32 v91, s0, v149
	v_and_b32_e32 v95, s1, v149
	v_and_b32_e32 v92, s0, v150
	v_and_b32_e32 v96, s1, v150
	v_and_b32_e32 v93, s0, v151
	v_and_b32_e32 v97, s1, v151
	s_waitcnt vmcnt(16)
	s_nop 0
	v_mfma_scale_f32_32x32x64_f8f6f4 v[2:17], v[30:33], v[90:97], v[2:17], v158, v158 op_sel_hi:[0,0,0] cbsz:4
	v_readlane_b32 s0, v184, 56
	v_readlane_b32 s1, v184, 57
	s_nop 0
	v_and_b32_e32 v90, s0, v148
	v_and_b32_e32 v94, s1, v148
	v_and_b32_e32 v91, s0, v149
	v_and_b32_e32 v95, s1, v149
	v_and_b32_e32 v92, s0, v150
	v_and_b32_e32 v96, s1, v150
	v_and_b32_e32 v93, s0, v151
	v_and_b32_e32 v97, s1, v151
	v_readlane_b32 s0, v174, 24
	v_readlane_b32 s1, v174, 25
	s_waitcnt vmcnt(15)
	v_mfma_scale_f32_32x32x64_f8f6f4 v[2:17], v[70:73], v[90:97], v[2:17], v158, v158 op_sel_hi:[0,0,0] cbsz:4
	v_mov_b32_e32 v31, s0
	v_mov_b32_e32 v30, s1
	v_readlane_b32 s0, v184, 58
	v_readlane_b32 s1, v184, 59
	v_cndmask_b32_e64 v30, v30, v31, s[4:5]
	v_and_b32_e32 v66, s0, v148
	v_and_b32_e32 v70, s1, v148
	v_and_b32_e32 v67, s0, v149
	v_and_b32_e32 v71, s1, v149
	v_and_b32_e32 v68, s0, v150
	v_and_b32_e32 v72, s1, v150
	v_and_b32_e32 v69, s0, v151
	v_and_b32_e32 v73, s1, v151
	v_readlane_b32 s0, v174, 26
	v_readlane_b32 s1, v174, 27
	s_waitcnt vmcnt(14)
	v_mfma_scale_f32_32x32x64_f8f6f4 v[2:17], v[50:53], v[66:73], v[2:17], v158, v158 op_sel_hi:[0,0,0] cbsz:4
	v_mov_b32_e32 v32, s0
	v_mov_b32_e32 v31, s1
	v_cndmask_b32_e64 v31, v31, v32, s[4:5]
	v_readlane_b32 s0, v184, 60
	v_readlane_b32 s1, v184, 61
	v_lshl_or_b32 v30, v30, 9, v1
	v_lshl_or_b32 v31, v31, 9, v1
	v_and_b32_e32 v90, s0, v148
	v_and_b32_e32 v94, s1, v148
	v_and_b32_e32 v91, s0, v149
	v_and_b32_e32 v95, s1, v149
	v_and_b32_e32 v92, s0, v150
	v_and_b32_e32 v96, s1, v150
	v_and_b32_e32 v93, s0, v151
	v_and_b32_e32 v97, s1, v151
	v_readlane_b32 s0, v174, 28
	v_readlane_b32 s1, v174, 29
	global_load_dwordx4 v[66:69], v30, s[10:11]
	global_load_dwordx4 v[50:53], v31, s[10:11]
	v_mov_b32_e32 v30, s1
	v_mov_b32_e32 v31, s0
	v_readlane_b32 s0, v174, 30
	v_readlane_b32 s1, v174, 31
	v_cndmask_b32_e64 v30, v30, v31, s[4:5]
	v_mov_b32_e32 v32, s0
	v_mov_b32_e32 v31, s1
	v_cndmask_b32_e64 v31, v31, v32, s[4:5]
	v_lshl_or_b32 v30, v30, 9, v1
	v_lshl_or_b32 v31, v31, 9, v1
	s_waitcnt vmcnt(15)
	v_mfma_scale_f32_32x32x64_f8f6f4 v[2:17], v[102:105], v[90:97], v[2:17], v158, v158 op_sel_hi:[0,0,0] cbsz:4
	global_load_dwordx4 v[90:93], v30, s[10:11]
	s_nop 0
	global_load_dwordx4 v[30:33], v31, s[10:11]
	v_readlane_b32 s0, v184, 62
	v_readlane_b32 s1, v184, 63
	s_nop 0
	v_and_b32_e32 v94, s0, v148
	v_and_b32_e32 v98, s1, v148
	v_and_b32_e32 v95, s0, v149
	v_and_b32_e32 v99, s1, v149
	v_and_b32_e32 v96, s0, v150
	v_and_b32_e32 v100, s1, v150
	v_and_b32_e32 v97, s0, v151
	v_and_b32_e32 v101, s1, v151
	s_waitcnt vmcnt(16)
; #define VLOADA(slot, ereg, lsel) { const int ea_ = __builtin_amdgcn_readlane((ereg), (lsel)), eb_ = __builtin_amdgcn_readlane((ereg), (lsel) + 1); const int el_ = hh ? eb_ : ea_; ring[slot] = *(const GAS v4u*)(V4 + (((unsigned)el_ << 9) + laneoff)); }
; template <bool FINAL>
; __device__ __forceinline__ void phase_gather_v_mfma(const bf16* X, const int* EID, const float* COEF, const unsigned char* V4, const float* g, const float* bb, bf16* Ob, float* Of) {
;     ...
;         for (int J = 0; J < 64; ++J) {
;             const int ra = __builtin_amdgcn_readlane((J >> 5) ? rep1 : rep0, (2 * J) & 63), rb = __builtin_amdgcn_readlane((J >> 5) ? rep1 : rep0, ((2 * J) & 63) + 1);
;             v8i A, B;
;             A[0] = (int)ring[J & 15].x; A[1] = (int)ring[J & 15].y; A[2] = (int)ring[J & 15].z; A[3] = (int)ring[J & 15].w; A[4] = 0; A[5] = 0; A[6] = 0; A[7] = 0;
; #pragma unroll
;             for (int d = 0; d < 4; ++d) { B[d] = ra & (int)mask[d]; B[4 + d] = rb & (int)mask[d]; }
;             acc = __builtin_amdgcn_mfma_scale_f32_32x32x64_f8f6f4(A, B, acc, 4, 0, 0, 0x7f7f7f7f, 0, 0x7f7f7f7f);
;             if (J + 16 < 64) { VLOADA(J & 15, ((J + 16) >> 5) ? e1 : e0, (2 * (J + 16)) & 63) }
;             else { VLOADA(J & 15, ne0, 2 * (J + 16 - 64)) }
;             if ((J & 3) == 3) __builtin_amdgcn_sched_barrier(0);
	s_nop 0
	v_mfma_scale_f32_32x32x64_f8f6f4 v[2:17], v[34:37], v[94:101], v[2:17], v158, v158 op_sel_hi:[0,0,0] cbsz:4
	v_bfe_u32 v34, v183, 8, 8
	v_mul_lo_u32 v106, v34, s2
	s_nop 0
	v_readlane_b32 s0, v106, 0
	v_readlane_b32 s1, v106, 1
	s_nop 0
	v_and_b32_e32 v94, s0, v148
	v_and_b32_e32 v98, s1, v148
	v_and_b32_e32 v95, s0, v149
	v_and_b32_e32 v99, s1, v149
	v_and_b32_e32 v96, s0, v150
	v_and_b32_e32 v100, s1, v150
	v_and_b32_e32 v97, s0, v151
	v_and_b32_e32 v101, s1, v151
	v_readlane_b32 s0, v174, 32
	v_readlane_b32 s1, v174, 33
	s_waitcnt vmcnt(15)
	v_mfma_scale_f32_32x32x64_f8f6f4 v[2:17], v[74:77], v[94:101], v[2:17], v158, v158 op_sel_hi:[0,0,0] cbsz:4
	v_mov_b32_e32 v35, s0
	v_mov_b32_e32 v34, s1
	v_readlane_b32 s0, v106, 2
	v_readlane_b32 s1, v106, 3
	v_cndmask_b32_e64 v34, v34, v35, s[4:5]
	v_and_b32_e32 v70, s0, v148
	v_and_b32_e32 v74, s1, v148
	v_and_b32_e32 v71, s0, v149
	v_and_b32_e32 v75, s1, v149
	v_and_b32_e32 v72, s0, v150
	v_and_b32_e32 v76, s1, v150
	v_and_b32_e32 v73, s0, v151
	v_and_b32_e32 v77, s1, v151
	v_readlane_b32 s0, v174, 34
	v_readlane_b32 s1, v174, 35
	s_waitcnt vmcnt(14)
	v_mfma_scale_f32_32x32x64_f8f6f4 v[2:17], v[54:57], v[70:77], v[2:17], v158, v158 op_sel_hi:[0,0,0] cbsz:4
	v_mov_b32_e32 v36, s0
	v_mov_b32_e32 v35, s1
	v_cndmask_b32_e64 v35, v35, v36, s[4:5]
	v_readlane_b32 s0, v106, 4
	v_readlane_b32 s1, v106, 5
	v_lshl_or_b32 v34, v34, 9, v1
	v_lshl_or_b32 v35, v35, 9, v1
	v_and_b32_e32 v94, s0, v148
	v_and_b32_e32 v98, s1, v148
	v_and_b32_e32 v95, s0, v149
	v_and_b32_e32 v99, s1, v149
	v_and_b32_e32 v96, s0, v150
	v_and_b32_e32 v100, s1, v150
	v_and_b32_e32 v97, s0, v151
	v_and_b32_e32 v101, s1, v151
	v_readlane_b32 s0, v174, 36
	v_readlane_b32 s1, v174, 37
	global_load_dwordx4 v[70:73], v34, s[10:11]
	global_load_dwordx4 v[54:57], v35, s[10:11]
	v_mov_b32_e32 v34, s1
	v_mov_b32_e32 v35, s0
	v_readlane_b32 s0, v174, 38
	v_readlane_b32 s1, v174, 39
	v_cndmask_b32_e64 v34, v34, v35, s[4:5]
	v_mov_b32_e32 v36, s0
	v_mov_b32_e32 v35, s1
	v_cndmask_b32_e64 v35, v35, v36, s[4:5]
	v_lshl_or_b32 v34, v34, 9, v1
	v_lshl_or_b32 v35, v35, 9, v1
	s_waitcnt vmcnt(15)
	v_mfma_scale_f32_32x32x64_f8f6f4 v[2:17], v[78:81], v[94:101], v[2:17], v158, v158 op_sel_hi:[0,0,0] cbsz:4
	global_load_dwordx4 v[94:97], v34, s[10:11]
	s_nop 0
	global_load_dwordx4 v[34:37], v35, s[10:11]
	v_readlane_b32 s0, v106, 6
	v_readlane_b32 s1, v106, 7
	s_nop 0
	v_and_b32_e32 v74, s0, v148
	v_and_b32_e32 v78, s1, v148
	v_and_b32_e32 v75, s0, v149
	v_and_b32_e32 v79, s1, v149
	v_and_b32_e32 v76, s0, v150
	v_and_b32_e32 v80, s1, v150
	v_and_b32_e32 v77, s0, v151
	v_and_b32_e32 v81, s1, v151
	s_waitcnt vmcnt(16)
	s_nop 0
	v_mfma_scale_f32_32x32x64_f8f6f4 v[2:17], v[22:25], v[74:81], v[2:17], v158, v158 op_sel_hi:[0,0,0] cbsz:4
	v_readlane_b32 s0, v106, 8
	v_readlane_b32 s1, v106, 9
	s_nop 0
	v_and_b32_e32 v74, s0, v148
	v_and_b32_e32 v78, s1, v148
	v_and_b32_e32 v75, s0, v149
	v_and_b32_e32 v79, s1, v149
	v_and_b32_e32 v76, s0, v150
	v_and_b32_e32 v80, s1, v150
	v_and_b32_e32 v77, s0, v151
	v_and_b32_e32 v81, s1, v151
	v_readlane_b32 s0, v174, 40
	v_readlane_b32 s1, v174, 41
	s_waitcnt vmcnt(15)
	v_mfma_scale_f32_32x32x64_f8f6f4 v[2:17], v[58:61], v[74:81], v[2:17], v158, v158 op_sel_hi:[0,0,0] cbsz:4
	v_mov_b32_e32 v23, s0
	v_mov_b32_e32 v22, s1
	v_readlane_b32 s0, v106, 10
	v_readlane_b32 s1, v106, 11
	v_cndmask_b32_e64 v22, v22, v23, s[4:5]
	v_and_b32_e32 v74, s0, v148
	v_and_b32_e32 v78, s1, v148
	v_and_b32_e32 v75, s0, v149
	v_and_b32_e32 v79, s1, v149
	v_and_b32_e32 v76, s0, v150
	v_and_b32_e32 v80, s1, v150
	v_and_b32_e32 v77, s0, v151
	v_and_b32_e32 v81, s1, v151
	v_readlane_b32 s0, v174, 42
	v_readlane_b32 s1, v174, 43
	s_waitcnt vmcnt(14)
	v_mfma_scale_f32_32x32x64_f8f6f4 v[2:17], v[38:41], v[74:81], v[2:17], v158, v158 op_sel_hi:[0,0,0] cbsz:4
	v_mov_b32_e32 v24, s0
	v_mov_b32_e32 v23, s1
	v_cndmask_b32_e64 v23, v23, v24, s[4:5]
	v_readlane_b32 s0, v106, 12
	v_readlane_b32 s1, v106, 13
	v_lshl_or_b32 v22, v22, 9, v1
	v_lshl_or_b32 v23, v23, 9, v1
	v_and_b32_e32 v98, s0, v148
	v_and_b32_e32 v102, s1, v148
	v_and_b32_e32 v99, s0, v149
	v_and_b32_e32 v103, s1, v149
	v_and_b32_e32 v100, s0, v150
	v_and_b32_e32 v104, s1, v150
	v_and_b32_e32 v101, s0, v151
	v_and_b32_e32 v105, s1, v151
	v_readlane_b32 s0, v174, 44
	v_readlane_b32 s1, v174, 45
	global_load_dwordx4 v[74:77], v22, s[10:11]
	global_load_dwordx4 v[38:41], v23, s[10:11]
	v_mov_b32_e32 v22, s1
	v_mov_b32_e32 v23, s0
	v_readlane_b32 s0, v174, 46
	v_readlane_b32 s1, v174, 47
	v_cndmask_b32_e64 v22, v22, v23, s[4:5]
	v_mov_b32_e32 v24, s0
	v_mov_b32_e32 v23, s1
	v_lshl_or_b32 v22, v22, 9, v1
	v_cndmask_b32_e64 v23, v23, v24, s[4:5]
	s_waitcnt vmcnt(15)
	v_mfma_scale_f32_32x32x64_f8f6f4 v[2:17], v[82:85], v[98:105], v[2:17], v158, v158 op_sel_hi:[0,0,0] cbsz:4
	v_lshl_or_b32 v23, v23, 9, v1
	global_load_dwordx4 v[98:101], v22, s[10:11]
	global_load_dwordx4 v[46:49], v23, s[10:11]
	v_readlane_b32 s0, v106, 14
	v_readlane_b32 s1, v106, 15
	s_nop 0
	v_and_b32_e32 v78, s0, v148
	v_and_b32_e32 v82, s1, v148
	v_and_b32_e32 v79, s0, v149
	v_and_b32_e32 v83, s1, v149
	v_and_b32_e32 v80, s0, v150
	v_and_b32_e32 v84, s1, v150
	v_and_b32_e32 v81, s0, v151
	v_and_b32_e32 v85, s1, v151
	s_waitcnt vmcnt(16)
	s_nop 0
	v_mfma_scale_f32_32x32x64_f8f6f4 v[2:17], v[18:21], v[78:85], v[2:17], v158, v158 op_sel_hi:[0,0,0] cbsz:4
	v_readlane_b32 s0, v106, 16
	v_readlane_b32 s1, v106, 17
	s_nop 0
	v_and_b32_e32 v18, s0, v148
	v_and_b32_e32 v22, s1, v148
	v_and_b32_e32 v19, s0, v149
	v_and_b32_e32 v23, s1, v149
	v_and_b32_e32 v20, s0, v150
	v_and_b32_e32 v24, s1, v150
	v_and_b32_e32 v21, s0, v151
	v_and_b32_e32 v25, s1, v151
	v_readlane_b32 s0, v174, 48
	v_readlane_b32 s1, v174, 49
	s_waitcnt vmcnt(15)
; #define VLOADA(slot, ereg, lsel) { const int ea_ = __builtin_amdgcn_readlane((ereg), (lsel)), eb_ = __builtin_amdgcn_readlane((ereg), (lsel) + 1); const int el_ = hh ? eb_ : ea_; ring[slot] = *(const GAS v4u*)(V4 + (((unsigned)el_ << 9) + laneoff)); }
; template <bool FINAL>
; __device__ __forceinline__ void phase_gather_v_mfma(const bf16* X, const int* EID, const float* COEF, const unsigned char* V4, const float* g, const float* bb, bf16* Ob, float* Of) {
;     ...
;         for (int J = 0; J < 64; ++J) {
;             const int ra = __builtin_amdgcn_readlane((J >> 5) ? rep1 : rep0, (2 * J) & 63), rb = __builtin_amdgcn_readlane((J >> 5) ? rep1 : rep0, ((2 * J) & 63) + 1);
;             v8i A, B;
;             A[0] = (int)ring[J & 15].x; A[1] = (int)ring[J & 15].y; A[2] = (int)ring[J & 15].z; A[3] = (int)ring[J & 15].w; A[4] = 0; A[5] = 0; A[6] = 0; A[7] = 0;
; #pragma unroll
;             for (int d = 0; d < 4; ++d) { B[d] = ra & (int)mask[d]; B[4 + d] = rb & (int)mask[d]; }
;             acc = __builtin_amdgcn_mfma_scale_f32_32x32x64_f8f6f4(A, B, acc, 4, 0, 0, 0x7f7f7f7f, 0, 0x7f7f7f7f);
;             if (J + 16 < 64) { VLOADA(J & 15, ((J + 16) >> 5) ? e1 : e0, (2 * (J + 16)) & 63) }
;             else { VLOADA(J & 15, ne0, 2 * (J + 16 - 64)) }
;             if ((J & 3) == 3) __builtin_amdgcn_sched_barrier(0);
	v_mfma_scale_f32_32x32x64_f8f6f4 v[2:17], v[62:65], v[18:25], v[2:17], v158, v158 op_sel_hi:[0,0,0] cbsz:4
	v_mov_b32_e32 v59, s0
	v_mov_b32_e32 v58, s1
	v_cndmask_b32_e64 v18, v58, v59, s[4:5]
	v_readlane_b32 s0, v106, 18
	v_readlane_b32 s1, v106, 19
	v_lshl_or_b32 v58, v18, 9, v1
	v_and_b32_e32 v18, s0, v148
	v_and_b32_e32 v22, s1, v148
	v_and_b32_e32 v19, s0, v149
	v_and_b32_e32 v23, s1, v149
	v_and_b32_e32 v20, s0, v150
	v_and_b32_e32 v24, s1, v150
	v_and_b32_e32 v21, s0, v151
	v_and_b32_e32 v25, s1, v151
	v_readlane_b32 s0, v174, 50
	v_readlane_b32 s1, v174, 51
	s_waitcnt vmcnt(14)
	v_mfma_scale_f32_32x32x64_f8f6f4 v[2:17], v[42:45], v[18:25], v[2:17], v158, v158 op_sel_hi:[0,0,0] cbsz:4
	v_mov_b32_e32 v18, s0
	v_mov_b32_e32 v59, s1
	v_cndmask_b32_e64 v18, v59, v18, s[4:5]
	v_lshl_or_b32 v18, v18, 9, v1
	v_readlane_b32 s0, v106, 20
	v_readlane_b32 s1, v106, 21
	global_load_dwordx4 v[78:81], v58, s[10:11]
	s_nop 0
	global_load_dwordx4 v[58:61], v18, s[10:11]
	v_and_b32_e32 v18, s0, v148
	v_and_b32_e32 v22, s1, v148
	v_and_b32_e32 v19, s0, v149
	v_and_b32_e32 v23, s1, v149
	v_and_b32_e32 v20, s0, v150
	v_and_b32_e32 v24, s1, v150
	v_and_b32_e32 v21, s0, v151
	v_and_b32_e32 v25, s1, v151
	v_readlane_b32 s0, v174, 52
	v_readlane_b32 s1, v174, 53
	s_waitcnt vmcnt(15)
	v_mfma_scale_f32_32x32x64_f8f6f4 v[2:17], v[86:89], v[18:25], v[2:17], v158, v158 op_sel_hi:[0,0,0] cbsz:4
	v_mov_b32_e32 v19, s0
	v_mov_b32_e32 v18, s1
	v_readlane_b32 s0, v174, 54
	v_readlane_b32 s1, v174, 55
	v_cndmask_b32_e64 v18, v18, v19, s[4:5]
	v_mov_b32_e32 v20, s0
	v_mov_b32_e32 v19, s1
	v_lshl_or_b32 v18, v18, 9, v1
	v_cndmask_b32_e64 v19, v19, v20, s[4:5]
	v_lshl_or_b32 v19, v19, 9, v1
	global_load_dwordx4 v[102:105], v18, s[10:11]
	global_load_dwordx4 v[62:65], v19, s[10:11]
	v_readlane_b32 s0, v106, 22
	v_readlane_b32 s1, v106, 23
	s_nop 0
	v_and_b32_e32 v18, s0, v148
	v_and_b32_e32 v22, s1, v148
	v_and_b32_e32 v19, s0, v149
	v_and_b32_e32 v23, s1, v149
	v_and_b32_e32 v20, s0, v150
	v_and_b32_e32 v24, s1, v150
	v_and_b32_e32 v21, s0, v151
	v_and_b32_e32 v25, s1, v151
	s_waitcnt vmcnt(16)
	s_nop 0
	v_mfma_scale_f32_32x32x64_f8f6f4 v[2:17], v[26:29], v[18:25], v[2:17], v158, v158 op_sel_hi:[0,0,0] cbsz:4
	v_readlane_b32 s0, v106, 24
	v_readlane_b32 s1, v106, 25
	s_nop 0
	v_and_b32_e32 v18, s0, v148
	v_and_b32_e32 v22, s1, v148
	v_and_b32_e32 v19, s0, v149
	v_and_b32_e32 v23, s1, v149
	v_and_b32_e32 v20, s0, v150
	v_and_b32_e32 v24, s1, v150
	v_and_b32_e32 v21, s0, v151
	v_and_b32_e32 v25, s1, v151
	v_readlane_b32 s0, v174, 56
	v_readlane_b32 s1, v174, 57
	s_waitcnt vmcnt(15)
	v_mfma_scale_f32_32x32x64_f8f6f4 v[2:17], v[66:69], v[18:25], v[2:17], v158, v158 op_sel_hi:[0,0,0] cbsz:4
	v_mov_b32_e32 v27, s0
	v_mov_b32_e32 v26, s1
	v_cndmask_b32_e64 v18, v26, v27, s[4:5]
	v_readlane_b32 s0, v106, 26
	v_readlane_b32 s1, v106, 27
	v_lshl_or_b32 v26, v18, 9, v1
	v_and_b32_e32 v18, s0, v148
	v_and_b32_e32 v22, s1, v148
	v_and_b32_e32 v19, s0, v149
	v_and_b32_e32 v23, s1, v149
	v_and_b32_e32 v20, s0, v150
	v_and_b32_e32 v24, s1, v150
	v_and_b32_e32 v21, s0, v151
	v_and_b32_e32 v25, s1, v151
	v_readlane_b32 s0, v174, 58
	v_readlane_b32 s1, v174, 59
	s_waitcnt vmcnt(14)
	v_mfma_scale_f32_32x32x64_f8f6f4 v[2:17], v[50:53], v[18:25], v[2:17], v158, v158 op_sel_hi:[0,0,0] cbsz:4
	v_mov_b32_e32 v18, s0
	v_mov_b32_e32 v27, s1
	v_cndmask_b32_e64 v18, v27, v18, s[4:5]
	v_lshl_or_b32 v18, v18, 9, v1
	v_readlane_b32 s0, v106, 28
	v_readlane_b32 s1, v106, 29
	global_load_dwordx4 v[86:89], v26, s[10:11]
	global_load_dwordx4 v[66:69], v18, s[10:11]
	v_and_b32_e32 v18, s0, v148
	v_and_b32_e32 v22, s1, v148
	v_and_b32_e32 v19, s0, v149
	v_and_b32_e32 v23, s1, v149
	v_and_b32_e32 v20, s0, v150
	v_and_b32_e32 v24, s1, v150
	v_and_b32_e32 v21, s0, v151
	v_and_b32_e32 v25, s1, v151
	v_readlane_b32 s0, v174, 60
	v_readlane_b32 s1, v174, 61
	s_waitcnt vmcnt(15)
	v_mfma_scale_f32_32x32x64_f8f6f4 v[2:17], v[90:93], v[18:25], v[2:17], v158, v158 op_sel_hi:[0,0,0] cbsz:4
	v_mov_b32_e32 v19, s0
	v_mov_b32_e32 v18, s1
	v_readlane_b32 s0, v174, 62
	v_readlane_b32 s1, v174, 63
	v_cndmask_b32_e64 v18, v18, v19, s[4:5]
	v_mov_b32_e32 v20, s0
	v_mov_b32_e32 v19, s1
	v_lshl_or_b32 v18, v18, 9, v1
	v_cndmask_b32_e64 v19, v19, v20, s[4:5]
	v_lshl_or_b32 v19, v19, 9, v1
	global_load_dwordx4 v[90:93], v18, s[10:11]
	global_load_dwordx4 v[82:85], v19, s[10:11]
	v_readlane_b32 s0, v106, 30
	v_readlane_b32 s1, v106, 31
	s_nop 0
	v_and_b32_e32 v18, s0, v148
	v_and_b32_e32 v22, s1, v148
	v_and_b32_e32 v19, s0, v149
	v_and_b32_e32 v23, s1, v149
	v_and_b32_e32 v20, s0, v150
	v_and_b32_e32 v24, s1, v150
	v_and_b32_e32 v21, s0, v151
	v_and_b32_e32 v25, s1, v151
	s_waitcnt vmcnt(16)
	s_nop 0
	v_mfma_scale_f32_32x32x64_f8f6f4 v[2:17], v[30:33], v[18:25], v[2:17], v158, v158 op_sel_hi:[0,0,0] cbsz:4
	v_readlane_b32 s0, v106, 32
	v_readlane_b32 s1, v106, 33
	s_nop 0
	v_and_b32_e32 v18, s0, v148
	v_and_b32_e32 v22, s1, v148
	v_and_b32_e32 v19, s0, v149
	v_and_b32_e32 v23, s1, v149
	v_and_b32_e32 v20, s0, v150
	v_and_b32_e32 v24, s1, v150
	v_and_b32_e32 v21, s0, v151
	v_and_b32_e32 v25, s1, v151
	v_readlane_b32 s0, v162, 0
	v_readlane_b32 s1, v162, 1
	s_waitcnt vmcnt(15)
	v_mfma_scale_f32_32x32x64_f8f6f4 v[2:17], v[70:73], v[18:25], v[2:17], v158, v158 op_sel_hi:[0,0,0] cbsz:4
	v_mov_b32_e32 v27, s0
	v_mov_b32_e32 v26, s1
	v_cndmask_b32_e64 v18, v26, v27, s[4:5]
	v_readlane_b32 s0, v106, 34
	v_readlane_b32 s1, v106, 35
	v_lshl_or_b32 v26, v18, 9, v1
	v_and_b32_e32 v18, s0, v148
	v_and_b32_e32 v22, s1, v148
	v_and_b32_e32 v19, s0, v149
	v_and_b32_e32 v23, s1, v149
	v_and_b32_e32 v20, s0, v150
	v_and_b32_e32 v24, s1, v150
	v_and_b32_e32 v21, s0, v151
	v_and_b32_e32 v25, s1, v151
	v_readlane_b32 s0, v162, 2
	v_readlane_b32 s1, v162, 3
	s_waitcnt vmcnt(14)
; #define VLOADA(slot, ereg, lsel) { const int ea_ = __builtin_amdgcn_readlane((ereg), (lsel)), eb_ = __builtin_amdgcn_readlane((ereg), (lsel) + 1); const int el_ = hh ? eb_ : ea_; ring[slot] = *(const GAS v4u*)(V4 + (((unsigned)el_ << 9) + laneoff)); }
; template <bool FINAL>
; __device__ __forceinline__ void phase_gather_v_mfma(const bf16* X, const int* EID, const float* COEF, const unsigned char* V4, const float* g, const float* bb, bf16* Ob, float* Of) {
;     ...
;         for (int J = 0; J < 64; ++J) {
;             const int ra = __builtin_amdgcn_readlane((J >> 5) ? rep1 : rep0, (2 * J) & 63), rb = __builtin_amdgcn_readlane((J >> 5) ? rep1 : rep0, ((2 * J) & 63) + 1);
;             v8i A, B;
;             A[0] = (int)ring[J & 15].x; A[1] = (int)ring[J & 15].y; A[2] = (int)ring[J & 15].z; A[3] = (int)ring[J & 15].w; A[4] = 0; A[5] = 0; A[6] = 0; A[7] = 0;
; #pragma unroll
;             for (int d = 0; d < 4; ++d) { B[d] = ra & (int)mask[d]; B[4 + d] = rb & (int)mask[d]; }
;             acc = __builtin_amdgcn_mfma_scale_f32_32x32x64_f8f6f4(A, B, acc, 4, 0, 0, 0x7f7f7f7f, 0, 0x7f7f7f7f);
;             if (J + 16 < 64) { VLOADA(J & 15, ((J + 16) >> 5) ? e1 : e0, (2 * (J + 16)) & 63) }
;             else { VLOADA(J & 15, ne0, 2 * (J + 16 - 64)) }
;             if ((J & 3) == 3) __builtin_amdgcn_sched_barrier(0);
	v_mfma_scale_f32_32x32x64_f8f6f4 v[2:17], v[54:57], v[18:25], v[2:17], v158, v158 op_sel_hi:[0,0,0] cbsz:4
	v_mov_b32_e32 v18, s0
	v_mov_b32_e32 v27, s1
	v_cndmask_b32_e64 v18, v27, v18, s[4:5]
	v_lshl_or_b32 v18, v18, 9, v1
	v_readlane_b32 s0, v106, 36
	v_readlane_b32 s1, v106, 37
	global_load_dwordx4 v[22:25], v26, s[10:11]
	s_nop 0
	global_load_dwordx4 v[18:21], v18, s[10:11]
	v_and_b32_e32 v26, s0, v148
	v_and_b32_e32 v30, s1, v148
	v_and_b32_e32 v27, s0, v149
	v_and_b32_e32 v31, s1, v149
	v_and_b32_e32 v28, s0, v150
	v_and_b32_e32 v32, s1, v150
	v_and_b32_e32 v29, s0, v151
	v_and_b32_e32 v33, s1, v151
	v_readlane_b32 s0, v162, 4
	v_readlane_b32 s1, v162, 5
	s_waitcnt vmcnt(15)
	v_mfma_scale_f32_32x32x64_f8f6f4 v[2:17], v[94:97], v[26:33], v[2:17], v158, v158 op_sel_hi:[0,0,0] cbsz:4
	v_mov_b32_e32 v27, s0
	v_mov_b32_e32 v26, s1
	v_readlane_b32 s0, v162, 6
	v_readlane_b32 s1, v162, 7
	v_cndmask_b32_e64 v26, v26, v27, s[4:5]
	v_mov_b32_e32 v28, s0
	v_mov_b32_e32 v27, s1
	v_cndmask_b32_e64 v27, v27, v28, s[4:5]
	v_lshl_or_b32 v26, v26, 9, v1
	v_lshl_or_b32 v27, v27, 9, v1
	global_load_dwordx4 v[30:33], v26, s[10:11]
	s_nop 0
	global_load_dwordx4 v[26:29], v27, s[10:11]
	v_readlane_b32 s0, v106, 38
	v_readlane_b32 s1, v106, 39
	s_nop 0
	v_and_b32_e32 v50, s0, v148
	v_and_b32_e32 v54, s1, v148
	v_and_b32_e32 v51, s0, v149
	v_and_b32_e32 v55, s1, v149
	v_and_b32_e32 v52, s0, v150
	v_and_b32_e32 v56, s1, v150
	v_and_b32_e32 v53, s0, v151
	v_and_b32_e32 v57, s1, v151
	s_waitcnt vmcnt(16)
	s_nop 0
	v_mfma_scale_f32_32x32x64_f8f6f4 v[2:17], v[34:37], v[50:57], v[2:17], v158, v158 op_sel_hi:[0,0,0] cbsz:4
	v_readlane_b32 s0, v106, 40
	v_readlane_b32 s1, v106, 41
	s_nop 0
	v_and_b32_e32 v50, s0, v148
	v_and_b32_e32 v54, s1, v148
	v_and_b32_e32 v51, s0, v149
	v_and_b32_e32 v55, s1, v149
	v_and_b32_e32 v52, s0, v150
	v_and_b32_e32 v56, s1, v150
	v_and_b32_e32 v53, s0, v151
	v_and_b32_e32 v57, s1, v151
	v_readlane_b32 s0, v162, 8
	v_readlane_b32 s1, v162, 9
	s_waitcnt vmcnt(15)
	v_mfma_scale_f32_32x32x64_f8f6f4 v[2:17], v[74:77], v[50:57], v[2:17], v158, v158 op_sel_hi:[0,0,0] cbsz:4
	v_mov_b32_e32 v35, s0
	v_mov_b32_e32 v34, s1
	v_readlane_b32 s0, v106, 42
	v_readlane_b32 s1, v106, 43
	v_cndmask_b32_e64 v34, v34, v35, s[4:5]
	v_and_b32_e32 v50, s0, v148
	v_and_b32_e32 v54, s1, v148
	v_and_b32_e32 v51, s0, v149
	v_and_b32_e32 v55, s1, v149
	v_and_b32_e32 v52, s0, v150
	v_and_b32_e32 v56, s1, v150
	v_and_b32_e32 v53, s0, v151
	v_and_b32_e32 v57, s1, v151
	v_readlane_b32 s0, v162, 10
	v_readlane_b32 s1, v162, 11
	s_waitcnt vmcnt(14)
	v_mfma_scale_f32_32x32x64_f8f6f4 v[2:17], v[38:41], v[50:57], v[2:17], v158, v158 op_sel_hi:[0,0,0] cbsz:4
	v_mov_b32_e32 v36, s0
	v_mov_b32_e32 v35, s1
	v_readlane_b32 s0, v106, 44
	v_readlane_b32 s1, v106, 45
	v_cndmask_b32_e64 v35, v35, v36, s[4:5]
	v_and_b32_e32 v50, s0, v148
	v_and_b32_e32 v54, s1, v148
	v_and_b32_e32 v51, s0, v149
	v_and_b32_e32 v55, s1, v149
	v_and_b32_e32 v52, s0, v150
	v_and_b32_e32 v56, s1, v150
	v_and_b32_e32 v53, s0, v151
	v_and_b32_e32 v57, s1, v151
	v_readlane_b32 s0, v162, 12
	v_readlane_b32 s1, v162, 13
	v_lshl_or_b32 v34, v34, 9, v1
	v_mov_b32_e32 v39, s0
	v_mov_b32_e32 v38, s1
	v_readlane_b32 s0, v162, 14
	v_readlane_b32 s1, v162, 15
	v_cndmask_b32_e64 v38, v38, v39, s[4:5]
	v_mov_b32_e32 v40, s0
	v_mov_b32_e32 v39, s1
	v_cndmask_b32_e64 v39, v39, v40, s[4:5]
	v_lshl_or_b32 v35, v35, 9, v1
	v_lshl_or_b32 v38, v38, 9, v1
	v_lshl_or_b32 v39, v39, 9, v1
	global_load_dwordx4 v[42:45], v34, s[10:11]
	s_nop 0
	global_load_dwordx4 v[34:37], v35, s[10:11]
	s_waitcnt vmcnt(15)
	v_mfma_scale_f32_32x32x64_f8f6f4 v[2:17], v[98:101], v[50:57], v[2:17], v158, v158 op_sel_hi:[0,0,0] cbsz:4
	global_load_dwordx4 v[54:57], v38, s[10:11]
	s_nop 0
	global_load_dwordx4 v[38:41], v39, s[10:11]
	v_readlane_b32 s0, v106, 46
	v_readlane_b32 s1, v106, 47
	s_nop 0
	v_and_b32_e32 v70, s0, v148
	v_and_b32_e32 v74, s1, v148
	v_and_b32_e32 v71, s0, v149
	v_and_b32_e32 v75, s1, v149
	v_and_b32_e32 v72, s0, v150
	v_and_b32_e32 v76, s1, v150
	v_and_b32_e32 v73, s0, v151
	v_and_b32_e32 v77, s1, v151
	s_waitcnt vmcnt(16)
	s_nop 0
	v_mfma_scale_f32_32x32x64_f8f6f4 v[2:17], v[46:49], v[70:77], v[2:17], v158, v158 op_sel_hi:[0,0,0] cbsz:4
	v_readlane_b32 s0, v106, 48
	v_readlane_b32 s1, v106, 49
	s_nop 0
	v_and_b32_e32 v46, s0, v148
	v_and_b32_e32 v50, s1, v148
	v_and_b32_e32 v47, s0, v149
	v_and_b32_e32 v51, s1, v149
	v_and_b32_e32 v48, s0, v150
	v_and_b32_e32 v52, s1, v150
	v_and_b32_e32 v49, s0, v151
	v_and_b32_e32 v53, s1, v151
	v_readlane_b32 s0, v162, 16
	v_readlane_b32 s1, v162, 17
	s_waitcnt vmcnt(15)
	v_mfma_scale_f32_32x32x64_f8f6f4 v[2:17], v[78:81], v[46:53], v[2:17], v158, v158 op_sel_hi:[0,0,0] cbsz:4
	v_mov_b32_e32 v71, s0
	v_mov_b32_e32 v70, s1
	v_cndmask_b32_e64 v46, v70, v71, s[4:5]
	v_readlane_b32 s0, v106, 50
	v_readlane_b32 s1, v106, 51
	v_lshl_or_b32 v70, v46, 9, v1
	v_and_b32_e32 v46, s0, v148
	v_and_b32_e32 v50, s1, v148
	v_and_b32_e32 v47, s0, v149
	v_and_b32_e32 v51, s1, v149
	v_and_b32_e32 v48, s0, v150
	v_and_b32_e32 v52, s1, v150
	v_and_b32_e32 v49, s0, v151
	v_and_b32_e32 v53, s1, v151
	v_readlane_b32 s0, v162, 18
	v_readlane_b32 s1, v162, 19
	s_waitcnt vmcnt(14)
	v_mfma_scale_f32_32x32x64_f8f6f4 v[2:17], v[58:61], v[46:53], v[2:17], v158, v158 op_sel_hi:[0,0,0] cbsz:4
	v_mov_b32_e32 v46, s0
	v_mov_b32_e32 v71, s1
	v_cndmask_b32_e64 v46, v71, v46, s[4:5]
	v_lshl_or_b32 v46, v46, 9, v1
	v_readlane_b32 s0, v106, 52
	v_readlane_b32 s1, v106, 53
	global_load_dwordx4 v[58:61], v70, s[10:11]
	s_nop 0
	global_load_dwordx4 v[46:49], v46, s[10:11]
	v_and_b32_e32 v70, s0, v148
	v_and_b32_e32 v74, s1, v148
	v_and_b32_e32 v71, s0, v149
	v_and_b32_e32 v75, s1, v149
	v_and_b32_e32 v72, s0, v150
	v_and_b32_e32 v76, s1, v150
	v_and_b32_e32 v73, s0, v151
	v_and_b32_e32 v77, s1, v151
	v_readlane_b32 s0, v162, 20
	v_readlane_b32 s1, v162, 21
	s_waitcnt vmcnt(15)
; #define VLOADA(slot, ereg, lsel) { const int ea_ = __builtin_amdgcn_readlane((ereg), (lsel)), eb_ = __builtin_amdgcn_readlane((ereg), (lsel) + 1); const int el_ = hh ? eb_ : ea_; ring[slot] = *(const GAS v4u*)(V4 + (((unsigned)el_ << 9) + laneoff)); }
; template <bool FINAL>
; __device__ __forceinline__ void phase_gather_v_mfma(const bf16* X, const int* EID, const float* COEF, const unsigned char* V4, const float* g, const float* bb, bf16* Ob, float* Of) {
;     ...
;         for (int J = 0; J < 64; ++J) {
;             const int ra = __builtin_amdgcn_readlane((J >> 5) ? rep1 : rep0, (2 * J) & 63), rb = __builtin_amdgcn_readlane((J >> 5) ? rep1 : rep0, ((2 * J) & 63) + 1);
;             v8i A, B;
;             A[0] = (int)ring[J & 15].x; A[1] = (int)ring[J & 15].y; A[2] = (int)ring[J & 15].z; A[3] = (int)ring[J & 15].w; A[4] = 0; A[5] = 0; A[6] = 0; A[7] = 0;
; #pragma unroll
;             for (int d = 0; d < 4; ++d) { B[d] = ra & (int)mask[d]; B[4 + d] = rb & (int)mask[d]; }
;             acc = __builtin_amdgcn_mfma_scale_f32_32x32x64_f8f6f4(A, B, acc, 4, 0, 0, 0x7f7f7f7f, 0, 0x7f7f7f7f);
;             if (J + 16 < 64) { VLOADA(J & 15, ((J + 16) >> 5) ? e1 : e0, (2 * (J + 16)) & 63) }
;             else { VLOADA(J & 15, ne0, 2 * (J + 16 - 64)) }
;             if ((J & 3) == 3) __builtin_amdgcn_sched_barrier(0);
;         }
;         float z[16]; float sm = 0.f;
; #pragma unroll
;         for (int r = 0; r < 16; ++r) { const float av = acc[r]; z[r] = ALPHA * bf2f(xs[r]) + av * invS; sm += z[r]; }
	v_mfma_scale_f32_32x32x64_f8f6f4 v[2:17], v[102:105], v[70:77], v[2:17], v158, v158 op_sel_hi:[0,0,0] cbsz:4
	v_mov_b32_e32 v51, s0
	v_mov_b32_e32 v50, s1
	v_readlane_b32 s0, v162, 22
	v_readlane_b32 s1, v162, 23
	v_cndmask_b32_e64 v50, v50, v51, s[4:5]
	v_mov_b32_e32 v52, s0
	v_mov_b32_e32 v51, s1
	v_cndmask_b32_e64 v51, v51, v52, s[4:5]
	v_lshl_or_b32 v50, v50, 9, v1
	v_lshl_or_b32 v51, v51, 9, v1
	global_load_dwordx4 v[70:73], v50, s[10:11]
	s_nop 0
	global_load_dwordx4 v[50:53], v51, s[10:11]
	v_readlane_b32 s0, v106, 54
	v_readlane_b32 s1, v106, 55
	s_nop 0
	v_and_b32_e32 v74, s0, v148
	v_and_b32_e32 v78, s1, v148
	v_and_b32_e32 v75, s0, v149
	v_and_b32_e32 v79, s1, v149
	v_and_b32_e32 v76, s0, v150
	v_and_b32_e32 v80, s1, v150
	v_and_b32_e32 v77, s0, v151
	v_and_b32_e32 v81, s1, v151
	s_waitcnt vmcnt(16)
	s_nop 0
	v_mfma_scale_f32_32x32x64_f8f6f4 v[2:17], v[62:65], v[74:81], v[2:17], v158, v158 op_sel_hi:[0,0,0] cbsz:4
	v_readlane_b32 s0, v106, 56
	v_readlane_b32 s1, v106, 57
	s_nop 0
	v_and_b32_e32 v74, s0, v148
	v_and_b32_e32 v78, s1, v148
	v_and_b32_e32 v75, s0, v149
	v_and_b32_e32 v79, s1, v149
	v_and_b32_e32 v76, s0, v150
	v_and_b32_e32 v80, s1, v150
	v_and_b32_e32 v77, s0, v151
	v_and_b32_e32 v81, s1, v151
	v_readlane_b32 s0, v162, 24
	v_readlane_b32 s1, v162, 25
	s_waitcnt vmcnt(15)
	v_mfma_scale_f32_32x32x64_f8f6f4 v[2:17], v[86:89], v[74:81], v[2:17], v158, v158 op_sel_hi:[0,0,0] cbsz:4
	v_mov_b32_e32 v63, s0
	v_mov_b32_e32 v62, s1
	v_readlane_b32 s0, v106, 58
	v_readlane_b32 s1, v106, 59
	v_cndmask_b32_e64 v62, v62, v63, s[4:5]
	v_and_b32_e32 v74, s0, v148
	v_and_b32_e32 v78, s1, v148
	v_and_b32_e32 v75, s0, v149
	v_and_b32_e32 v79, s1, v149
	v_and_b32_e32 v76, s0, v150
	v_and_b32_e32 v80, s1, v150
	v_and_b32_e32 v77, s0, v151
	v_and_b32_e32 v81, s1, v151
	v_readlane_b32 s0, v162, 26
	v_readlane_b32 s1, v162, 27
	s_waitcnt vmcnt(14)
	v_mfma_scale_f32_32x32x64_f8f6f4 v[2:17], v[66:69], v[74:81], v[2:17], v158, v158 op_sel_hi:[0,0,0] cbsz:4
	v_mov_b32_e32 v64, s0
	v_mov_b32_e32 v63, s1
	v_readlane_b32 s0, v106, 60
	v_readlane_b32 s1, v106, 61
	v_cndmask_b32_e64 v63, v63, v64, s[4:5]
	v_and_b32_e32 v94, s0, v148
	v_and_b32_e32 v98, s1, v148
	v_and_b32_e32 v95, s0, v149
	v_and_b32_e32 v99, s1, v149
	v_and_b32_e32 v96, s0, v150
	v_and_b32_e32 v100, s1, v150
	v_and_b32_e32 v97, s0, v151
	v_and_b32_e32 v101, s1, v151
	v_readlane_b32 s0, v162, 28
	v_readlane_b32 s1, v162, 29
	v_lshl_or_b32 v62, v62, 9, v1
	v_mov_b32_e32 v67, s0
	v_mov_b32_e32 v66, s1
	v_readlane_b32 s0, v162, 30
	v_readlane_b32 s1, v162, 31
	v_cndmask_b32_e64 v66, v66, v67, s[4:5]
	v_mov_b32_e32 v68, s0
	v_mov_b32_e32 v67, s1
	v_cndmask_b32_e64 v67, v67, v68, s[4:5]
	v_lshl_or_b32 v63, v63, 9, v1
	v_lshl_or_b32 v66, v66, 9, v1
	v_lshl_or_b32 v67, v67, 9, v1
	global_load_dwordx4 v[74:77], v62, s[10:11]
	s_nop 0
	global_load_dwordx4 v[62:65], v63, s[10:11]
	s_nop 0
	global_load_dwordx4 v[78:81], v66, s[10:11]
	s_nop 0
	global_load_dwordx4 v[66:69], v67, s[10:11]
	s_waitcnt vmcnt(17)
	v_mfma_scale_f32_32x32x64_f8f6f4 v[2:17], v[90:93], v[94:101], v[2:17], v158, v158 op_sel_hi:[0,0,0] cbsz:4
	v_readlane_b32 s0, v106, 62
	v_readlane_b32 s1, v106, 63
	s_nop 0
	v_and_b32_e32 v86, s0, v148
	v_and_b32_e32 v90, s1, v148
	v_and_b32_e32 v87, s0, v149
	v_and_b32_e32 v91, s1, v149
	v_and_b32_e32 v88, s0, v150
	v_and_b32_e32 v92, s1, v150
	v_and_b32_e32 v89, s0, v151
	v_and_b32_e32 v93, s1, v151
	s_waitcnt vmcnt(16)
	s_nop 0
	v_mfma_scale_f32_32x32x64_f8f6f4 v[2:17], v[82:85], v[86:93], v[2:17], v158, v158 op_sel_hi:[0,0,0] cbsz:4
	v_lshlrev_b32_e32 v82, 16, v182
	s_nop 15
	s_nop 2
	v_mul_f32_e32 v2, v2, v165
	v_fmac_f32_e32 v2, 0x3fb504f3, v82
	v_lshlrev_b32_e32 v83, 16, v181
	v_mul_f32_e32 v84, v3, v165
	v_add_f32_e32 v82, 0, v2
	v_fmac_f32_e32 v84, 0x3fb504f3, v83
	v_add_f32_e32 v3, v84, v82
	v_lshlrev_b32_e32 v82, 16, v180
	v_mul_f32_e32 v4, v4, v165
	v_fmac_f32_e32 v4, 0x3fb504f3, v82
	v_lshlrev_b32_e32 v82, 16, v179
	v_mul_f32_e32 v5, v5, v165
	v_add_f32_e32 v3, v4, v3
	v_fmac_f32_e32 v5, 0x3fb504f3, v82
	v_lshlrev_b32_e32 v82, 16, v178
	v_mul_f32_e32 v6, v6, v165
	v_add_f32_e32 v3, v5, v3
	v_fmac_f32_e32 v6, 0x3fb504f3, v82
	v_lshlrev_b32_e32 v82, 16, v177
	v_mul_f32_e32 v7, v7, v165
	v_add_f32_e32 v3, v6, v3
	v_fmac_f32_e32 v7, 0x3fb504f3, v82
	v_lshlrev_b32_e32 v82, 16, v176
	v_mul_f32_e32 v8, v8, v165
	v_add_f32_e32 v3, v7, v3
	v_fmac_f32_e32 v8, 0x3fb504f3, v82
	v_lshlrev_b32_e32 v82, 16, v175
	v_mul_f32_e32 v9, v9, v165
	v_add_f32_e32 v3, v8, v3
	v_fmac_f32_e32 v9, 0x3fb504f3, v82
	v_lshlrev_b32_e32 v82, 16, v173
	v_mul_f32_e32 v10, v10, v165
	v_add_f32_e32 v3, v9, v3
	v_fmac_f32_e32 v10, 0x3fb504f3, v82
	v_lshlrev_b32_e32 v82, 16, v172
	v_mul_f32_e32 v11, v11, v165
	v_add_f32_e32 v3, v10, v3
	v_fmac_f32_e32 v11, 0x3fb504f3, v82
	v_lshlrev_b32_e32 v82, 16, v171
	v_mul_f32_e32 v12, v12, v165
	v_add_f32_e32 v3, v11, v3
	v_fmac_f32_e32 v12, 0x3fb504f3, v82
	v_lshlrev_b32_e32 v82, 16, v170
	v_mul_f32_e32 v13, v13, v165
	v_add_f32_e32 v3, v12, v3
	v_fmac_f32_e32 v13, 0x3fb504f3, v82
	v_lshlrev_b32_e32 v82, 16, v169
	v_mul_f32_e32 v14, v14, v165
	v_add_f32_e32 v3, v13, v3
	v_fmac_f32_e32 v14, 0x3fb504f3, v82
	v_lshlrev_b32_e32 v82, 16, v168
	v_mul_f32_e32 v15, v15, v165
	v_add_f32_e32 v3, v14, v3
	v_fmac_f32_e32 v15, 0x3fb504f3, v82
	v_lshlrev_b32_e32 v82, 16, v167
	v_mul_f32_e32 v16, v16, v165
; __device__ __forceinline__ unsigned f2bf(float f) { return pk2(f, 0.f) & 0xffffu; }
; __device__ __forceinline__ float wave_sum(float v) {
; #pragma unroll
;     for (int o = 1; o < 64; o <<= 1) v += __shfl_xor(v, o);
;     return v;
; }
; template <bool FINAL>
; __device__ __forceinline__ void phase_gather_v_mfma(const bf16* X, const int* EID, const float* COEF, const unsigned char* V4, const float* g, const float* bb, bf16* Ob, float* Of) {
;     ...
;         float z[16]; float sm = 0.f;
; #pragma unroll
;         for (int r = 0; r < 16; ++r) { const float av = acc[r]; z[r] = ALPHA * bf2f(xs[r]) + av * invS; sm += z[r]; }
;         const float mean = wave_sum(sm) * (1.f / D); float s2 = 0.f;
; #pragma unroll
;         for (int r = 0; r < 16; ++r) { z[r] -= mean; s2 += z[r] * z[r]; }
;         const float rstd = 1.f / sqrtf(wave_sum(s2) * (1.f / D) + LN_EPS);
; #pragma unroll
;         for (int r = 0; r < 16; ++r) { const int col = 32 * ((r & 3) + 8 * (r >> 2) + 4 * hh) + n; const float o = z[r] * rstd * gl[r] + bl[r];
;             if (FINAL) Of[(size_t)t * D + col] = o; else Ob[(size_t)t * D + col] = (bf16)f2bf(o); }
	v_add_f32_e32 v3, v15, v3
	v_fmac_f32_e32 v16, 0x3fb504f3, v82
	v_lshlrev_b32_e32 v82, 16, v166
	v_mul_f32_e32 v17, v17, v165
	v_add_f32_e32 v3, v16, v3
	v_fmac_f32_e32 v17, 0x3fb504f3, v82
	v_add_f32_e32 v3, v17, v3
	v_lshl_add_u64 v[112:113], v[112:113], 0, s[18:19]
	v_lshl_add_u64 v[114:115], v[114:115], 0, s[20:21]
	v_mov_b32_e32 v174, v161
	v_mov_b32_e32 v102, v162
	s_nop 1
	v_add_f32_dpp v3, v3, v3 row_shr:1 row_mask:0xf bank_mask:0xf
	s_nop 1
	v_add_f32_dpp v3, v3, v3 row_shr:2 row_mask:0xf bank_mask:0xf
	s_nop 1
	v_add_f32_dpp v3, v3, v3 row_shr:4 row_mask:0xf bank_mask:0xf
	s_nop 1
	v_add_f32_dpp v3, v3, v3 row_shr:8 row_mask:0xf bank_mask:0xf
	s_nop 1
	v_add_f32_dpp v3, v3, v3 row_bcast:15 row_mask:0xa bank_mask:0xf
	s_nop 1
	v_add_f32_dpp v3, v3, v3 row_bcast:31 row_mask:0xc bank_mask:0xf
	s_nop 0
	v_readlane_b32 s98, v3, 63
	s_nop 1
	v_mov_b32_e32 v3, s98
	v_fmac_f32_e32 v84, 0xba800000, v3
	v_fmac_f32_e32 v2, 0xba800000, v3
	v_mul_f32_e32 v82, v84, v84
	v_fmac_f32_e32 v82, v2, v2
	v_fmac_f32_e32 v4, 0xba800000, v3
	v_fmac_f32_e32 v82, v4, v4
	v_fmac_f32_e32 v5, 0xba800000, v3
	v_fmac_f32_e32 v82, v5, v5
	v_fmac_f32_e32 v6, 0xba800000, v3
	v_fmac_f32_e32 v82, v6, v6
	v_fmac_f32_e32 v7, 0xba800000, v3
	v_fmac_f32_e32 v82, v7, v7
	v_fmac_f32_e32 v8, 0xba800000, v3
	v_fmac_f32_e32 v82, v8, v8
	v_fmac_f32_e32 v9, 0xba800000, v3
	v_fmac_f32_e32 v82, v9, v9
	v_fmac_f32_e32 v10, 0xba800000, v3
	v_fmac_f32_e32 v82, v10, v10
	v_fmac_f32_e32 v11, 0xba800000, v3
	v_fmac_f32_e32 v82, v11, v11
	v_fmac_f32_e32 v12, 0xba800000, v3
	v_fmac_f32_e32 v82, v12, v12
	v_fmac_f32_e32 v13, 0xba800000, v3
	v_fmac_f32_e32 v82, v13, v13
	v_fmac_f32_e32 v14, 0xba800000, v3
	v_fmac_f32_e32 v82, v14, v14
	v_fmac_f32_e32 v15, 0xba800000, v3
	v_fmac_f32_e32 v82, v15, v15
	v_fmac_f32_e32 v16, 0xba800000, v3
	v_fmac_f32_e32 v82, v16, v16
	v_fmac_f32_e32 v17, 0xba800000, v3
	v_fmac_f32_e32 v82, v17, v17
	s_nop 1
	v_add_f32_dpp v82, v82, v82 row_shr:1 row_mask:0xf bank_mask:0xf
	s_nop 1
	v_add_f32_dpp v82, v82, v82 row_shr:2 row_mask:0xf bank_mask:0xf
	s_nop 1
	v_add_f32_dpp v82, v82, v82 row_shr:4 row_mask:0xf bank_mask:0xf
	s_nop 1
	v_add_f32_dpp v82, v82, v82 row_shr:8 row_mask:0xf bank_mask:0xf
	s_nop 1
	v_add_f32_dpp v82, v82, v82 row_bcast:15 row_mask:0xa bank_mask:0xf
	s_nop 1
	v_add_f32_dpp v82, v82, v82 row_bcast:31 row_mask:0xc bank_mask:0xf
	s_nop 0
	v_readlane_b32 s98, v82, 63
	s_nop 1
	v_mov_b32_e32 v3, s98
	v_fmamk_f32 v3, v3, 0x3a800000, v159
	v_mul_f32_e32 v82, 0x4f800000, v3
	v_cmp_gt_f32_e32 vcc, s3, v3
	s_nop 1
	v_cndmask_b32_e32 v3, v3, v82, vcc
	v_sqrt_f32_e32 v82, v3
	s_nop 0
	v_add_u32_e32 v83, -1, v82
	v_fma_f32 v85, -v83, v82, v3
	v_cmp_ge_f32_e64 s[0:1], 0, v85
	v_add_u32_e32 v85, 1, v82
	s_nop 0
	v_cndmask_b32_e64 v83, v82, v83, s[0:1]
	v_fma_f32 v82, -v85, v82, v3
	v_cmp_lt_f32_e64 s[0:1], 0, v82
	s_nop 1
	v_cndmask_b32_e64 v82, v83, v85, s[0:1]
	v_mul_f32_e32 v83, 0x37800000, v82
	v_cndmask_b32_e32 v82, v82, v83, vcc
	v_cmp_class_f32_e32 vcc, v3, v160
	s_nop 1
	v_cndmask_b32_e32 v3, v82, v3, vcc
	v_div_scale_f32 v82, s[0:1], v3, v3, 1.0
	v_rcp_f32_e32 v83, v82
	s_nop 0
	v_fma_f32 v85, -v82, v83, 1.0
	v_fmac_f32_e32 v83, v85, v83
	v_div_scale_f32 v85, vcc, 1.0, v3, 1.0
	v_mul_f32_e32 v86, v85, v83
	v_fma_f32 v87, -v82, v86, v85
	v_fmac_f32_e32 v86, v87, v83
	v_fma_f32 v82, -v82, v86, v85
	v_div_fmas_f32 v82, v82, v83, v86
	v_div_fixup_f32 v82, v82, v3, 1.0
	v_mul_f32_e32 v2, v2, v82
	v_mul_f32_e32 v4, v4, v82
	v_fma_f32 v83, v116, v2, v117
	v_lshl_add_u64 v[2:3], s[14:15], 0, v[110:111]
	v_fma_f32 v4, v120, v4, v121
	global_store_dword v[2:3], v4, off offset:256 nt
	v_mul_f32_e32 v4, v5, v82
	v_fma_f32 v4, v122, v4, v123
	global_store_dword v[2:3], v4, off offset:384 nt
	v_mul_f32_e32 v4, v6, v82
	v_fma_f32 v4, v124, v4, v125
	global_store_dword v[2:3], v4, off offset:1024 nt
	v_mul_f32_e32 v4, v7, v82
	v_fma_f32 v4, v126, v4, v127
	global_store_dword v[2:3], v4, off offset:1152 nt
	v_mul_f32_e32 v4, v8, v82
	v_fma_f32 v4, v128, v4, v129
	global_store_dword v[2:3], v4, off offset:1280 nt
	v_mul_f32_e32 v4, v9, v82
	v_fma_f32 v4, v130, v4, v131
	global_store_dword v[2:3], v4, off offset:1408 nt
	v_mul_f32_e32 v4, v10, v82
	v_fma_f32 v4, v132, v4, v133
	global_store_dword v[2:3], v4, off offset:2048 nt
	v_mul_f32_e32 v4, v11, v82
	v_fma_f32 v4, v134, v4, v135
	global_store_dword v[2:3], v4, off offset:2176 nt
	v_mul_f32_e32 v4, v12, v82
	v_fma_f32 v4, v136, v4, v137
	global_store_dword v[2:3], v4, off offset:2304 nt
	v_mul_f32_e32 v4, v13, v82
	v_fma_f32 v4, v138, v4, v139
	global_store_dword v[2:3], v4, off offset:2432 nt
	v_mul_f32_e32 v4, v14, v82
	v_fma_f32 v4, v140, v4, v141
	global_store_dword v[2:3], v4, off offset:3072 nt
	v_mul_f32_e32 v4, v15, v82
	v_fma_f32 v4, v142, v4, v143
	global_store_dword v[2:3], v4, off offset:3200 nt
	v_mul_f32_e32 v4, v16, v82
	v_fma_f32 v4, v144, v4, v145
	global_store_dword v[2:3], v83, off nt
	v_mul_f32_e32 v83, v84, v82
	global_store_dword v[2:3], v4, off offset:3328 nt
	v_mul_f32_e32 v4, v17, v82
	v_fma_f32 v83, v118, v83, v119
	v_fma_f32 v4, v146, v4, v147
	s_add_u32 s14, s14, s16
	global_store_dword v[2:3], v83, off offset:128 nt
	global_store_dword v[2:3], v4, off offset:3456 nt
	s_addc_u32 s15, s15, s17
	s_andn2_b64 vcc, exec, s[22:23]
	v_mov_b32_e32 v3, v164
	v_mov_b32_e32 v2, v163
	s_cbranch_vccz .LBB0_2009

; __global__ void __launch_bounds__(NTHR, 2) mk_fwd(Args args) {
	.amdhsa_kernel _Z6mk_fwd4Args
		.amdhsa_group_segment_fixed_size 0
		.amdhsa_private_segment_fixed_size 0
		.amdhsa_kernarg_size 416
		.amdhsa_user_sgpr_count 2
		.amdhsa_user_sgpr_dispatch_ptr 0
		.amdhsa_user_sgpr_queue_ptr 0
		.amdhsa_user_sgpr_kernarg_segment_ptr 1
		.amdhsa_user_sgpr_dispatch_id 0
		.amdhsa_user_sgpr_kernarg_preload_length 0
		.amdhsa_user_sgpr_kernarg_preload_offset 0
		.amdhsa_user_sgpr_private_segment_size 0
		.amdhsa_uses_dynamic_stack 0
		.amdhsa_enable_private_segment 0
		.amdhsa_system_sgpr_workgroup_id_x 1
		.amdhsa_system_sgpr_workgroup_id_y 0
		.amdhsa_system_sgpr_workgroup_id_z 0
		.amdhsa_system_sgpr_workgroup_info 0
		.amdhsa_system_vgpr_workitem_id 0
		.amdhsa_next_free_vgpr 256
		.amdhsa_next_free_sgpr 100
		.amdhsa_accum_offset 256
		.amdhsa_reserve_vcc 1
		.amdhsa_float_round_mode_32 0
		.amdhsa_float_round_mode_16_64 0
		.amdhsa_float_denorm_mode_32 3
		.amdhsa_float_denorm_mode_16_64 3
		.amdhsa_dx10_clamp 1
		.amdhsa_ieee_mode 1
		.amdhsa_fp16_overflow 0
		.amdhsa_tg_split 0
		.amdhsa_exception_fp_ieee_invalid_op 0
		.amdhsa_exception_fp_denorm_src 0
		.amdhsa_exception_fp_ieee_div_zero 0
		.amdhsa_exception_fp_ieee_overflow 0
		.amdhsa_exception_fp_ieee_underflow 0
		.amdhsa_exception_fp_ieee_inexact 0
		.amdhsa_exception_int_div_zero 0
	.end_amdhsa_kernel

; __global__ void __launch_bounds__(NTHR, 2) mk_fwd(Args args) {
amdhsa.kernels:
  - .agpr_count:     0
    .args:
      - .offset:         0
        .size:           160
        .value_kind:     by_value
      - .offset:         160
        .size:           4
        .value_kind:     hidden_block_count_x
      - .offset:         164
        .size:           4
        .value_kind:     hidden_block_count_y
      - .offset:         168
        .size:           4
        .value_kind:     hidden_block_count_z
      - .offset:         172
        .size:           2
        .value_kind:     hidden_group_size_x
      - .offset:         174
        .size:           2
        .value_kind:     hidden_group_size_y
      - .offset:         176
        .size:           2
        .value_kind:     hidden_group_size_z
      - .offset:         178
        .size:           2
        .value_kind:     hidden_remainder_x
      - .offset:         180
        .size:           2
        .value_kind:     hidden_remainder_y
      - .offset:         182
        .size:           2
        .value_kind:     hidden_remainder_z
      - .offset:         200
        .size:           8
        .value_kind:     hidden_global_offset_x
      - .offset:         208
        .size:           8
        .value_kind:     hidden_global_offset_y
      - .offset:         216
        .size:           8
        .value_kind:     hidden_global_offset_z
      - .offset:         224
        .size:           2
        .value_kind:     hidden_grid_dims
      - .offset:         280
        .size:           4
        .value_kind:     hidden_dynamic_lds_size
    .group_segment_fixed_size: 0
    .kernarg_segment_align: 8
    .kernarg_segment_size: 416
    .language:       OpenCL C
    .language_version:
      - 2
      - 0
    .max_flat_workgroup_size: 512
    .name:           _Z6mk_fwd4Args
    .private_segment_fixed_size: 0
    .sgpr_count:     106
    .sgpr_spill_count: 53
    .symbol:         _Z6mk_fwd4Args.kd
    .uniform_work_group_size: 1
    .uses_dynamic_stack: false
    .vgpr_count:     256
    .vgpr_spill_count: 0
    .wavefront_size: 64
